# younger wave half (wr==1) runs its own copy of each plain GEMM K loop with s_setprio levels 2/1 instead of 1/0 (static offset on top of the per-phase flips)
# baseline (speedup 1.0000x reference)
; #define PG8_STAGE(bufoff, gbase, voff) do { _Pragma("unroll") for (int _i = 0; _i < 2; ++_i) \
;         __builtin_amdgcn_global_load_lds((const unsigned*)((const char*)(gbase) + (voff)[_i]), (LAS unsigned*)(lds + (bufoff) + ldsw + _i * 8192), 16, 0, 0); } while (0)
; #define PG8_LDA(dst, b, h) do { _Pragma("unroll") for (int m = 0; m < 4; ++m) _Pragma("unroll") for (int k = 0; k < 2; ++k) dst[m][k] = *(const LAS bf16x8*)(lds + PG8_SA(b, h) + aoff + m * 2048 + k * 1024); } while (0)
; #define PG8_LDB(dst, b, h) do { _Pragma("unroll") for (int n = 0; n < 2; ++n) _Pragma("unroll") for (int k = 0; k < 2; ++k) dst[n][k] = *(const LAS bf16x8*)(lds + PG8_SB(b, h) + boff + n * 2048 + k * 1024); } while (0)
; #define PG8_SCHED __builtin_amdgcn_sched_barrier(0)
; #define PG8_STAGE(bufoff, gbase, voff) do { _Pragma("unroll") for (int _i = 0; _i < 2; ++_i) \
;         __builtin_amdgcn_global_load_lds((const unsigned*)((const char*)(gbase) + (voff)[_i]), (LAS unsigned*)(lds + (bufoff) + ldsw + _i * 8192), 16, 0, 0); } while (0)
; #define PG8_LDA(dst, b, h) do { _Pragma("unroll") for (int m = 0; m < 4; ++m) _Pragma("unroll") for (int k = 0; k < 2; ++k) dst[m][k] = *(const LAS bf16x8*)(lds + PG8_SA(b, h) + aoff + m * 2048 + k * 1024); } while (0)
; #define PG8_SCHED __builtin_amdgcn_sched_barrier(0)
; template <class Epi, class Sched>
; __device__ __forceinline__ void gemm_phase(LAS unsigned char* lds, const Gemm g, const Sched& S, const Epi& E) {
;     ...
;         const char* nA = has_next ? (const char*)g.A + (size_t)nxt.pm * tstepA : cA; const char* nB = has_next ? (const char*)g.Bt + (size_t)nxt.pn * tstepB : cB;
;         for (int t = 0; t < nt; t += 2) {
;             const bool last = (t == nt - 2);
;             const char* a1 = cA + (size_t)(t + 1) * kstep;
;             const char* a2 = last ? nA : cA + (size_t)(t + 2) * kstep; const char* b2 = last ? nB : cB + (size_t)(t + 2) * kstep;
;             const char* a3 = a2 + kstep; const char* b3 = b2 + kstep;
;             PG8_LDB(B0, 0, 0); PG8_LDB(B1, 0, 1); PG8_SCHED; PG8_LDA(At, 0, 0); PG8_STAGE(PG8_SA(1, 1), a1 + hstepA, voffA);
;     ...
; #pragma unroll
;         for (int a = 0; a < 2; ++a)
; #pragma unroll
;             for (int b = 0; b < 2; ++b)
; #pragma unroll
;                 for (int m = 0; m < 4; ++m)
; #pragma unroll
;                     for (int n = 0; n < 2; ++n) acc[a][b][m][n] = (f32x4){0.f, 0.f, 0.f, 0.f};
.LBB0_181:
	s_ashr_i32 s13, s12, 31
	s_lshl_b64 s[14:15], s[12:13], 19
	s_add_u32 s14, s34, s14
	s_addc_u32 s15, s35, s15
	s_and_b64 s[16:17], s[6:7], exec
	s_cselect_b32 s13, s15, s25
	s_cselect_b32 s21, s14, s24
	s_ashr_i32 s11, s10, 31
	s_lshl_b64 s[16:17], s[10:11], 19
	s_add_u32 s16, s29, s16
	s_addc_u32 s17, s30, s17
	s_and_b64 s[26:27], s[6:7], exec
	s_cselect_b32 s11, s17, s19
	s_cselect_b32 s23, s16, s18
	s_add_u32 s46, s18, 0x100
	s_addc_u32 s51, s19, 0
	s_add_u32 s18, s24, 0x40080
	v_mov_b32_e32 v2, 0
	s_addc_u32 s19, s25, 0
	s_mov_b32 s52, -2
	v_mov_b32_e32 v3, v2
	v_mov_b32_e32 v4, v2
	v_mov_b32_e32 v5, v2
	v_mov_b32_e32 v6, v2
	v_mov_b32_e32 v7, v2
	v_mov_b32_e32 v8, v2
	v_mov_b32_e32 v9, v2
	v_mov_b32_e32 v18, v2
	v_mov_b32_e32 v19, v2
	v_mov_b32_e32 v20, v2
	v_mov_b32_e32 v21, v2
	v_mov_b32_e32 v22, v2
	v_mov_b32_e32 v23, v2
	v_mov_b32_e32 v24, v2
	v_mov_b32_e32 v25, v2
	v_mov_b32_e32 v34, v2
	v_mov_b32_e32 v35, v2
	v_mov_b32_e32 v36, v2
	v_mov_b32_e32 v37, v2
	v_mov_b32_e32 v38, v2
	v_mov_b32_e32 v39, v2
	v_mov_b32_e32 v40, v2
	v_mov_b32_e32 v41, v2
	v_mov_b32_e32 v50, v2
	v_mov_b32_e32 v51, v2
	v_mov_b32_e32 v52, v2
	v_mov_b32_e32 v53, v2
	v_mov_b32_e32 v54, v2
	v_mov_b32_e32 v55, v2
	v_mov_b32_e32 v56, v2
	v_mov_b32_e32 v57, v2
	v_mov_b32_e32 v10, v2
	v_mov_b32_e32 v11, v2
	v_mov_b32_e32 v12, v2
	v_mov_b32_e32 v13, v2
	v_mov_b32_e32 v14, v2
	v_mov_b32_e32 v15, v2
	v_mov_b32_e32 v16, v2
	v_mov_b32_e32 v17, v2
	v_mov_b32_e32 v26, v2
	v_mov_b32_e32 v27, v2
	v_mov_b32_e32 v28, v2
	v_mov_b32_e32 v29, v2
	v_mov_b32_e32 v30, v2
	v_mov_b32_e32 v31, v2
	v_mov_b32_e32 v32, v2
	v_mov_b32_e32 v33, v2
	v_mov_b32_e32 v42, v2
	v_mov_b32_e32 v43, v2
	v_mov_b32_e32 v44, v2
	v_mov_b32_e32 v45, v2
	v_mov_b32_e32 v46, v2
	v_mov_b32_e32 v47, v2
	v_mov_b32_e32 v48, v2
	v_mov_b32_e32 v49, v2
	v_mov_b32_e32 v58, v2
	v_mov_b32_e32 v59, v2
	v_mov_b32_e32 v60, v2
	v_mov_b32_e32 v61, v2
	v_mov_b32_e32 v62, v2
	v_mov_b32_e32 v63, v2
	v_mov_b32_e32 v64, v2
	v_mov_b32_e32 v65, v2
	v_mov_b32_e32 v66, v2
	v_mov_b32_e32 v67, v2
	v_mov_b32_e32 v68, v2
	v_mov_b32_e32 v69, v2
	v_mov_b32_e32 v70, v2
	v_mov_b32_e32 v71, v2
	v_mov_b32_e32 v72, v2
	v_mov_b32_e32 v73, v2
	v_mov_b32_e32 v82, v2
	v_mov_b32_e32 v83, v2
	v_mov_b32_e32 v84, v2
	v_mov_b32_e32 v85, v2
	v_mov_b32_e32 v86, v2
	v_mov_b32_e32 v87, v2
	v_mov_b32_e32 v88, v2
	v_mov_b32_e32 v89, v2
	v_mov_b32_e32 v98, v2
	v_mov_b32_e32 v99, v2
	v_mov_b32_e32 v100, v2
	v_mov_b32_e32 v101, v2
	v_mov_b32_e32 v102, v2
	v_mov_b32_e32 v103, v2
	v_mov_b32_e32 v104, v2
	v_mov_b32_e32 v105, v2
	s_waitcnt vmcnt(0)
	v_mov_b32_e32 v114, v2
	v_mov_b32_e32 v115, v2
	v_mov_b32_e32 v116, v2
	v_mov_b32_e32 v117, v2
	v_mov_b32_e32 v118, v2
	v_mov_b32_e32 v119, v2
	v_mov_b32_e32 v120, v2
	v_mov_b32_e32 v121, v2
	v_mov_b32_e32 v74, v2
	v_mov_b32_e32 v75, v2
	v_mov_b32_e32 v76, v2
	v_mov_b32_e32 v77, v2
	v_mov_b32_e32 v78, v2
	v_mov_b32_e32 v79, v2
	v_mov_b32_e32 v80, v2
	v_mov_b32_e32 v81, v2
	v_mov_b32_e32 v90, v2
	v_mov_b32_e32 v91, v2
	v_mov_b32_e32 v92, v2
	v_mov_b32_e32 v93, v2
	v_mov_b32_e32 v94, v2
	v_mov_b32_e32 v95, v2
	v_mov_b32_e32 v96, v2
	v_mov_b32_e32 v97, v2
	v_mov_b32_e32 v106, v2
	v_mov_b32_e32 v107, v2
	v_mov_b32_e32 v108, v2
	v_mov_b32_e32 v109, v2
	v_mov_b32_e32 v110, v2
	v_mov_b32_e32 v111, v2
	v_mov_b32_e32 v112, v2
	v_mov_b32_e32 v113, v2
	v_mov_b32_e32 v122, v2
	v_mov_b32_e32 v123, v2
	v_mov_b32_e32 v124, v2
	v_mov_b32_e32 v125, v2
	v_mov_b32_e32 v126, v2
	v_mov_b32_e32 v127, v2
	v_mov_b32_e32 v128, v2
	v_mov_b32_e32 v129, v2
	s_cmp_lg_u64 s[2:3], 0
	s_cbranch_scc1 .Lkb_proj
.LBB0_182:
	s_add_u32 s24, s18, 0xfffc0080
	s_addc_u32 s25, s19, -1
	s_add_i32 s53, 0, 0x10000
	s_cmp_eq_u32 s52, 12
	s_cselect_b32 s27, s13, s25
	s_cselect_b32 s26, s21, s24
	v_add_u32_e32 v151, s53, v154
	s_cselect_b32 s25, s11, s51
	s_cselect_b32 s24, s23, s46
	s_add_i32 s56, 0, 0x14000
	ds_read_b128 v[130:133], v151
	ds_read_b128 v[134:137], v151 offset:1024
	ds_read_b128 v[156:159], v151 offset:2048
	ds_read_b128 v[160:163], v151 offset:3072
	v_add_u32_e32 v151, s56, v154
	ds_read_b128 v[164:167], v151
	ds_read_b128 v[168:171], v151 offset:1024
	ds_read_b128 v[172:175], v151 offset:2048
	ds_read_b128 v[176:179], v151 offset:3072
	v_lshl_add_u64 v[152:153], s[18:19], 0, v[148:149]
	s_add_i32 m0, s36, 0xc000
	ds_read_b128 v[186:189], v155
	ds_read_b128 v[190:193], v155 offset:1024
	ds_read_b128 v[194:197], v155 offset:2048
	ds_read_b128 v[198:201], v155 offset:3072
	ds_read_b128 v[202:205], v155 offset:4096
	ds_read_b128 v[206:209], v155 offset:5120
	ds_read_b128 v[210:213], v155 offset:6144
	ds_read_b128 v[226:229], v155 offset:7168
	global_load_lds_dwordx4 v[152:153], off
	v_lshl_add_u64 v[152:153], s[18:19], 0, v[146:147]
	s_add_i32 m0, s36, 0xe000
	s_nop 0
	global_load_lds_dwordx4 v[152:153], off
	s_waitcnt vmcnt(8)
	s_waitcnt lgkmcnt(0)
	s_barrier
; #define PG8_STAGE(bufoff, gbase, voff) do { _Pragma("unroll") for (int _i = 0; _i < 2; ++_i) \
;         __builtin_amdgcn_global_load_lds((const unsigned*)((const char*)(gbase) + (voff)[_i]), (LAS unsigned*)(lds + (bufoff) + ldsw + _i * 8192), 16, 0, 0); } while (0)
; #define PG8_LDA(dst, b, h) do { _Pragma("unroll") for (int m = 0; m < 4; ++m) _Pragma("unroll") for (int k = 0; k < 2; ++k) dst[m][k] = *(const LAS bf16x8*)(lds + PG8_SA(b, h) + aoff + m * 2048 + k * 1024); } while (0)
; #define PG8_MMA(ai, bj, At, Bt) do { __builtin_amdgcn_s_setprio(1); _Pragma("unroll") for (int m = 0; m < 4; ++m) _Pragma("unroll") for (int n = 0; n < 2; ++n) _Pragma("unroll") for (int k = 0; k < 2; ++k) \
;         acc[ai][bj][m][n] = __builtin_amdgcn_mfma_f32_16x16x32_bf16(Bt[n][k], At[m][k], acc[ai][bj][m][n], 0, 0, 0); __builtin_amdgcn_s_setprio(0); } while (0)
; #define PG8_WAIT_V(n) asm volatile("s_waitcnt vmcnt(" #n ")" ::: "memory")
; #define PG8_WAIT_L(n) asm volatile("s_waitcnt lgkmcnt(" #n ")" ::: "memory")
; #define PG8_BAR __builtin_amdgcn_s_barrier()
; #define PG8_SCHED __builtin_amdgcn_sched_barrier(0)
; #define PG8_STAGE(bufoff, gbase, voff) do { _Pragma("unroll") for (int _i = 0; _i < 2; ++_i) \
;         __builtin_amdgcn_global_load_lds((const unsigned*)((const char*)(gbase) + (voff)[_i]), (LAS unsigned*)(lds + (bufoff) + ldsw + _i * 8192), 16, 0, 0); } while (0)
; #define PG8_LDA(dst, b, h) do { _Pragma("unroll") for (int m = 0; m < 4; ++m) _Pragma("unroll") for (int k = 0; k < 2; ++k) dst[m][k] = *(const LAS bf16x8*)(lds + PG8_SA(b, h) + aoff + m * 2048 + k * 1024); } while (0)
; #define PG8_WAIT_V(n) asm volatile("s_waitcnt vmcnt(" #n ")" ::: "memory")
; #define PG8_WAIT_L(n) asm volatile("s_waitcnt lgkmcnt(" #n ")" ::: "memory")
; #define PG8_BAR __builtin_amdgcn_s_barrier()
; template <class Epi, class Sched>
; __device__ __forceinline__ void gemm_phase(LAS unsigned char* lds, const Gemm g, const Sched& S, const Epi& E) {
;     ...
;             PG8_WAIT_V(8); PG8_WAIT_L(0); PG8_BAR; PG8_MMA(0, 0, At, B0); PG8_MMA(0, 1, At, B1); PG8_BAR; PG8_SCHED;
;             PG8_LDA(At, 0, 1); PG8_STAGE(PG8_SB(0, 0), b2, voffB); PG8_STAGE(PG8_SB(0, 1), b2 + hstepB, voffB); PG8_STAGE(PG8_SA(0, 0), a2, voffA);
;             PG8_WAIT_V(8); PG8_WAIT_L(0); PG8_BAR; PG8_MMA(1, 0, At, B0); PG8_MMA(1, 1, At, B1); PG8_BAR; PG8_SCHED;
	s_setprio 1
	s_waitcnt lgkmcnt(0)
	v_mfma_f32_16x16x32_bf16 v[126:129], v[130:133], v[186:189], v[126:129]
	v_mfma_f32_16x16x32_bf16 v[122:125], v[156:159], v[186:189], v[122:125]
	v_mfma_f32_16x16x32_bf16 v[110:113], v[130:133], v[194:197], v[110:113]
	v_mfma_f32_16x16x32_bf16 v[106:109], v[156:159], v[194:197], v[106:109]
	v_mfma_f32_16x16x32_bf16 v[94:97], v[130:133], v[202:205], v[94:97]
	v_mfma_f32_16x16x32_bf16 v[90:93], v[156:159], v[202:205], v[90:93]
	v_mfma_f32_16x16x32_bf16 v[78:81], v[130:133], v[210:213], v[78:81]
	v_mfma_f32_16x16x32_bf16 v[74:77], v[156:159], v[210:213], v[74:77]
	v_mfma_f32_16x16x32_bf16 v[126:129], v[134:137], v[190:193], v[126:129]
	v_mfma_f32_16x16x32_bf16 v[122:125], v[160:163], v[190:193], v[122:125]
	v_mfma_f32_16x16x32_bf16 v[110:113], v[134:137], v[198:201], v[110:113]
	v_mfma_f32_16x16x32_bf16 v[106:109], v[160:163], v[198:201], v[106:109]
	v_mfma_f32_16x16x32_bf16 v[94:97], v[134:137], v[206:209], v[94:97]
	v_mfma_f32_16x16x32_bf16 v[90:93], v[160:163], v[206:209], v[90:93]
	v_mfma_f32_16x16x32_bf16 v[78:81], v[134:137], v[226:229], v[78:81]
	v_mfma_f32_16x16x32_bf16 v[74:77], v[160:163], v[226:229], v[74:77]
	s_setprio 0
	s_setprio 1
	v_mfma_f32_16x16x32_bf16 v[118:121], v[164:167], v[186:189], v[118:121]
	v_mfma_f32_16x16x32_bf16 v[114:117], v[172:175], v[186:189], v[114:117]
	v_mfma_f32_16x16x32_bf16 v[102:105], v[164:167], v[194:197], v[102:105]
	v_mfma_f32_16x16x32_bf16 v[98:101], v[172:175], v[194:197], v[98:101]
	v_mfma_f32_16x16x32_bf16 v[86:89], v[164:167], v[202:205], v[86:89]
	v_mfma_f32_16x16x32_bf16 v[82:85], v[172:175], v[202:205], v[82:85]
	v_mfma_f32_16x16x32_bf16 v[70:73], v[164:167], v[210:213], v[70:73]
	v_mfma_f32_16x16x32_bf16 v[66:69], v[172:175], v[210:213], v[66:69]
	v_mfma_f32_16x16x32_bf16 v[118:121], v[168:171], v[190:193], v[118:121]
	v_mfma_f32_16x16x32_bf16 v[114:117], v[176:179], v[190:193], v[114:117]
	v_mfma_f32_16x16x32_bf16 v[102:105], v[168:171], v[198:201], v[102:105]
	v_mfma_f32_16x16x32_bf16 v[98:101], v[176:179], v[198:201], v[98:101]
	v_mfma_f32_16x16x32_bf16 v[86:89], v[168:171], v[206:209], v[86:89]
	v_mfma_f32_16x16x32_bf16 v[82:85], v[176:179], v[206:209], v[82:85]
	v_mfma_f32_16x16x32_bf16 v[70:73], v[168:171], v[226:229], v[70:73]
	v_mfma_f32_16x16x32_bf16 v[66:69], v[176:179], v[226:229], v[66:69]
	s_setprio 0
	s_barrier
	s_add_i32 s53, s53, s31
	v_lshl_add_u64 v[152:153], s[24:25], 0, v[140:141]
	s_mov_b32 m0, s53
	ds_read_b128 v[186:189], v155 offset:16384
	ds_read_b128 v[190:193], v155 offset:17408
	ds_read_b128 v[194:197], v155 offset:18432
	ds_read_b128 v[198:201], v155 offset:19456
	ds_read_b128 v[202:205], v155 offset:20480
	ds_read_b128 v[206:209], v155 offset:21504
	ds_read_b128 v[210:213], v155 offset:22528
	ds_read_b128 v[226:229], v155 offset:23552
	global_load_lds_dwordx4 v[152:153], off
	s_add_i32 m0, s53, 0x2000
	s_add_u32 s54, s24, 0x40000
	v_lshl_add_u64 v[182:183], s[24:25], 0, v[144:145]
	s_addc_u32 s55, s25, 0
	s_add_i32 s53, s56, s31
	global_load_lds_dwordx4 v[182:183], off
	v_lshl_add_u64 v[184:185], s[54:55], 0, v[140:141]
	s_mov_b32 m0, s53
	v_lshl_add_u64 v[214:215], s[26:27], 0, v[142:143]
	global_load_lds_dwordx4 v[184:185], off
	v_lshl_add_u64 v[184:185], s[54:55], 0, v[144:145]
	s_add_i32 m0, s53, 0x2000
	s_nop 0
	global_load_lds_dwordx4 v[184:185], off
	v_lshl_add_u64 v[184:185], s[26:27], 0, v[138:139]
	s_mov_b32 m0, s36
	s_nop 0
	global_load_lds_dwordx4 v[184:185], off
	s_mov_b32 m0, s37
	s_nop 0
	global_load_lds_dwordx4 v[214:215], off
	s_waitcnt vmcnt(8)
	s_waitcnt lgkmcnt(0)
	s_barrier
	s_setprio 1
	s_waitcnt lgkmcnt(0)
	v_mfma_f32_16x16x32_bf16 v[62:65], v[130:133], v[186:189], v[62:65]
	v_mfma_f32_16x16x32_bf16 v[58:61], v[156:159], v[186:189], v[58:61]
	v_mfma_f32_16x16x32_bf16 v[46:49], v[130:133], v[194:197], v[46:49]
	v_mfma_f32_16x16x32_bf16 v[42:45], v[156:159], v[194:197], v[42:45]
	v_mfma_f32_16x16x32_bf16 v[30:33], v[130:133], v[202:205], v[30:33]
	v_mfma_f32_16x16x32_bf16 v[26:29], v[156:159], v[202:205], v[26:29]
	v_mfma_f32_16x16x32_bf16 v[14:17], v[130:133], v[210:213], v[14:17]
	v_mfma_f32_16x16x32_bf16 v[10:13], v[156:159], v[210:213], v[10:13]
	v_mfma_f32_16x16x32_bf16 v[62:65], v[134:137], v[190:193], v[62:65]
	v_mfma_f32_16x16x32_bf16 v[58:61], v[160:163], v[190:193], v[58:61]
	v_mfma_f32_16x16x32_bf16 v[46:49], v[134:137], v[198:201], v[46:49]
	v_mfma_f32_16x16x32_bf16 v[42:45], v[160:163], v[198:201], v[42:45]
	v_mfma_f32_16x16x32_bf16 v[30:33], v[134:137], v[206:209], v[30:33]
	v_mfma_f32_16x16x32_bf16 v[26:29], v[160:163], v[206:209], v[26:29]
	v_mfma_f32_16x16x32_bf16 v[14:17], v[134:137], v[226:229], v[14:17]
	v_mfma_f32_16x16x32_bf16 v[10:13], v[160:163], v[226:229], v[10:13]
	s_setprio 0
	s_setprio 1
	v_mfma_f32_16x16x32_bf16 v[54:57], v[164:167], v[186:189], v[54:57]
	v_mfma_f32_16x16x32_bf16 v[50:53], v[172:175], v[186:189], v[50:53]
	v_mfma_f32_16x16x32_bf16 v[38:41], v[164:167], v[194:197], v[38:41]
	v_mfma_f32_16x16x32_bf16 v[34:37], v[172:175], v[194:197], v[34:37]
	v_mfma_f32_16x16x32_bf16 v[22:25], v[164:167], v[202:205], v[22:25]
	v_mfma_f32_16x16x32_bf16 v[18:21], v[172:175], v[202:205], v[18:21]
	v_mfma_f32_16x16x32_bf16 v[6:9], v[164:167], v[210:213], v[6:9]
	v_mfma_f32_16x16x32_bf16 v[2:5], v[172:175], v[210:213], v[2:5]
	v_mfma_f32_16x16x32_bf16 v[54:57], v[168:171], v[190:193], v[54:57]
	v_mfma_f32_16x16x32_bf16 v[50:53], v[176:179], v[190:193], v[50:53]
	v_mfma_f32_16x16x32_bf16 v[38:41], v[168:171], v[198:201], v[38:41]
	v_mfma_f32_16x16x32_bf16 v[34:37], v[176:179], v[198:201], v[34:37]
	v_mfma_f32_16x16x32_bf16 v[22:25], v[168:171], v[206:209], v[22:25]
	v_mfma_f32_16x16x32_bf16 v[18:21], v[176:179], v[206:209], v[18:21]
	v_mfma_f32_16x16x32_bf16 v[6:9], v[168:171], v[226:229], v[6:9]
	v_mfma_f32_16x16x32_bf16 v[2:5], v[176:179], v[226:229], v[2:5]
	s_setprio 0
	s_barrier
; #define PG8_STAGE(bufoff, gbase, voff) do { _Pragma("unroll") for (int _i = 0; _i < 2; ++_i) \
;         __builtin_amdgcn_global_load_lds((const unsigned*)((const char*)(gbase) + (voff)[_i]), (LAS unsigned*)(lds + (bufoff) + ldsw + _i * 8192), 16, 0, 0); } while (0)
; #define PG8_LDA(dst, b, h) do { _Pragma("unroll") for (int m = 0; m < 4; ++m) _Pragma("unroll") for (int k = 0; k < 2; ++k) dst[m][k] = *(const LAS bf16x8*)(lds + PG8_SA(b, h) + aoff + m * 2048 + k * 1024); } while (0)
; #define PG8_LDB(dst, b, h) do { _Pragma("unroll") for (int n = 0; n < 2; ++n) _Pragma("unroll") for (int k = 0; k < 2; ++k) dst[n][k] = *(const LAS bf16x8*)(lds + PG8_SB(b, h) + boff + n * 2048 + k * 1024); } while (0)
; #define PG8_MMA(ai, bj, At, Bt) do { __builtin_amdgcn_s_setprio(1); _Pragma("unroll") for (int m = 0; m < 4; ++m) _Pragma("unroll") for (int n = 0; n < 2; ++n) _Pragma("unroll") for (int k = 0; k < 2; ++k) \
;         acc[ai][bj][m][n] = __builtin_amdgcn_mfma_f32_16x16x32_bf16(Bt[n][k], At[m][k], acc[ai][bj][m][n], 0, 0, 0); __builtin_amdgcn_s_setprio(0); } while (0)
; #define PG8_WAIT_V(n) asm volatile("s_waitcnt vmcnt(" #n ")" ::: "memory")
; #define PG8_WAIT_L(n) asm volatile("s_waitcnt lgkmcnt(" #n ")" ::: "memory")
; #define PG8_BAR __builtin_amdgcn_s_barrier()
; #define PG8_SCHED __builtin_amdgcn_sched_barrier(0)
; #define PG8_STAGE(bufoff, gbase, voff) do { _Pragma("unroll") for (int _i = 0; _i < 2; ++_i) \
;         __builtin_amdgcn_global_load_lds((const unsigned*)((const char*)(gbase) + (voff)[_i]), (LAS unsigned*)(lds + (bufoff) + ldsw + _i * 8192), 16, 0, 0); } while (0)
; #define PG8_LDA(dst, b, h) do { _Pragma("unroll") for (int m = 0; m < 4; ++m) _Pragma("unroll") for (int k = 0; k < 2; ++k) dst[m][k] = *(const LAS bf16x8*)(lds + PG8_SA(b, h) + aoff + m * 2048 + k * 1024); } while (0)
; template <class Epi, class Sched>
; __device__ __forceinline__ void gemm_phase(LAS unsigned char* lds, const Gemm g, const Sched& S, const Epi& E) {
;     ...
;             PG8_LDB(B0, 1, 0); PG8_LDB(B1, 1, 1); PG8_SCHED; PG8_LDA(At, 1, 0); PG8_STAGE(PG8_SA(0, 1), a2 + hstepA, voffA);
;             PG8_WAIT_V(8); PG8_WAIT_L(0); PG8_BAR; PG8_MMA(0, 0, At, B0); PG8_MMA(0, 1, At, B1); PG8_BAR; PG8_SCHED;
;             PG8_LDA(At, 1, 1); PG8_STAGE(PG8_SB(1, 0), b3, voffB); PG8_STAGE(PG8_SB(1, 1), b3 + hstepB, voffB); PG8_STAGE(PG8_SA(1, 0), a3, voffA);
	s_add_i32 s53, 0, 0x18000
	v_add_u32_e32 v151, s53, v154
	s_add_i32 s54, 0, 0x1c000
	ds_read_b128 v[130:133], v151
	ds_read_b128 v[134:137], v151 offset:1024
	ds_read_b128 v[156:159], v151 offset:2048
	ds_read_b128 v[160:163], v151 offset:3072
	v_add_u32_e32 v151, s54, v154
	ds_read_b128 v[164:167], v151
	ds_read_b128 v[168:171], v151 offset:1024
	ds_read_b128 v[172:175], v151 offset:2048
	ds_read_b128 v[176:179], v151 offset:3072
	s_add_u32 s26, s26, 0x40000
	s_addc_u32 s27, s27, 0
	s_mov_b32 m0, s38
	v_lshl_add_u64 v[230:231], s[26:27], 0, v[138:139]
	ds_read_b128 v[186:189], v155 offset:32768
	ds_read_b128 v[190:193], v155 offset:33792
	ds_read_b128 v[194:197], v155 offset:34816
	ds_read_b128 v[198:201], v155 offset:35840
	ds_read_b128 v[202:205], v155 offset:36864
	ds_read_b128 v[206:209], v155 offset:37888
	ds_read_b128 v[210:213], v155 offset:38912
	ds_read_b128 v[226:229], v155 offset:39936
	global_load_lds_dwordx4 v[230:231], off
	v_lshl_add_u64 v[230:231], s[26:27], 0, v[142:143]
	s_mov_b32 m0, s39
	s_nop 0
	global_load_lds_dwordx4 v[230:231], off
	s_waitcnt vmcnt(8)
	s_waitcnt lgkmcnt(0)
	s_barrier
	s_setprio 1
	s_waitcnt lgkmcnt(0)
	v_mfma_f32_16x16x32_bf16 v[126:129], v[130:133], v[186:189], v[126:129]
	v_mfma_f32_16x16x32_bf16 v[122:125], v[156:159], v[186:189], v[122:125]
	v_mfma_f32_16x16x32_bf16 v[110:113], v[130:133], v[194:197], v[110:113]
	v_mfma_f32_16x16x32_bf16 v[106:109], v[156:159], v[194:197], v[106:109]
	v_mfma_f32_16x16x32_bf16 v[94:97], v[130:133], v[202:205], v[94:97]
	v_mfma_f32_16x16x32_bf16 v[90:93], v[156:159], v[202:205], v[90:93]
	v_mfma_f32_16x16x32_bf16 v[78:81], v[130:133], v[210:213], v[78:81]
	v_mfma_f32_16x16x32_bf16 v[74:77], v[156:159], v[210:213], v[74:77]
	v_mfma_f32_16x16x32_bf16 v[126:129], v[134:137], v[190:193], v[126:129]
	v_mfma_f32_16x16x32_bf16 v[122:125], v[160:163], v[190:193], v[122:125]
	v_mfma_f32_16x16x32_bf16 v[110:113], v[134:137], v[198:201], v[110:113]
	v_mfma_f32_16x16x32_bf16 v[106:109], v[160:163], v[198:201], v[106:109]
	v_mfma_f32_16x16x32_bf16 v[94:97], v[134:137], v[206:209], v[94:97]
	v_mfma_f32_16x16x32_bf16 v[90:93], v[160:163], v[206:209], v[90:93]
	v_mfma_f32_16x16x32_bf16 v[78:81], v[134:137], v[226:229], v[78:81]
	v_mfma_f32_16x16x32_bf16 v[74:77], v[160:163], v[226:229], v[74:77]
	s_setprio 0
	s_setprio 1
	v_mfma_f32_16x16x32_bf16 v[118:121], v[164:167], v[186:189], v[118:121]
	v_mfma_f32_16x16x32_bf16 v[114:117], v[172:175], v[186:189], v[114:117]
	v_mfma_f32_16x16x32_bf16 v[102:105], v[164:167], v[194:197], v[102:105]
	v_mfma_f32_16x16x32_bf16 v[98:101], v[172:175], v[194:197], v[98:101]
	v_mfma_f32_16x16x32_bf16 v[86:89], v[164:167], v[202:205], v[86:89]
	v_mfma_f32_16x16x32_bf16 v[82:85], v[172:175], v[202:205], v[82:85]
	v_mfma_f32_16x16x32_bf16 v[70:73], v[164:167], v[210:213], v[70:73]
	v_mfma_f32_16x16x32_bf16 v[66:69], v[172:175], v[210:213], v[66:69]
	v_mfma_f32_16x16x32_bf16 v[118:121], v[168:171], v[190:193], v[118:121]
	v_mfma_f32_16x16x32_bf16 v[114:117], v[176:179], v[190:193], v[114:117]
	v_mfma_f32_16x16x32_bf16 v[102:105], v[168:171], v[198:201], v[102:105]
	v_mfma_f32_16x16x32_bf16 v[98:101], v[176:179], v[198:201], v[98:101]
	v_mfma_f32_16x16x32_bf16 v[86:89], v[168:171], v[206:209], v[86:89]
	v_mfma_f32_16x16x32_bf16 v[82:85], v[176:179], v[206:209], v[82:85]
	v_mfma_f32_16x16x32_bf16 v[70:73], v[168:171], v[226:229], v[70:73]
	v_mfma_f32_16x16x32_bf16 v[66:69], v[176:179], v[226:229], v[66:69]
	s_setprio 0
	s_barrier
	s_add_i32 s26, s53, s31
	v_lshl_add_u64 v[152:153], v[152:153], 0, s[86:87]
	s_mov_b32 m0, s26
	ds_read_b128 v[186:189], v155 offset:49152
	ds_read_b128 v[190:193], v155 offset:50176
	ds_read_b128 v[194:197], v155 offset:51200
	ds_read_b128 v[198:201], v155 offset:52224
	ds_read_b128 v[202:205], v155 offset:53248
	ds_read_b128 v[206:209], v155 offset:54272
	ds_read_b128 v[210:213], v155 offset:55296
	ds_read_b128 v[226:229], v155 offset:56320
	global_load_lds_dwordx4 v[152:153], off
	s_add_i32 m0, s26, 0x2000
	s_add_u32 s24, s24, 0x40080
	v_lshl_add_u64 v[152:153], v[182:183], 0, s[86:87]
	s_addc_u32 s25, s25, 0
	s_add_i32 s26, s54, s31
	global_load_lds_dwordx4 v[152:153], off
	v_lshl_add_u64 v[152:153], s[24:25], 0, v[140:141]
	s_mov_b32 m0, s26
	s_nop 0
	global_load_lds_dwordx4 v[152:153], off
	v_lshl_add_u64 v[152:153], s[24:25], 0, v[144:145]
	s_add_i32 m0, s26, 0x2000
	s_nop 0
	global_load_lds_dwordx4 v[152:153], off
	v_lshl_add_u64 v[152:153], v[184:185], 0, s[86:87]
	s_mov_b32 m0, s48
	s_nop 0
	global_load_lds_dwordx4 v[152:153], off
	v_lshl_add_u64 v[152:153], v[214:215], 0, s[86:87]
	s_mov_b32 m0, s49
	s_nop 0
	global_load_lds_dwordx4 v[152:153], off
	s_waitcnt vmcnt(8)
	s_waitcnt lgkmcnt(0)
	s_barrier
; #define PG8_STAGE(bufoff, gbase, voff) do { _Pragma("unroll") for (int _i = 0; _i < 2; ++_i) \
;         __builtin_amdgcn_global_load_lds((const unsigned*)((const char*)(gbase) + (voff)[_i]), (LAS unsigned*)(lds + (bufoff) + ldsw + _i * 8192), 16, 0, 0); } while (0)
; #define PG8_LDA(dst, b, h) do { _Pragma("unroll") for (int m = 0; m < 4; ++m) _Pragma("unroll") for (int k = 0; k < 2; ++k) dst[m][k] = *(const LAS bf16x8*)(lds + PG8_SA(b, h) + aoff + m * 2048 + k * 1024); } while (0)
; #define PG8_LDB(dst, b, h) do { _Pragma("unroll") for (int n = 0; n < 2; ++n) _Pragma("unroll") for (int k = 0; k < 2; ++k) dst[n][k] = *(const LAS bf16x8*)(lds + PG8_SB(b, h) + boff + n * 2048 + k * 1024); } while (0)
; #define PG8_MMA(ai, bj, At, Bt) do { __builtin_amdgcn_s_setprio(1); _Pragma("unroll") for (int m = 0; m < 4; ++m) _Pragma("unroll") for (int n = 0; n < 2; ++n) _Pragma("unroll") for (int k = 0; k < 2; ++k) \
;         acc[ai][bj][m][n] = __builtin_amdgcn_mfma_f32_16x16x32_bf16(Bt[n][k], At[m][k], acc[ai][bj][m][n], 0, 0, 0); __builtin_amdgcn_s_setprio(0); } while (0)
; #define PG8_WAIT_V(n) asm volatile("s_waitcnt vmcnt(" #n ")" ::: "memory")
; #define PG8_WAIT_L(n) asm volatile("s_waitcnt lgkmcnt(" #n ")" ::: "memory")
; #define PG8_BAR __builtin_amdgcn_s_barrier()
; #define PG8_SCHED __builtin_amdgcn_sched_barrier(0)
; #define PG8_STAGE(bufoff, gbase, voff) do { _Pragma("unroll") for (int _i = 0; _i < 2; ++_i) \
;         __builtin_amdgcn_global_load_lds((const unsigned*)((const char*)(gbase) + (voff)[_i]), (LAS unsigned*)(lds + (bufoff) + ldsw + _i * 8192), 16, 0, 0); } while (0)
; #define PG8_LDA(dst, b, h) do { _Pragma("unroll") for (int m = 0; m < 4; ++m) _Pragma("unroll") for (int k = 0; k < 2; ++k) dst[m][k] = *(const LAS bf16x8*)(lds + PG8_SA(b, h) + aoff + m * 2048 + k * 1024); } while (0)
; #define PG8_BAR __builtin_amdgcn_s_barrier()
; template <class Epi, class Sched>
; __device__ __forceinline__ void gemm_phase(LAS unsigned char* lds, const Gemm g, const Sched& S, const Epi& E) {
;     ...
;             PG8_LDB(B0, 0, 0); PG8_LDB(B1, 0, 1); PG8_SCHED; PG8_LDA(At, 0, 0); PG8_STAGE(PG8_SA(1, 1), a1 + hstepA, voffA);
;             PG8_WAIT_V(8); PG8_WAIT_L(0); PG8_BAR; PG8_MMA(0, 0, At, B0); PG8_MMA(0, 1, At, B1); PG8_BAR; PG8_SCHED;
;     ...
;             PG8_WAIT_V(8); PG8_WAIT_L(0); PG8_BAR; PG8_MMA(1, 0, At, B0); PG8_MMA(1, 1, At, B1); PG8_BAR; PG8_SCHED;
	s_setprio 1
	s_waitcnt lgkmcnt(0)
	v_mfma_f32_16x16x32_bf16 v[62:65], v[130:133], v[186:189], v[62:65]
	v_mfma_f32_16x16x32_bf16 v[58:61], v[156:159], v[186:189], v[58:61]
	v_mfma_f32_16x16x32_bf16 v[46:49], v[130:133], v[194:197], v[46:49]
	v_mfma_f32_16x16x32_bf16 v[42:45], v[156:159], v[194:197], v[42:45]
	v_mfma_f32_16x16x32_bf16 v[30:33], v[130:133], v[202:205], v[30:33]
	v_mfma_f32_16x16x32_bf16 v[26:29], v[156:159], v[202:205], v[26:29]
	v_mfma_f32_16x16x32_bf16 v[14:17], v[130:133], v[210:213], v[14:17]
	v_mfma_f32_16x16x32_bf16 v[10:13], v[156:159], v[210:213], v[10:13]
	v_mfma_f32_16x16x32_bf16 v[62:65], v[134:137], v[190:193], v[62:65]
	v_mfma_f32_16x16x32_bf16 v[58:61], v[160:163], v[190:193], v[58:61]
	v_mfma_f32_16x16x32_bf16 v[46:49], v[134:137], v[198:201], v[46:49]
	v_mfma_f32_16x16x32_bf16 v[42:45], v[160:163], v[198:201], v[42:45]
	v_mfma_f32_16x16x32_bf16 v[30:33], v[134:137], v[206:209], v[30:33]
	v_mfma_f32_16x16x32_bf16 v[26:29], v[160:163], v[206:209], v[26:29]
	v_mfma_f32_16x16x32_bf16 v[14:17], v[134:137], v[226:229], v[14:17]
	v_mfma_f32_16x16x32_bf16 v[10:13], v[160:163], v[226:229], v[10:13]
	s_setprio 0
	s_setprio 1
	v_mfma_f32_16x16x32_bf16 v[54:57], v[164:167], v[186:189], v[54:57]
	v_mfma_f32_16x16x32_bf16 v[50:53], v[172:175], v[186:189], v[50:53]
	v_mfma_f32_16x16x32_bf16 v[38:41], v[164:167], v[194:197], v[38:41]
	v_mfma_f32_16x16x32_bf16 v[34:37], v[172:175], v[194:197], v[34:37]
	v_mfma_f32_16x16x32_bf16 v[22:25], v[164:167], v[202:205], v[22:25]
	v_mfma_f32_16x16x32_bf16 v[18:21], v[172:175], v[202:205], v[18:21]
	v_mfma_f32_16x16x32_bf16 v[6:9], v[164:167], v[210:213], v[6:9]
	v_mfma_f32_16x16x32_bf16 v[2:5], v[172:175], v[210:213], v[2:5]
	v_mfma_f32_16x16x32_bf16 v[54:57], v[168:171], v[190:193], v[54:57]
	v_mfma_f32_16x16x32_bf16 v[50:53], v[176:179], v[190:193], v[50:53]
	v_mfma_f32_16x16x32_bf16 v[38:41], v[168:171], v[198:201], v[38:41]
	v_mfma_f32_16x16x32_bf16 v[34:37], v[176:179], v[198:201], v[34:37]
	v_mfma_f32_16x16x32_bf16 v[22:25], v[168:171], v[206:209], v[22:25]
	v_mfma_f32_16x16x32_bf16 v[18:21], v[176:179], v[206:209], v[18:21]
	v_mfma_f32_16x16x32_bf16 v[6:9], v[168:171], v[226:229], v[6:9]
	v_mfma_f32_16x16x32_bf16 v[2:5], v[176:179], v[226:229], v[2:5]
	s_setprio 0
	s_barrier
	s_add_i32 s52, s52, 2
	s_add_u32 s46, s46, 0x100
	s_addc_u32 s51, s51, 0
	s_add_u32 s18, s18, 0x100
	s_addc_u32 s19, s19, 0
	s_cmp_gt_u32 s52, 13
	s_cbranch_scc0 .LBB0_182
	s_branch .Lkend_proj
.Lkb_proj:
	s_add_u32 s24, s18, 0xfffc0080
	s_addc_u32 s25, s19, -1
	s_add_i32 s53, 0, 0x10000
	s_cmp_eq_u32 s52, 12
	s_cselect_b32 s27, s13, s25
	s_cselect_b32 s26, s21, s24
	v_add_u32_e32 v151, s53, v154
	s_cselect_b32 s25, s11, s51
	s_cselect_b32 s24, s23, s46
	s_add_i32 s56, 0, 0x14000
	ds_read_b128 v[130:133], v151
	ds_read_b128 v[134:137], v151 offset:1024
	ds_read_b128 v[156:159], v151 offset:2048
	ds_read_b128 v[160:163], v151 offset:3072
	v_add_u32_e32 v151, s56, v154
	ds_read_b128 v[164:167], v151
	ds_read_b128 v[168:171], v151 offset:1024
	ds_read_b128 v[172:175], v151 offset:2048
	ds_read_b128 v[176:179], v151 offset:3072
	v_lshl_add_u64 v[152:153], s[18:19], 0, v[148:149]
	s_add_i32 m0, s36, 0xc000
	ds_read_b128 v[186:189], v155
	ds_read_b128 v[190:193], v155 offset:1024
	ds_read_b128 v[194:197], v155 offset:2048
	ds_read_b128 v[198:201], v155 offset:3072
	ds_read_b128 v[202:205], v155 offset:4096
	ds_read_b128 v[206:209], v155 offset:5120
	ds_read_b128 v[210:213], v155 offset:6144
	ds_read_b128 v[226:229], v155 offset:7168
	global_load_lds_dwordx4 v[152:153], off
	v_lshl_add_u64 v[152:153], s[18:19], 0, v[146:147]
	s_add_i32 m0, s36, 0xe000
	s_nop 0
	global_load_lds_dwordx4 v[152:153], off
	s_waitcnt vmcnt(8)
	s_waitcnt lgkmcnt(0)
	s_barrier
	s_setprio 2
	s_waitcnt lgkmcnt(0)
	v_mfma_f32_16x16x32_bf16 v[126:129], v[130:133], v[186:189], v[126:129]
	v_mfma_f32_16x16x32_bf16 v[122:125], v[156:159], v[186:189], v[122:125]
	v_mfma_f32_16x16x32_bf16 v[110:113], v[130:133], v[194:197], v[110:113]
	v_mfma_f32_16x16x32_bf16 v[106:109], v[156:159], v[194:197], v[106:109]
	v_mfma_f32_16x16x32_bf16 v[94:97], v[130:133], v[202:205], v[94:97]
	v_mfma_f32_16x16x32_bf16 v[90:93], v[156:159], v[202:205], v[90:93]
	v_mfma_f32_16x16x32_bf16 v[78:81], v[130:133], v[210:213], v[78:81]
	v_mfma_f32_16x16x32_bf16 v[74:77], v[156:159], v[210:213], v[74:77]
	v_mfma_f32_16x16x32_bf16 v[126:129], v[134:137], v[190:193], v[126:129]
	v_mfma_f32_16x16x32_bf16 v[122:125], v[160:163], v[190:193], v[122:125]
	v_mfma_f32_16x16x32_bf16 v[110:113], v[134:137], v[198:201], v[110:113]
	v_mfma_f32_16x16x32_bf16 v[106:109], v[160:163], v[198:201], v[106:109]
	v_mfma_f32_16x16x32_bf16 v[94:97], v[134:137], v[206:209], v[94:97]
	v_mfma_f32_16x16x32_bf16 v[90:93], v[160:163], v[206:209], v[90:93]
	v_mfma_f32_16x16x32_bf16 v[78:81], v[134:137], v[226:229], v[78:81]
	v_mfma_f32_16x16x32_bf16 v[74:77], v[160:163], v[226:229], v[74:77]
	s_setprio 1
	s_setprio 2
	v_mfma_f32_16x16x32_bf16 v[118:121], v[164:167], v[186:189], v[118:121]
	v_mfma_f32_16x16x32_bf16 v[114:117], v[172:175], v[186:189], v[114:117]
	v_mfma_f32_16x16x32_bf16 v[102:105], v[164:167], v[194:197], v[102:105]
	v_mfma_f32_16x16x32_bf16 v[98:101], v[172:175], v[194:197], v[98:101]
	v_mfma_f32_16x16x32_bf16 v[86:89], v[164:167], v[202:205], v[86:89]
	v_mfma_f32_16x16x32_bf16 v[82:85], v[172:175], v[202:205], v[82:85]
	v_mfma_f32_16x16x32_bf16 v[70:73], v[164:167], v[210:213], v[70:73]
	v_mfma_f32_16x16x32_bf16 v[66:69], v[172:175], v[210:213], v[66:69]
	v_mfma_f32_16x16x32_bf16 v[118:121], v[168:171], v[190:193], v[118:121]
	v_mfma_f32_16x16x32_bf16 v[114:117], v[176:179], v[190:193], v[114:117]
	v_mfma_f32_16x16x32_bf16 v[102:105], v[168:171], v[198:201], v[102:105]
	v_mfma_f32_16x16x32_bf16 v[98:101], v[176:179], v[198:201], v[98:101]
	v_mfma_f32_16x16x32_bf16 v[86:89], v[168:171], v[206:209], v[86:89]
	v_mfma_f32_16x16x32_bf16 v[82:85], v[176:179], v[206:209], v[82:85]
	v_mfma_f32_16x16x32_bf16 v[70:73], v[168:171], v[226:229], v[70:73]
	v_mfma_f32_16x16x32_bf16 v[66:69], v[176:179], v[226:229], v[66:69]
	s_setprio 1
	s_barrier
; #define PG8_STAGE(bufoff, gbase, voff) do { _Pragma("unroll") for (int _i = 0; _i < 2; ++_i) \
;         __builtin_amdgcn_global_load_lds((const unsigned*)((const char*)(gbase) + (voff)[_i]), (LAS unsigned*)(lds + (bufoff) + ldsw + _i * 8192), 16, 0, 0); } while (0)
; #define PG8_LDA(dst, b, h) do { _Pragma("unroll") for (int m = 0; m < 4; ++m) _Pragma("unroll") for (int k = 0; k < 2; ++k) dst[m][k] = *(const LAS bf16x8*)(lds + PG8_SA(b, h) + aoff + m * 2048 + k * 1024); } while (0)
; #define PG8_LDB(dst, b, h) do { _Pragma("unroll") for (int n = 0; n < 2; ++n) _Pragma("unroll") for (int k = 0; k < 2; ++k) dst[n][k] = *(const LAS bf16x8*)(lds + PG8_SB(b, h) + boff + n * 2048 + k * 1024); } while (0)
; #define PG8_MMA(ai, bj, At, Bt) do { __builtin_amdgcn_s_setprio(1); _Pragma("unroll") for (int m = 0; m < 4; ++m) _Pragma("unroll") for (int n = 0; n < 2; ++n) _Pragma("unroll") for (int k = 0; k < 2; ++k) \
;         acc[ai][bj][m][n] = __builtin_amdgcn_mfma_f32_16x16x32_bf16(Bt[n][k], At[m][k], acc[ai][bj][m][n], 0, 0, 0); __builtin_amdgcn_s_setprio(0); } while (0)
; #define PG8_WAIT_V(n) asm volatile("s_waitcnt vmcnt(" #n ")" ::: "memory")
; #define PG8_WAIT_L(n) asm volatile("s_waitcnt lgkmcnt(" #n ")" ::: "memory")
; #define PG8_BAR __builtin_amdgcn_s_barrier()
; #define PG8_SCHED __builtin_amdgcn_sched_barrier(0)
; #define PG8_LDA(dst, b, h) do { _Pragma("unroll") for (int m = 0; m < 4; ++m) _Pragma("unroll") for (int k = 0; k < 2; ++k) dst[m][k] = *(const LAS bf16x8*)(lds + PG8_SA(b, h) + aoff + m * 2048 + k * 1024); } while (0)
; template <class Epi, class Sched>
; __device__ __forceinline__ void gemm_phase(LAS unsigned char* lds, const Gemm g, const Sched& S, const Epi& E) {
;     ...
;             PG8_LDA(At, 0, 1); PG8_STAGE(PG8_SB(0, 0), b2, voffB); PG8_STAGE(PG8_SB(0, 1), b2 + hstepB, voffB); PG8_STAGE(PG8_SA(0, 0), a2, voffA);
;             PG8_WAIT_V(8); PG8_WAIT_L(0); PG8_BAR; PG8_MMA(1, 0, At, B0); PG8_MMA(1, 1, At, B1); PG8_BAR; PG8_SCHED;
;             PG8_LDB(B0, 1, 0); PG8_LDB(B1, 1, 1); PG8_SCHED; PG8_LDA(At, 1, 0); PG8_STAGE(PG8_SA(0, 1), a2 + hstepA, voffA);
;             PG8_WAIT_V(8); PG8_WAIT_L(0); PG8_BAR; PG8_MMA(0, 0, At, B0); PG8_MMA(0, 1, At, B1); PG8_BAR; PG8_SCHED;
;             PG8_LDA(At, 1, 1); PG8_STAGE(PG8_SB(1, 0), b3, voffB); PG8_STAGE(PG8_SB(1, 1), b3 + hstepB, voffB); PG8_STAGE(PG8_SA(1, 0), a3, voffA);
	s_add_i32 s53, s53, s31
	v_lshl_add_u64 v[152:153], s[24:25], 0, v[140:141]
	s_mov_b32 m0, s53
	ds_read_b128 v[186:189], v155 offset:16384
	ds_read_b128 v[190:193], v155 offset:17408
	ds_read_b128 v[194:197], v155 offset:18432
	ds_read_b128 v[198:201], v155 offset:19456
	ds_read_b128 v[202:205], v155 offset:20480
	ds_read_b128 v[206:209], v155 offset:21504
	ds_read_b128 v[210:213], v155 offset:22528
	ds_read_b128 v[226:229], v155 offset:23552
	global_load_lds_dwordx4 v[152:153], off
	s_add_i32 m0, s53, 0x2000
	s_add_u32 s54, s24, 0x40000
	v_lshl_add_u64 v[182:183], s[24:25], 0, v[144:145]
	s_addc_u32 s55, s25, 0
	s_add_i32 s53, s56, s31
	global_load_lds_dwordx4 v[182:183], off
	v_lshl_add_u64 v[184:185], s[54:55], 0, v[140:141]
	s_mov_b32 m0, s53
	v_lshl_add_u64 v[214:215], s[26:27], 0, v[142:143]
	global_load_lds_dwordx4 v[184:185], off
	v_lshl_add_u64 v[184:185], s[54:55], 0, v[144:145]
	s_add_i32 m0, s53, 0x2000
	s_nop 0
	global_load_lds_dwordx4 v[184:185], off
	v_lshl_add_u64 v[184:185], s[26:27], 0, v[138:139]
	s_mov_b32 m0, s36
	s_nop 0
	global_load_lds_dwordx4 v[184:185], off
	s_mov_b32 m0, s37
	s_nop 0
	global_load_lds_dwordx4 v[214:215], off
	s_waitcnt vmcnt(8)
	s_waitcnt lgkmcnt(0)
	s_barrier
	s_setprio 2
	s_waitcnt lgkmcnt(0)
	v_mfma_f32_16x16x32_bf16 v[62:65], v[130:133], v[186:189], v[62:65]
	v_mfma_f32_16x16x32_bf16 v[58:61], v[156:159], v[186:189], v[58:61]
	v_mfma_f32_16x16x32_bf16 v[46:49], v[130:133], v[194:197], v[46:49]
	v_mfma_f32_16x16x32_bf16 v[42:45], v[156:159], v[194:197], v[42:45]
	v_mfma_f32_16x16x32_bf16 v[30:33], v[130:133], v[202:205], v[30:33]
	v_mfma_f32_16x16x32_bf16 v[26:29], v[156:159], v[202:205], v[26:29]
	v_mfma_f32_16x16x32_bf16 v[14:17], v[130:133], v[210:213], v[14:17]
	v_mfma_f32_16x16x32_bf16 v[10:13], v[156:159], v[210:213], v[10:13]
	v_mfma_f32_16x16x32_bf16 v[62:65], v[134:137], v[190:193], v[62:65]
	v_mfma_f32_16x16x32_bf16 v[58:61], v[160:163], v[190:193], v[58:61]
	v_mfma_f32_16x16x32_bf16 v[46:49], v[134:137], v[198:201], v[46:49]
	v_mfma_f32_16x16x32_bf16 v[42:45], v[160:163], v[198:201], v[42:45]
	v_mfma_f32_16x16x32_bf16 v[30:33], v[134:137], v[206:209], v[30:33]
	v_mfma_f32_16x16x32_bf16 v[26:29], v[160:163], v[206:209], v[26:29]
	v_mfma_f32_16x16x32_bf16 v[14:17], v[134:137], v[226:229], v[14:17]
	v_mfma_f32_16x16x32_bf16 v[10:13], v[160:163], v[226:229], v[10:13]
	s_setprio 1
	s_setprio 2
	v_mfma_f32_16x16x32_bf16 v[54:57], v[164:167], v[186:189], v[54:57]
	v_mfma_f32_16x16x32_bf16 v[50:53], v[172:175], v[186:189], v[50:53]
	v_mfma_f32_16x16x32_bf16 v[38:41], v[164:167], v[194:197], v[38:41]
	v_mfma_f32_16x16x32_bf16 v[34:37], v[172:175], v[194:197], v[34:37]
	v_mfma_f32_16x16x32_bf16 v[22:25], v[164:167], v[202:205], v[22:25]
	v_mfma_f32_16x16x32_bf16 v[18:21], v[172:175], v[202:205], v[18:21]
	v_mfma_f32_16x16x32_bf16 v[6:9], v[164:167], v[210:213], v[6:9]
	v_mfma_f32_16x16x32_bf16 v[2:5], v[172:175], v[210:213], v[2:5]
	v_mfma_f32_16x16x32_bf16 v[54:57], v[168:171], v[190:193], v[54:57]
	v_mfma_f32_16x16x32_bf16 v[50:53], v[176:179], v[190:193], v[50:53]
	v_mfma_f32_16x16x32_bf16 v[38:41], v[168:171], v[198:201], v[38:41]
	v_mfma_f32_16x16x32_bf16 v[34:37], v[176:179], v[198:201], v[34:37]
	v_mfma_f32_16x16x32_bf16 v[22:25], v[168:171], v[206:209], v[22:25]
	v_mfma_f32_16x16x32_bf16 v[18:21], v[176:179], v[206:209], v[18:21]
	v_mfma_f32_16x16x32_bf16 v[6:9], v[168:171], v[226:229], v[6:9]
	v_mfma_f32_16x16x32_bf16 v[2:5], v[176:179], v[226:229], v[2:5]
	s_setprio 1
	s_barrier
	s_add_i32 s53, 0, 0x18000
	v_add_u32_e32 v151, s53, v154
	s_add_i32 s54, 0, 0x1c000
	ds_read_b128 v[130:133], v151
	ds_read_b128 v[134:137], v151 offset:1024
	ds_read_b128 v[156:159], v151 offset:2048
	ds_read_b128 v[160:163], v151 offset:3072
	v_add_u32_e32 v151, s54, v154
	ds_read_b128 v[164:167], v151
	ds_read_b128 v[168:171], v151 offset:1024
	ds_read_b128 v[172:175], v151 offset:2048
	ds_read_b128 v[176:179], v151 offset:3072
	s_add_u32 s26, s26, 0x40000
	s_addc_u32 s27, s27, 0
	s_mov_b32 m0, s38
	v_lshl_add_u64 v[230:231], s[26:27], 0, v[138:139]
	ds_read_b128 v[186:189], v155 offset:32768
	ds_read_b128 v[190:193], v155 offset:33792
	ds_read_b128 v[194:197], v155 offset:34816
	ds_read_b128 v[198:201], v155 offset:35840
	ds_read_b128 v[202:205], v155 offset:36864
	ds_read_b128 v[206:209], v155 offset:37888
	ds_read_b128 v[210:213], v155 offset:38912
	ds_read_b128 v[226:229], v155 offset:39936
	global_load_lds_dwordx4 v[230:231], off
	v_lshl_add_u64 v[230:231], s[26:27], 0, v[142:143]
	s_mov_b32 m0, s39
	s_nop 0
	global_load_lds_dwordx4 v[230:231], off
	s_waitcnt vmcnt(8)
	s_waitcnt lgkmcnt(0)
	s_barrier
; #define PG8_MMA(ai, bj, At, Bt) do { __builtin_amdgcn_s_setprio(1); _Pragma("unroll") for (int m = 0; m < 4; ++m) _Pragma("unroll") for (int n = 0; n < 2; ++n) _Pragma("unroll") for (int k = 0; k < 2; ++k) \
;         acc[ai][bj][m][n] = __builtin_amdgcn_mfma_f32_16x16x32_bf16(Bt[n][k], At[m][k], acc[ai][bj][m][n], 0, 0, 0); __builtin_amdgcn_s_setprio(0); } while (0)
; #define PG8_WAIT_V(n) asm volatile("s_waitcnt vmcnt(" #n ")" ::: "memory")
; #define PG8_WAIT_L(n) asm volatile("s_waitcnt lgkmcnt(" #n ")" ::: "memory")
; #define PG8_BAR __builtin_amdgcn_s_barrier()
; #define PG8_SCHED __builtin_amdgcn_sched_barrier(0)
; #define PG8_MMA(ai, bj, At, Bt) do { __builtin_amdgcn_s_setprio(1); _Pragma("unroll") for (int m = 0; m < 4; ++m) _Pragma("unroll") for (int n = 0; n < 2; ++n) _Pragma("unroll") for (int k = 0; k < 2; ++k) \
;         acc[ai][bj][m][n] = __builtin_amdgcn_mfma_f32_16x16x32_bf16(Bt[n][k], At[m][k], acc[ai][bj][m][n], 0, 0, 0); __builtin_amdgcn_s_setprio(0); } while (0)
; #define PG8_WAIT_V(n) asm volatile("s_waitcnt vmcnt(" #n ")" ::: "memory")
; #define PG8_WAIT_L(n) asm volatile("s_waitcnt lgkmcnt(" #n ")" ::: "memory")
; #define PG8_BAR __builtin_amdgcn_s_barrier()
; #define PG8_SCHED __builtin_amdgcn_sched_barrier(0)
; template <class Epi, class Sched>
; __device__ __forceinline__ void gemm_phase(LAS unsigned char* lds, const Gemm g, const Sched& S, const Epi& E) {
;     ...
;             PG8_WAIT_V(8); PG8_WAIT_L(0); PG8_BAR; PG8_MMA(1, 0, At, B0); PG8_MMA(1, 1, At, B1); PG8_BAR; PG8_SCHED;
;         }
;         if (wr == 0) PG8_BAR;
	s_setprio 2
	s_waitcnt lgkmcnt(0)
	v_mfma_f32_16x16x32_bf16 v[126:129], v[130:133], v[186:189], v[126:129]
	v_mfma_f32_16x16x32_bf16 v[122:125], v[156:159], v[186:189], v[122:125]
	v_mfma_f32_16x16x32_bf16 v[110:113], v[130:133], v[194:197], v[110:113]
	v_mfma_f32_16x16x32_bf16 v[106:109], v[156:159], v[194:197], v[106:109]
	v_mfma_f32_16x16x32_bf16 v[94:97], v[130:133], v[202:205], v[94:97]
	v_mfma_f32_16x16x32_bf16 v[90:93], v[156:159], v[202:205], v[90:93]
	v_mfma_f32_16x16x32_bf16 v[78:81], v[130:133], v[210:213], v[78:81]
	v_mfma_f32_16x16x32_bf16 v[74:77], v[156:159], v[210:213], v[74:77]
	v_mfma_f32_16x16x32_bf16 v[126:129], v[134:137], v[190:193], v[126:129]
	v_mfma_f32_16x16x32_bf16 v[122:125], v[160:163], v[190:193], v[122:125]
	v_mfma_f32_16x16x32_bf16 v[110:113], v[134:137], v[198:201], v[110:113]
	v_mfma_f32_16x16x32_bf16 v[106:109], v[160:163], v[198:201], v[106:109]
	v_mfma_f32_16x16x32_bf16 v[94:97], v[134:137], v[206:209], v[94:97]
	v_mfma_f32_16x16x32_bf16 v[90:93], v[160:163], v[206:209], v[90:93]
	v_mfma_f32_16x16x32_bf16 v[78:81], v[134:137], v[226:229], v[78:81]
	v_mfma_f32_16x16x32_bf16 v[74:77], v[160:163], v[226:229], v[74:77]
	s_setprio 1
	s_setprio 2
	v_mfma_f32_16x16x32_bf16 v[118:121], v[164:167], v[186:189], v[118:121]
	v_mfma_f32_16x16x32_bf16 v[114:117], v[172:175], v[186:189], v[114:117]
	v_mfma_f32_16x16x32_bf16 v[102:105], v[164:167], v[194:197], v[102:105]
	v_mfma_f32_16x16x32_bf16 v[98:101], v[172:175], v[194:197], v[98:101]
	v_mfma_f32_16x16x32_bf16 v[86:89], v[164:167], v[202:205], v[86:89]
	v_mfma_f32_16x16x32_bf16 v[82:85], v[172:175], v[202:205], v[82:85]
	v_mfma_f32_16x16x32_bf16 v[70:73], v[164:167], v[210:213], v[70:73]
	v_mfma_f32_16x16x32_bf16 v[66:69], v[172:175], v[210:213], v[66:69]
	v_mfma_f32_16x16x32_bf16 v[118:121], v[168:171], v[190:193], v[118:121]
	v_mfma_f32_16x16x32_bf16 v[114:117], v[176:179], v[190:193], v[114:117]
	v_mfma_f32_16x16x32_bf16 v[102:105], v[168:171], v[198:201], v[102:105]
	v_mfma_f32_16x16x32_bf16 v[98:101], v[176:179], v[198:201], v[98:101]
	v_mfma_f32_16x16x32_bf16 v[86:89], v[168:171], v[206:209], v[86:89]
	v_mfma_f32_16x16x32_bf16 v[82:85], v[176:179], v[206:209], v[82:85]
	v_mfma_f32_16x16x32_bf16 v[70:73], v[168:171], v[226:229], v[70:73]
	v_mfma_f32_16x16x32_bf16 v[66:69], v[176:179], v[226:229], v[66:69]
	s_setprio 1
	s_barrier
	s_add_i32 s26, s53, s31
	v_lshl_add_u64 v[152:153], v[152:153], 0, s[86:87]
	s_mov_b32 m0, s26
	ds_read_b128 v[186:189], v155 offset:49152
	ds_read_b128 v[190:193], v155 offset:50176
	ds_read_b128 v[194:197], v155 offset:51200
	ds_read_b128 v[198:201], v155 offset:52224
	ds_read_b128 v[202:205], v155 offset:53248
	ds_read_b128 v[206:209], v155 offset:54272
	ds_read_b128 v[210:213], v155 offset:55296
	ds_read_b128 v[226:229], v155 offset:56320
	global_load_lds_dwordx4 v[152:153], off
	s_add_i32 m0, s26, 0x2000
	s_add_u32 s24, s24, 0x40080
	v_lshl_add_u64 v[152:153], v[182:183], 0, s[86:87]
	s_addc_u32 s25, s25, 0
	s_add_i32 s26, s54, s31
	global_load_lds_dwordx4 v[152:153], off
	v_lshl_add_u64 v[152:153], s[24:25], 0, v[140:141]
	s_mov_b32 m0, s26
	s_nop 0
	global_load_lds_dwordx4 v[152:153], off
	v_lshl_add_u64 v[152:153], s[24:25], 0, v[144:145]
	s_add_i32 m0, s26, 0x2000
	s_nop 0
	global_load_lds_dwordx4 v[152:153], off
	v_lshl_add_u64 v[152:153], v[184:185], 0, s[86:87]
	s_mov_b32 m0, s48
	s_nop 0
	global_load_lds_dwordx4 v[152:153], off
	v_lshl_add_u64 v[152:153], v[214:215], 0, s[86:87]
	s_mov_b32 m0, s49
	s_nop 0
	global_load_lds_dwordx4 v[152:153], off
	s_waitcnt vmcnt(8)
	s_waitcnt lgkmcnt(0)
	s_barrier
	s_setprio 2
	s_waitcnt lgkmcnt(0)
	v_mfma_f32_16x16x32_bf16 v[62:65], v[130:133], v[186:189], v[62:65]
	v_mfma_f32_16x16x32_bf16 v[58:61], v[156:159], v[186:189], v[58:61]
	v_mfma_f32_16x16x32_bf16 v[46:49], v[130:133], v[194:197], v[46:49]
	v_mfma_f32_16x16x32_bf16 v[42:45], v[156:159], v[194:197], v[42:45]
	v_mfma_f32_16x16x32_bf16 v[30:33], v[130:133], v[202:205], v[30:33]
	v_mfma_f32_16x16x32_bf16 v[26:29], v[156:159], v[202:205], v[26:29]
	v_mfma_f32_16x16x32_bf16 v[14:17], v[130:133], v[210:213], v[14:17]
	v_mfma_f32_16x16x32_bf16 v[10:13], v[156:159], v[210:213], v[10:13]
	v_mfma_f32_16x16x32_bf16 v[62:65], v[134:137], v[190:193], v[62:65]
	v_mfma_f32_16x16x32_bf16 v[58:61], v[160:163], v[190:193], v[58:61]
	v_mfma_f32_16x16x32_bf16 v[46:49], v[134:137], v[198:201], v[46:49]
	v_mfma_f32_16x16x32_bf16 v[42:45], v[160:163], v[198:201], v[42:45]
	v_mfma_f32_16x16x32_bf16 v[30:33], v[134:137], v[206:209], v[30:33]
	v_mfma_f32_16x16x32_bf16 v[26:29], v[160:163], v[206:209], v[26:29]
	v_mfma_f32_16x16x32_bf16 v[14:17], v[134:137], v[226:229], v[14:17]
	v_mfma_f32_16x16x32_bf16 v[10:13], v[160:163], v[226:229], v[10:13]
	s_setprio 1
	s_setprio 2
	v_mfma_f32_16x16x32_bf16 v[54:57], v[164:167], v[186:189], v[54:57]
	v_mfma_f32_16x16x32_bf16 v[50:53], v[172:175], v[186:189], v[50:53]
	v_mfma_f32_16x16x32_bf16 v[38:41], v[164:167], v[194:197], v[38:41]
	v_mfma_f32_16x16x32_bf16 v[34:37], v[172:175], v[194:197], v[34:37]
	v_mfma_f32_16x16x32_bf16 v[22:25], v[164:167], v[202:205], v[22:25]
	v_mfma_f32_16x16x32_bf16 v[18:21], v[172:175], v[202:205], v[18:21]
	v_mfma_f32_16x16x32_bf16 v[6:9], v[164:167], v[210:213], v[6:9]
	v_mfma_f32_16x16x32_bf16 v[2:5], v[172:175], v[210:213], v[2:5]
	v_mfma_f32_16x16x32_bf16 v[54:57], v[168:171], v[190:193], v[54:57]
	v_mfma_f32_16x16x32_bf16 v[50:53], v[176:179], v[190:193], v[50:53]
	v_mfma_f32_16x16x32_bf16 v[38:41], v[168:171], v[198:201], v[38:41]
	v_mfma_f32_16x16x32_bf16 v[34:37], v[176:179], v[198:201], v[34:37]
	v_mfma_f32_16x16x32_bf16 v[22:25], v[168:171], v[206:209], v[22:25]
	v_mfma_f32_16x16x32_bf16 v[18:21], v[176:179], v[206:209], v[18:21]
	v_mfma_f32_16x16x32_bf16 v[6:9], v[168:171], v[226:229], v[6:9]
	v_mfma_f32_16x16x32_bf16 v[2:5], v[176:179], v[226:229], v[2:5]
	s_setprio 1
	s_barrier
	s_add_i32 s52, s52, 2
	s_add_u32 s46, s46, 0x100
	s_addc_u32 s51, s51, 0
	s_add_u32 s18, s18, 0x100
	s_addc_u32 s19, s19, 0
	s_cmp_gt_u32 s52, 13
	s_cbranch_scc0 .Lkb_proj
	s_setprio 0
.Lkend_proj:
	s_and_b64 vcc, exec, s[8:9]
	s_cbranch_vccz .LBB0_185
	s_barrier

; #define PG8_STAGE(bufoff, gbase, voff) do { _Pragma("unroll") for (int _i = 0; _i < 2; ++_i) \
;         __builtin_amdgcn_global_load_lds((const unsigned*)((const char*)(gbase) + (voff)[_i]), (LAS unsigned*)(lds + (bufoff) + ldsw + _i * 8192), 16, 0, 0); } while (0)
; #define PG8_LDA(dst, b, h) do { _Pragma("unroll") for (int m = 0; m < 4; ++m) _Pragma("unroll") for (int k = 0; k < 2; ++k) dst[m][k] = *(const LAS bf16x8*)(lds + PG8_SA(b, h) + aoff + m * 2048 + k * 1024); } while (0)
; #define PG8_LDB(dst, b, h) do { _Pragma("unroll") for (int n = 0; n < 2; ++n) _Pragma("unroll") for (int k = 0; k < 2; ++k) dst[n][k] = *(const LAS bf16x8*)(lds + PG8_SB(b, h) + boff + n * 2048 + k * 1024); } while (0)
; #define PG8_SCHED __builtin_amdgcn_sched_barrier(0)
; #define PG8_STAGE(bufoff, gbase, voff) do { _Pragma("unroll") for (int _i = 0; _i < 2; ++_i) \
;         __builtin_amdgcn_global_load_lds((const unsigned*)((const char*)(gbase) + (voff)[_i]), (LAS unsigned*)(lds + (bufoff) + ldsw + _i * 8192), 16, 0, 0); } while (0)
; #define PG8_LDA(dst, b, h) do { _Pragma("unroll") for (int m = 0; m < 4; ++m) _Pragma("unroll") for (int k = 0; k < 2; ++k) dst[m][k] = *(const LAS bf16x8*)(lds + PG8_SA(b, h) + aoff + m * 2048 + k * 1024); } while (0)
; #define PG8_SCHED __builtin_amdgcn_sched_barrier(0)
; template <class Epi, class Sched>
; __device__ __forceinline__ void gemm_phase(LAS unsigned char* lds, const Gemm g, const Sched& S, const Epi& E) {
;     ...
;         const char* nA = has_next ? (const char*)g.A + (size_t)nxt.pm * tstepA : cA; const char* nB = has_next ? (const char*)g.Bt + (size_t)nxt.pn * tstepB : cB;
;         for (int t = 0; t < nt; t += 2) {
;             const bool last = (t == nt - 2);
;             const char* a1 = cA + (size_t)(t + 1) * kstep;
;             const char* a2 = last ? nA : cA + (size_t)(t + 2) * kstep; const char* b2 = last ? nB : cB + (size_t)(t + 2) * kstep;
;             const char* a3 = a2 + kstep; const char* b3 = b2 + kstep;
;             PG8_LDB(B0, 0, 0); PG8_LDB(B1, 0, 1); PG8_SCHED; PG8_LDA(At, 0, 0); PG8_STAGE(PG8_SA(1, 1), a1 + hstepA, voffA);
;     ...
; #pragma unroll
;         for (int a = 0; a < 2; ++a)
; #pragma unroll
;             for (int b = 0; b < 2; ++b)
; #pragma unroll
;                 for (int m = 0; m < 4; ++m)
; #pragma unroll
;                     for (int n = 0; n < 2; ++n) acc[a][b][m][n] = (f32x4){0.f, 0.f, 0.f, 0.f};
.LBB0_830:
	s_ashr_i32 s15, s14, 31
	s_lshl_b64 s[16:17], s[14:15], 19
	s_add_u32 s16, s31, s16
	s_addc_u32 s17, s34, s17
	s_and_b64 s[18:19], s[6:7], exec
	s_cselect_b32 s15, s17, s23
	s_cselect_b32 s46, s16, s22
	s_ashr_i32 s13, s12, 31
	s_lshl_b64 s[18:19], s[12:13], 19
	s_add_u32 s18, s28, s18
	s_addc_u32 s19, s29, s19
	s_and_b64 s[24:25], s[6:7], exec
	s_cselect_b32 s13, s19, s21
	s_cselect_b32 s48, s18, s20
	s_add_u32 s49, s20, 0x100
	s_addc_u32 s50, s21, 0
	s_add_u32 s20, s22, 0x40080
	v_mov_b32_e32 v2, 0
	s_addc_u32 s21, s23, 0
	s_mov_b32 s51, -2
	v_mov_b32_e32 v3, v2
	v_mov_b32_e32 v4, v2
	v_mov_b32_e32 v5, v2
	v_mov_b32_e32 v6, v2
	v_mov_b32_e32 v7, v2
	v_mov_b32_e32 v8, v2
	v_mov_b32_e32 v9, v2
	v_mov_b32_e32 v18, v2
	v_mov_b32_e32 v19, v2
	v_mov_b32_e32 v20, v2
	v_mov_b32_e32 v21, v2
	v_mov_b32_e32 v22, v2
	v_mov_b32_e32 v23, v2
	v_mov_b32_e32 v24, v2
	v_mov_b32_e32 v25, v2
	v_mov_b32_e32 v34, v2
	v_mov_b32_e32 v35, v2
	v_mov_b32_e32 v36, v2
	v_mov_b32_e32 v37, v2
	v_mov_b32_e32 v38, v2
	v_mov_b32_e32 v39, v2
	v_mov_b32_e32 v40, v2
	v_mov_b32_e32 v41, v2
	v_mov_b32_e32 v50, v2
	v_mov_b32_e32 v51, v2
	v_mov_b32_e32 v52, v2
	v_mov_b32_e32 v53, v2
	v_mov_b32_e32 v54, v2
	v_mov_b32_e32 v55, v2
	v_mov_b32_e32 v56, v2
	v_mov_b32_e32 v57, v2
	v_mov_b32_e32 v10, v2
	v_mov_b32_e32 v11, v2
	v_mov_b32_e32 v12, v2
	v_mov_b32_e32 v13, v2
	v_mov_b32_e32 v14, v2
	v_mov_b32_e32 v15, v2
	v_mov_b32_e32 v16, v2
	v_mov_b32_e32 v17, v2
	v_mov_b32_e32 v26, v2
	v_mov_b32_e32 v27, v2
	v_mov_b32_e32 v28, v2
	v_mov_b32_e32 v29, v2
	v_mov_b32_e32 v30, v2
	v_mov_b32_e32 v31, v2
	v_mov_b32_e32 v32, v2
	v_mov_b32_e32 v33, v2
	v_mov_b32_e32 v42, v2
	v_mov_b32_e32 v43, v2
	v_mov_b32_e32 v44, v2
	v_mov_b32_e32 v45, v2
	v_mov_b32_e32 v46, v2
	v_mov_b32_e32 v47, v2
	v_mov_b32_e32 v48, v2
	v_mov_b32_e32 v49, v2
	v_mov_b32_e32 v58, v2
	v_mov_b32_e32 v59, v2
	v_mov_b32_e32 v60, v2
	v_mov_b32_e32 v61, v2
	v_mov_b32_e32 v62, v2
	v_mov_b32_e32 v63, v2
	v_mov_b32_e32 v64, v2
	v_mov_b32_e32 v65, v2
	v_mov_b32_e32 v66, v2
	v_mov_b32_e32 v67, v2
	v_mov_b32_e32 v68, v2
	v_mov_b32_e32 v69, v2
	v_mov_b32_e32 v70, v2
	v_mov_b32_e32 v71, v2
	v_mov_b32_e32 v72, v2
	v_mov_b32_e32 v73, v2
	v_mov_b32_e32 v82, v2
	v_mov_b32_e32 v83, v2
	v_mov_b32_e32 v84, v2
	v_mov_b32_e32 v85, v2
	v_mov_b32_e32 v86, v2
	v_mov_b32_e32 v87, v2
	v_mov_b32_e32 v88, v2
	v_mov_b32_e32 v89, v2
	v_mov_b32_e32 v98, v2
	v_mov_b32_e32 v99, v2
	v_mov_b32_e32 v100, v2
	v_mov_b32_e32 v101, v2
	v_mov_b32_e32 v102, v2
	v_mov_b32_e32 v103, v2
	v_mov_b32_e32 v104, v2
	v_mov_b32_e32 v105, v2
	s_waitcnt vmcnt(0)
	v_mov_b32_e32 v114, v2
	v_mov_b32_e32 v115, v2
	v_mov_b32_e32 v116, v2
	v_mov_b32_e32 v117, v2
	v_mov_b32_e32 v118, v2
	v_mov_b32_e32 v119, v2
	v_mov_b32_e32 v120, v2
	v_mov_b32_e32 v121, v2
	v_mov_b32_e32 v74, v2
	v_mov_b32_e32 v75, v2
	v_mov_b32_e32 v76, v2
	v_mov_b32_e32 v77, v2
	v_mov_b32_e32 v78, v2
	v_mov_b32_e32 v79, v2
	v_mov_b32_e32 v80, v2
	v_mov_b32_e32 v81, v2
	v_mov_b32_e32 v90, v2
	v_mov_b32_e32 v91, v2
	v_mov_b32_e32 v92, v2
	v_mov_b32_e32 v93, v2
	v_mov_b32_e32 v94, v2
	v_mov_b32_e32 v95, v2
	v_mov_b32_e32 v96, v2
	v_mov_b32_e32 v97, v2
	v_mov_b32_e32 v106, v2
	v_mov_b32_e32 v107, v2
	v_mov_b32_e32 v108, v2
	v_mov_b32_e32 v109, v2
	v_mov_b32_e32 v110, v2
	v_mov_b32_e32 v111, v2
	v_mov_b32_e32 v112, v2
	v_mov_b32_e32 v113, v2
	v_mov_b32_e32 v122, v2
	v_mov_b32_e32 v123, v2
	v_mov_b32_e32 v124, v2
	v_mov_b32_e32 v125, v2
	v_mov_b32_e32 v126, v2
	v_mov_b32_e32 v127, v2
	v_mov_b32_e32 v128, v2
	v_mov_b32_e32 v129, v2
	s_cmp_lg_u64 s[4:5], 0
	s_cbranch_scc1 .Lkb_gates
.LBB0_831:
	s_add_u32 s22, s20, 0xfffc0080
	s_addc_u32 s23, s21, -1
	s_add_i32 s52, 0, 0x10000
	s_cmp_eq_u32 s51, 12
	s_cselect_b32 s25, s15, s23
	s_cselect_b32 s24, s46, s22
	v_add_u32_e32 v144, s52, v1
	s_cselect_b32 s23, s13, s50
	s_cselect_b32 s22, s48, s49
	s_add_i32 s54, 0, 0x14000
	ds_read_b128 v[148:151], v144
	ds_read_b128 v[152:155], v144 offset:1024
	ds_read_b128 v[156:159], v144 offset:2048
	ds_read_b128 v[160:163], v144 offset:3072
	v_add_u32_e32 v144, s54, v1
	ds_read_b128 v[164:167], v144
	ds_read_b128 v[168:171], v144 offset:1024
	ds_read_b128 v[172:175], v144 offset:2048
	ds_read_b128 v[176:179], v144 offset:3072
	v_lshl_add_u64 v[144:145], s[20:21], 0, v[142:143]
	s_add_i32 m0, s36, 0xc000
	ds_read_b128 v[182:185], v147
	ds_read_b128 v[186:189], v147 offset:1024
	ds_read_b128 v[190:193], v147 offset:2048
	ds_read_b128 v[194:197], v147 offset:3072
	ds_read_b128 v[198:201], v147 offset:4096
	ds_read_b128 v[202:205], v147 offset:5120
	ds_read_b128 v[206:209], v147 offset:6144
	ds_read_b128 v[210:213], v147 offset:7168
	global_load_lds_dwordx4 v[144:145], off
	v_lshl_add_u64 v[144:145], s[20:21], 0, v[140:141]
	s_add_i32 m0, s36, 0xe000
	s_nop 0
	global_load_lds_dwordx4 v[144:145], off
	s_waitcnt vmcnt(8)
	s_waitcnt lgkmcnt(0)
	s_barrier
; #define PG8_STAGE(bufoff, gbase, voff) do { _Pragma("unroll") for (int _i = 0; _i < 2; ++_i) \
;         __builtin_amdgcn_global_load_lds((const unsigned*)((const char*)(gbase) + (voff)[_i]), (LAS unsigned*)(lds + (bufoff) + ldsw + _i * 8192), 16, 0, 0); } while (0)
; #define PG8_LDA(dst, b, h) do { _Pragma("unroll") for (int m = 0; m < 4; ++m) _Pragma("unroll") for (int k = 0; k < 2; ++k) dst[m][k] = *(const LAS bf16x8*)(lds + PG8_SA(b, h) + aoff + m * 2048 + k * 1024); } while (0)
; #define PG8_MMA(ai, bj, At, Bt) do { __builtin_amdgcn_s_setprio(1); _Pragma("unroll") for (int m = 0; m < 4; ++m) _Pragma("unroll") for (int n = 0; n < 2; ++n) _Pragma("unroll") for (int k = 0; k < 2; ++k) \
;         acc[ai][bj][m][n] = __builtin_amdgcn_mfma_f32_16x16x32_bf16(Bt[n][k], At[m][k], acc[ai][bj][m][n], 0, 0, 0); __builtin_amdgcn_s_setprio(0); } while (0)
; #define PG8_WAIT_V(n) asm volatile("s_waitcnt vmcnt(" #n ")" ::: "memory")
; #define PG8_WAIT_L(n) asm volatile("s_waitcnt lgkmcnt(" #n ")" ::: "memory")
; #define PG8_BAR __builtin_amdgcn_s_barrier()
; #define PG8_SCHED __builtin_amdgcn_sched_barrier(0)
; #define PG8_STAGE(bufoff, gbase, voff) do { _Pragma("unroll") for (int _i = 0; _i < 2; ++_i) \
;         __builtin_amdgcn_global_load_lds((const unsigned*)((const char*)(gbase) + (voff)[_i]), (LAS unsigned*)(lds + (bufoff) + ldsw + _i * 8192), 16, 0, 0); } while (0)
; #define PG8_LDA(dst, b, h) do { _Pragma("unroll") for (int m = 0; m < 4; ++m) _Pragma("unroll") for (int k = 0; k < 2; ++k) dst[m][k] = *(const LAS bf16x8*)(lds + PG8_SA(b, h) + aoff + m * 2048 + k * 1024); } while (0)
; #define PG8_WAIT_V(n) asm volatile("s_waitcnt vmcnt(" #n ")" ::: "memory")
; #define PG8_WAIT_L(n) asm volatile("s_waitcnt lgkmcnt(" #n ")" ::: "memory")
; #define PG8_BAR __builtin_amdgcn_s_barrier()
; template <class Epi, class Sched>
; __device__ __forceinline__ void gemm_phase(LAS unsigned char* lds, const Gemm g, const Sched& S, const Epi& E) {
;     ...
;             PG8_WAIT_V(8); PG8_WAIT_L(0); PG8_BAR; PG8_MMA(0, 0, At, B0); PG8_MMA(0, 1, At, B1); PG8_BAR; PG8_SCHED;
;             PG8_LDA(At, 0, 1); PG8_STAGE(PG8_SB(0, 0), b2, voffB); PG8_STAGE(PG8_SB(0, 1), b2 + hstepB, voffB); PG8_STAGE(PG8_SA(0, 0), a2, voffA);
;             PG8_WAIT_V(8); PG8_WAIT_L(0); PG8_BAR; PG8_MMA(1, 0, At, B0); PG8_MMA(1, 1, At, B1); PG8_BAR; PG8_SCHED;
	s_setprio 1
	s_waitcnt lgkmcnt(0)
	v_mfma_f32_16x16x32_bf16 v[126:129], v[148:151], v[182:185], v[126:129]
	v_mfma_f32_16x16x32_bf16 v[122:125], v[156:159], v[182:185], v[122:125]
	v_mfma_f32_16x16x32_bf16 v[110:113], v[148:151], v[190:193], v[110:113]
	v_mfma_f32_16x16x32_bf16 v[106:109], v[156:159], v[190:193], v[106:109]
	v_mfma_f32_16x16x32_bf16 v[94:97], v[148:151], v[198:201], v[94:97]
	v_mfma_f32_16x16x32_bf16 v[90:93], v[156:159], v[198:201], v[90:93]
	v_mfma_f32_16x16x32_bf16 v[78:81], v[148:151], v[206:209], v[78:81]
	v_mfma_f32_16x16x32_bf16 v[74:77], v[156:159], v[206:209], v[74:77]
	v_mfma_f32_16x16x32_bf16 v[126:129], v[152:155], v[186:189], v[126:129]
	v_mfma_f32_16x16x32_bf16 v[122:125], v[160:163], v[186:189], v[122:125]
	v_mfma_f32_16x16x32_bf16 v[110:113], v[152:155], v[194:197], v[110:113]
	v_mfma_f32_16x16x32_bf16 v[106:109], v[160:163], v[194:197], v[106:109]
	v_mfma_f32_16x16x32_bf16 v[94:97], v[152:155], v[202:205], v[94:97]
	v_mfma_f32_16x16x32_bf16 v[90:93], v[160:163], v[202:205], v[90:93]
	v_mfma_f32_16x16x32_bf16 v[78:81], v[152:155], v[210:213], v[78:81]
	v_mfma_f32_16x16x32_bf16 v[74:77], v[160:163], v[210:213], v[74:77]
	s_setprio 0
	s_setprio 1
	v_mfma_f32_16x16x32_bf16 v[118:121], v[164:167], v[182:185], v[118:121]
	v_mfma_f32_16x16x32_bf16 v[114:117], v[172:175], v[182:185], v[114:117]
	v_mfma_f32_16x16x32_bf16 v[102:105], v[164:167], v[190:193], v[102:105]
	v_mfma_f32_16x16x32_bf16 v[98:101], v[172:175], v[190:193], v[98:101]
	v_mfma_f32_16x16x32_bf16 v[86:89], v[164:167], v[198:201], v[86:89]
	v_mfma_f32_16x16x32_bf16 v[82:85], v[172:175], v[198:201], v[82:85]
	v_mfma_f32_16x16x32_bf16 v[70:73], v[164:167], v[206:209], v[70:73]
	v_mfma_f32_16x16x32_bf16 v[66:69], v[172:175], v[206:209], v[66:69]
	v_mfma_f32_16x16x32_bf16 v[118:121], v[168:171], v[186:189], v[118:121]
	v_mfma_f32_16x16x32_bf16 v[114:117], v[176:179], v[186:189], v[114:117]
	v_mfma_f32_16x16x32_bf16 v[102:105], v[168:171], v[194:197], v[102:105]
	v_mfma_f32_16x16x32_bf16 v[98:101], v[176:179], v[194:197], v[98:101]
	v_mfma_f32_16x16x32_bf16 v[86:89], v[168:171], v[202:205], v[86:89]
	v_mfma_f32_16x16x32_bf16 v[82:85], v[176:179], v[202:205], v[82:85]
	v_mfma_f32_16x16x32_bf16 v[70:73], v[168:171], v[210:213], v[70:73]
	v_mfma_f32_16x16x32_bf16 v[66:69], v[176:179], v[210:213], v[66:69]
	s_setprio 0
	s_barrier
	s_add_i32 s52, s52, s30
	v_lshl_add_u64 v[144:145], s[22:23], 0, v[134:135]
	s_mov_b32 m0, s52
	ds_read_b128 v[182:185], v147 offset:16384
	ds_read_b128 v[186:189], v147 offset:17408
	ds_read_b128 v[190:193], v147 offset:18432
	ds_read_b128 v[194:197], v147 offset:19456
	ds_read_b128 v[198:201], v147 offset:20480
	ds_read_b128 v[202:205], v147 offset:21504
	ds_read_b128 v[206:209], v147 offset:22528
	ds_read_b128 v[210:213], v147 offset:23552
	global_load_lds_dwordx4 v[144:145], off
	s_add_i32 m0, s52, 0x2000
	s_add_u32 s52, s22, 0x40000
	v_lshl_add_u64 v[214:215], s[22:23], 0, v[130:131]
	s_addc_u32 s53, s23, 0
	s_add_i32 s54, s54, s30
	global_load_lds_dwordx4 v[214:215], off
	v_lshl_add_u64 v[226:227], s[52:53], 0, v[134:135]
	s_mov_b32 m0, s54
	v_lshl_add_u64 v[228:229], s[24:25], 0, v[132:133]
	global_load_lds_dwordx4 v[226:227], off
	v_lshl_add_u64 v[226:227], s[52:53], 0, v[130:131]
	s_add_i32 m0, s54, 0x2000
	s_nop 0
	global_load_lds_dwordx4 v[226:227], off
	v_lshl_add_u64 v[226:227], s[24:25], 0, v[136:137]
	s_mov_b32 m0, s36
	s_nop 0
	global_load_lds_dwordx4 v[226:227], off
	s_mov_b32 m0, s37
	s_nop 0
	global_load_lds_dwordx4 v[228:229], off
	s_waitcnt vmcnt(8)
	s_waitcnt lgkmcnt(0)
	s_barrier
	s_setprio 1
	s_waitcnt lgkmcnt(0)
	v_mfma_f32_16x16x32_bf16 v[62:65], v[148:151], v[182:185], v[62:65]
	v_mfma_f32_16x16x32_bf16 v[58:61], v[156:159], v[182:185], v[58:61]
	v_mfma_f32_16x16x32_bf16 v[46:49], v[148:151], v[190:193], v[46:49]
	v_mfma_f32_16x16x32_bf16 v[42:45], v[156:159], v[190:193], v[42:45]
	v_mfma_f32_16x16x32_bf16 v[30:33], v[148:151], v[198:201], v[30:33]
	v_mfma_f32_16x16x32_bf16 v[26:29], v[156:159], v[198:201], v[26:29]
	v_mfma_f32_16x16x32_bf16 v[14:17], v[148:151], v[206:209], v[14:17]
	v_mfma_f32_16x16x32_bf16 v[10:13], v[156:159], v[206:209], v[10:13]
	v_mfma_f32_16x16x32_bf16 v[62:65], v[152:155], v[186:189], v[62:65]
	v_mfma_f32_16x16x32_bf16 v[58:61], v[160:163], v[186:189], v[58:61]
	v_mfma_f32_16x16x32_bf16 v[46:49], v[152:155], v[194:197], v[46:49]
	v_mfma_f32_16x16x32_bf16 v[42:45], v[160:163], v[194:197], v[42:45]
	v_mfma_f32_16x16x32_bf16 v[30:33], v[152:155], v[202:205], v[30:33]
	v_mfma_f32_16x16x32_bf16 v[26:29], v[160:163], v[202:205], v[26:29]
	v_mfma_f32_16x16x32_bf16 v[14:17], v[152:155], v[210:213], v[14:17]
	v_mfma_f32_16x16x32_bf16 v[10:13], v[160:163], v[210:213], v[10:13]
	s_setprio 0
	s_setprio 1
	v_mfma_f32_16x16x32_bf16 v[54:57], v[164:167], v[182:185], v[54:57]
	v_mfma_f32_16x16x32_bf16 v[50:53], v[172:175], v[182:185], v[50:53]
	v_mfma_f32_16x16x32_bf16 v[38:41], v[164:167], v[190:193], v[38:41]
	v_mfma_f32_16x16x32_bf16 v[34:37], v[172:175], v[190:193], v[34:37]
	v_mfma_f32_16x16x32_bf16 v[22:25], v[164:167], v[198:201], v[22:25]
	v_mfma_f32_16x16x32_bf16 v[18:21], v[172:175], v[198:201], v[18:21]
	v_mfma_f32_16x16x32_bf16 v[6:9], v[164:167], v[206:209], v[6:9]
	v_mfma_f32_16x16x32_bf16 v[2:5], v[172:175], v[206:209], v[2:5]
	v_mfma_f32_16x16x32_bf16 v[54:57], v[168:171], v[186:189], v[54:57]
	v_mfma_f32_16x16x32_bf16 v[50:53], v[176:179], v[186:189], v[50:53]
	v_mfma_f32_16x16x32_bf16 v[38:41], v[168:171], v[194:197], v[38:41]
	v_mfma_f32_16x16x32_bf16 v[34:37], v[176:179], v[194:197], v[34:37]
	v_mfma_f32_16x16x32_bf16 v[22:25], v[168:171], v[202:205], v[22:25]
	v_mfma_f32_16x16x32_bf16 v[18:21], v[176:179], v[202:205], v[18:21]
	v_mfma_f32_16x16x32_bf16 v[6:9], v[168:171], v[210:213], v[6:9]
	v_mfma_f32_16x16x32_bf16 v[2:5], v[176:179], v[210:213], v[2:5]
	s_setprio 0
	s_barrier
; #define PG8_STAGE(bufoff, gbase, voff) do { _Pragma("unroll") for (int _i = 0; _i < 2; ++_i) \
;         __builtin_amdgcn_global_load_lds((const unsigned*)((const char*)(gbase) + (voff)[_i]), (LAS unsigned*)(lds + (bufoff) + ldsw + _i * 8192), 16, 0, 0); } while (0)
; #define PG8_LDA(dst, b, h) do { _Pragma("unroll") for (int m = 0; m < 4; ++m) _Pragma("unroll") for (int k = 0; k < 2; ++k) dst[m][k] = *(const LAS bf16x8*)(lds + PG8_SA(b, h) + aoff + m * 2048 + k * 1024); } while (0)
; #define PG8_LDB(dst, b, h) do { _Pragma("unroll") for (int n = 0; n < 2; ++n) _Pragma("unroll") for (int k = 0; k < 2; ++k) dst[n][k] = *(const LAS bf16x8*)(lds + PG8_SB(b, h) + boff + n * 2048 + k * 1024); } while (0)
; #define PG8_MMA(ai, bj, At, Bt) do { __builtin_amdgcn_s_setprio(1); _Pragma("unroll") for (int m = 0; m < 4; ++m) _Pragma("unroll") for (int n = 0; n < 2; ++n) _Pragma("unroll") for (int k = 0; k < 2; ++k) \
;         acc[ai][bj][m][n] = __builtin_amdgcn_mfma_f32_16x16x32_bf16(Bt[n][k], At[m][k], acc[ai][bj][m][n], 0, 0, 0); __builtin_amdgcn_s_setprio(0); } while (0)
; #define PG8_WAIT_V(n) asm volatile("s_waitcnt vmcnt(" #n ")" ::: "memory")
; #define PG8_WAIT_L(n) asm volatile("s_waitcnt lgkmcnt(" #n ")" ::: "memory")
; #define PG8_BAR __builtin_amdgcn_s_barrier()
; #define PG8_SCHED __builtin_amdgcn_sched_barrier(0)
; #define PG8_STAGE(bufoff, gbase, voff) do { _Pragma("unroll") for (int _i = 0; _i < 2; ++_i) \
;         __builtin_amdgcn_global_load_lds((const unsigned*)((const char*)(gbase) + (voff)[_i]), (LAS unsigned*)(lds + (bufoff) + ldsw + _i * 8192), 16, 0, 0); } while (0)
; #define PG8_LDA(dst, b, h) do { _Pragma("unroll") for (int m = 0; m < 4; ++m) _Pragma("unroll") for (int k = 0; k < 2; ++k) dst[m][k] = *(const LAS bf16x8*)(lds + PG8_SA(b, h) + aoff + m * 2048 + k * 1024); } while (0)
; template <class Epi, class Sched>
; __device__ __forceinline__ void gemm_phase(LAS unsigned char* lds, const Gemm g, const Sched& S, const Epi& E) {
;     ...
;             PG8_LDB(B0, 1, 0); PG8_LDB(B1, 1, 1); PG8_SCHED; PG8_LDA(At, 1, 0); PG8_STAGE(PG8_SA(0, 1), a2 + hstepA, voffA);
;             PG8_WAIT_V(8); PG8_WAIT_L(0); PG8_BAR; PG8_MMA(0, 0, At, B0); PG8_MMA(0, 1, At, B1); PG8_BAR; PG8_SCHED;
;             PG8_LDA(At, 1, 1); PG8_STAGE(PG8_SB(1, 0), b3, voffB); PG8_STAGE(PG8_SB(1, 1), b3 + hstepB, voffB); PG8_STAGE(PG8_SA(1, 0), a3, voffA);
	s_add_i32 s52, 0, 0x18000
	s_add_i32 s53, 0, 0x1c000
	v_add_u32_e32 v160, s52, v1
	v_add_u32_e32 v176, s53, v1
	ds_read_b128 v[148:151], v160
	ds_read_b128 v[152:155], v160 offset:1024
	ds_read_b128 v[156:159], v160 offset:2048
	ds_read_b128 v[160:163], v160 offset:3072
	ds_read_b128 v[164:167], v176
	ds_read_b128 v[168:171], v176 offset:1024
	ds_read_b128 v[172:175], v176 offset:2048
	ds_read_b128 v[176:179], v176 offset:3072
	s_add_u32 s24, s24, 0x40000
	s_addc_u32 s25, s25, 0
	s_mov_b32 m0, s38
	v_lshl_add_u64 v[232:233], s[24:25], 0, v[136:137]
	ds_read_b128 v[182:185], v147 offset:32768
	ds_read_b128 v[186:189], v147 offset:33792
	ds_read_b128 v[190:193], v147 offset:34816
	ds_read_b128 v[194:197], v147 offset:35840
	ds_read_b128 v[198:201], v147 offset:36864
	ds_read_b128 v[202:205], v147 offset:37888
	ds_read_b128 v[206:209], v147 offset:38912
	ds_read_b128 v[210:213], v147 offset:39936
	global_load_lds_dwordx4 v[232:233], off
	v_lshl_add_u64 v[232:233], s[24:25], 0, v[132:133]
	s_mov_b32 m0, s39
	s_nop 0
	global_load_lds_dwordx4 v[232:233], off
	s_waitcnt vmcnt(8)
	s_waitcnt lgkmcnt(0)
	s_barrier
	s_setprio 1
	s_waitcnt lgkmcnt(0)
	v_mfma_f32_16x16x32_bf16 v[126:129], v[148:151], v[182:185], v[126:129]
	v_mfma_f32_16x16x32_bf16 v[122:125], v[156:159], v[182:185], v[122:125]
	v_mfma_f32_16x16x32_bf16 v[110:113], v[148:151], v[190:193], v[110:113]
	v_mfma_f32_16x16x32_bf16 v[106:109], v[156:159], v[190:193], v[106:109]
	v_mfma_f32_16x16x32_bf16 v[94:97], v[148:151], v[198:201], v[94:97]
	v_mfma_f32_16x16x32_bf16 v[90:93], v[156:159], v[198:201], v[90:93]
	v_mfma_f32_16x16x32_bf16 v[78:81], v[148:151], v[206:209], v[78:81]
	v_mfma_f32_16x16x32_bf16 v[74:77], v[156:159], v[206:209], v[74:77]
	v_mfma_f32_16x16x32_bf16 v[126:129], v[152:155], v[186:189], v[126:129]
	v_mfma_f32_16x16x32_bf16 v[122:125], v[160:163], v[186:189], v[122:125]
	v_mfma_f32_16x16x32_bf16 v[110:113], v[152:155], v[194:197], v[110:113]
	v_mfma_f32_16x16x32_bf16 v[106:109], v[160:163], v[194:197], v[106:109]
	v_mfma_f32_16x16x32_bf16 v[94:97], v[152:155], v[202:205], v[94:97]
	v_mfma_f32_16x16x32_bf16 v[90:93], v[160:163], v[202:205], v[90:93]
	v_mfma_f32_16x16x32_bf16 v[78:81], v[152:155], v[210:213], v[78:81]
	v_mfma_f32_16x16x32_bf16 v[74:77], v[160:163], v[210:213], v[74:77]
	s_setprio 0
	s_setprio 1
	v_mfma_f32_16x16x32_bf16 v[118:121], v[164:167], v[182:185], v[118:121]
	v_mfma_f32_16x16x32_bf16 v[114:117], v[172:175], v[182:185], v[114:117]
	v_mfma_f32_16x16x32_bf16 v[102:105], v[164:167], v[190:193], v[102:105]
	v_mfma_f32_16x16x32_bf16 v[98:101], v[172:175], v[190:193], v[98:101]
	v_mfma_f32_16x16x32_bf16 v[86:89], v[164:167], v[198:201], v[86:89]
	v_mfma_f32_16x16x32_bf16 v[82:85], v[172:175], v[198:201], v[82:85]
	v_mfma_f32_16x16x32_bf16 v[70:73], v[164:167], v[206:209], v[70:73]
	v_mfma_f32_16x16x32_bf16 v[66:69], v[172:175], v[206:209], v[66:69]
	v_mfma_f32_16x16x32_bf16 v[118:121], v[168:171], v[186:189], v[118:121]
	v_mfma_f32_16x16x32_bf16 v[114:117], v[176:179], v[186:189], v[114:117]
	v_mfma_f32_16x16x32_bf16 v[102:105], v[168:171], v[194:197], v[102:105]
	v_mfma_f32_16x16x32_bf16 v[98:101], v[176:179], v[194:197], v[98:101]
	v_mfma_f32_16x16x32_bf16 v[86:89], v[168:171], v[202:205], v[86:89]
	v_mfma_f32_16x16x32_bf16 v[82:85], v[176:179], v[202:205], v[82:85]
	v_mfma_f32_16x16x32_bf16 v[70:73], v[168:171], v[210:213], v[70:73]
	v_mfma_f32_16x16x32_bf16 v[66:69], v[176:179], v[210:213], v[66:69]
	s_setprio 0
	s_barrier
	s_add_i32 s24, s52, s30
	v_lshl_add_u64 v[144:145], v[144:145], 0, s[86:87]
	s_mov_b32 m0, s24
	ds_read_b128 v[182:185], v147 offset:49152
	ds_read_b128 v[186:189], v147 offset:50176
	ds_read_b128 v[190:193], v147 offset:51200
	ds_read_b128 v[194:197], v147 offset:52224
	ds_read_b128 v[198:201], v147 offset:53248
	ds_read_b128 v[202:205], v147 offset:54272
	ds_read_b128 v[206:209], v147 offset:55296
	ds_read_b128 v[210:213], v147 offset:56320
	global_load_lds_dwordx4 v[144:145], off
	s_add_i32 m0, s24, 0x2000
	s_add_u32 s22, s22, 0x40080
	v_lshl_add_u64 v[144:145], v[214:215], 0, s[86:87]
	s_addc_u32 s23, s23, 0
	s_add_i32 s24, s53, s30
	global_load_lds_dwordx4 v[144:145], off
	v_lshl_add_u64 v[144:145], s[22:23], 0, v[134:135]
	s_mov_b32 m0, s24
	s_nop 0
	global_load_lds_dwordx4 v[144:145], off
	v_lshl_add_u64 v[144:145], s[22:23], 0, v[130:131]
	s_add_i32 m0, s24, 0x2000
	s_nop 0
	global_load_lds_dwordx4 v[144:145], off
	v_lshl_add_u64 v[144:145], v[226:227], 0, s[86:87]
	s_mov_b32 m0, s42
	s_nop 0
	global_load_lds_dwordx4 v[144:145], off
	v_lshl_add_u64 v[144:145], v[228:229], 0, s[86:87]
	s_mov_b32 m0, s43
	s_nop 0
	global_load_lds_dwordx4 v[144:145], off
	s_waitcnt vmcnt(8)
	s_waitcnt lgkmcnt(0)
	s_barrier
; #define PG8_STAGE(bufoff, gbase, voff) do { _Pragma("unroll") for (int _i = 0; _i < 2; ++_i) \
;         __builtin_amdgcn_global_load_lds((const unsigned*)((const char*)(gbase) + (voff)[_i]), (LAS unsigned*)(lds + (bufoff) + ldsw + _i * 8192), 16, 0, 0); } while (0)
; #define PG8_LDA(dst, b, h) do { _Pragma("unroll") for (int m = 0; m < 4; ++m) _Pragma("unroll") for (int k = 0; k < 2; ++k) dst[m][k] = *(const LAS bf16x8*)(lds + PG8_SA(b, h) + aoff + m * 2048 + k * 1024); } while (0)
; #define PG8_LDB(dst, b, h) do { _Pragma("unroll") for (int n = 0; n < 2; ++n) _Pragma("unroll") for (int k = 0; k < 2; ++k) dst[n][k] = *(const LAS bf16x8*)(lds + PG8_SB(b, h) + boff + n * 2048 + k * 1024); } while (0)
; #define PG8_MMA(ai, bj, At, Bt) do { __builtin_amdgcn_s_setprio(1); _Pragma("unroll") for (int m = 0; m < 4; ++m) _Pragma("unroll") for (int n = 0; n < 2; ++n) _Pragma("unroll") for (int k = 0; k < 2; ++k) \
;         acc[ai][bj][m][n] = __builtin_amdgcn_mfma_f32_16x16x32_bf16(Bt[n][k], At[m][k], acc[ai][bj][m][n], 0, 0, 0); __builtin_amdgcn_s_setprio(0); } while (0)
; #define PG8_WAIT_V(n) asm volatile("s_waitcnt vmcnt(" #n ")" ::: "memory")
; #define PG8_WAIT_L(n) asm volatile("s_waitcnt lgkmcnt(" #n ")" ::: "memory")
; #define PG8_BAR __builtin_amdgcn_s_barrier()
; #define PG8_SCHED __builtin_amdgcn_sched_barrier(0)
; #define PG8_STAGE(bufoff, gbase, voff) do { _Pragma("unroll") for (int _i = 0; _i < 2; ++_i) \
;         __builtin_amdgcn_global_load_lds((const unsigned*)((const char*)(gbase) + (voff)[_i]), (LAS unsigned*)(lds + (bufoff) + ldsw + _i * 8192), 16, 0, 0); } while (0)
; #define PG8_LDA(dst, b, h) do { _Pragma("unroll") for (int m = 0; m < 4; ++m) _Pragma("unroll") for (int k = 0; k < 2; ++k) dst[m][k] = *(const LAS bf16x8*)(lds + PG8_SA(b, h) + aoff + m * 2048 + k * 1024); } while (0)
; #define PG8_BAR __builtin_amdgcn_s_barrier()
; template <class Epi, class Sched>
; __device__ __forceinline__ void gemm_phase(LAS unsigned char* lds, const Gemm g, const Sched& S, const Epi& E) {
;     ...
;             PG8_LDB(B0, 0, 0); PG8_LDB(B1, 0, 1); PG8_SCHED; PG8_LDA(At, 0, 0); PG8_STAGE(PG8_SA(1, 1), a1 + hstepA, voffA);
;             PG8_WAIT_V(8); PG8_WAIT_L(0); PG8_BAR; PG8_MMA(0, 0, At, B0); PG8_MMA(0, 1, At, B1); PG8_BAR; PG8_SCHED;
;     ...
;             PG8_WAIT_V(8); PG8_WAIT_L(0); PG8_BAR; PG8_MMA(1, 0, At, B0); PG8_MMA(1, 1, At, B1); PG8_BAR; PG8_SCHED;
	s_setprio 1
	s_waitcnt lgkmcnt(0)
	v_mfma_f32_16x16x32_bf16 v[62:65], v[148:151], v[182:185], v[62:65]
	v_mfma_f32_16x16x32_bf16 v[58:61], v[156:159], v[182:185], v[58:61]
	v_mfma_f32_16x16x32_bf16 v[46:49], v[148:151], v[190:193], v[46:49]
	v_mfma_f32_16x16x32_bf16 v[42:45], v[156:159], v[190:193], v[42:45]
	v_mfma_f32_16x16x32_bf16 v[30:33], v[148:151], v[198:201], v[30:33]
	v_mfma_f32_16x16x32_bf16 v[26:29], v[156:159], v[198:201], v[26:29]
	v_mfma_f32_16x16x32_bf16 v[14:17], v[148:151], v[206:209], v[14:17]
	v_mfma_f32_16x16x32_bf16 v[10:13], v[156:159], v[206:209], v[10:13]
	v_mfma_f32_16x16x32_bf16 v[62:65], v[152:155], v[186:189], v[62:65]
	v_mfma_f32_16x16x32_bf16 v[58:61], v[160:163], v[186:189], v[58:61]
	v_mfma_f32_16x16x32_bf16 v[46:49], v[152:155], v[194:197], v[46:49]
	v_mfma_f32_16x16x32_bf16 v[42:45], v[160:163], v[194:197], v[42:45]
	v_mfma_f32_16x16x32_bf16 v[30:33], v[152:155], v[202:205], v[30:33]
	v_mfma_f32_16x16x32_bf16 v[26:29], v[160:163], v[202:205], v[26:29]
	v_mfma_f32_16x16x32_bf16 v[14:17], v[152:155], v[210:213], v[14:17]
	v_mfma_f32_16x16x32_bf16 v[10:13], v[160:163], v[210:213], v[10:13]
	s_setprio 0
	s_setprio 1
	v_mfma_f32_16x16x32_bf16 v[54:57], v[164:167], v[182:185], v[54:57]
	v_mfma_f32_16x16x32_bf16 v[50:53], v[172:175], v[182:185], v[50:53]
	v_mfma_f32_16x16x32_bf16 v[38:41], v[164:167], v[190:193], v[38:41]
	v_mfma_f32_16x16x32_bf16 v[34:37], v[172:175], v[190:193], v[34:37]
	v_mfma_f32_16x16x32_bf16 v[22:25], v[164:167], v[198:201], v[22:25]
	v_mfma_f32_16x16x32_bf16 v[18:21], v[172:175], v[198:201], v[18:21]
	v_mfma_f32_16x16x32_bf16 v[6:9], v[164:167], v[206:209], v[6:9]
	v_mfma_f32_16x16x32_bf16 v[2:5], v[172:175], v[206:209], v[2:5]
	v_mfma_f32_16x16x32_bf16 v[54:57], v[168:171], v[186:189], v[54:57]
	v_mfma_f32_16x16x32_bf16 v[50:53], v[176:179], v[186:189], v[50:53]
	v_mfma_f32_16x16x32_bf16 v[38:41], v[168:171], v[194:197], v[38:41]
	v_mfma_f32_16x16x32_bf16 v[34:37], v[176:179], v[194:197], v[34:37]
	v_mfma_f32_16x16x32_bf16 v[22:25], v[168:171], v[202:205], v[22:25]
	v_mfma_f32_16x16x32_bf16 v[18:21], v[176:179], v[202:205], v[18:21]
	v_mfma_f32_16x16x32_bf16 v[6:9], v[168:171], v[210:213], v[6:9]
	v_mfma_f32_16x16x32_bf16 v[2:5], v[176:179], v[210:213], v[2:5]
	s_setprio 0
	s_barrier
	s_add_i32 s51, s51, 2
	s_add_u32 s49, s49, 0x100
	s_addc_u32 s50, s50, 0
	s_add_u32 s20, s20, 0x100
	s_addc_u32 s21, s21, 0
	s_cmp_gt_u32 s51, 13
	s_cbranch_scc0 .LBB0_831
	s_branch .Lkend_gates
.Lkb_gates:
	s_add_u32 s22, s20, 0xfffc0080
	s_addc_u32 s23, s21, -1
	s_add_i32 s52, 0, 0x10000
	s_cmp_eq_u32 s51, 12
	s_cselect_b32 s25, s15, s23
	s_cselect_b32 s24, s46, s22
	v_add_u32_e32 v144, s52, v1
	s_cselect_b32 s23, s13, s50
	s_cselect_b32 s22, s48, s49
	s_add_i32 s54, 0, 0x14000
	ds_read_b128 v[148:151], v144
	ds_read_b128 v[152:155], v144 offset:1024
	ds_read_b128 v[156:159], v144 offset:2048
	ds_read_b128 v[160:163], v144 offset:3072
	v_add_u32_e32 v144, s54, v1
	ds_read_b128 v[164:167], v144
	ds_read_b128 v[168:171], v144 offset:1024
	ds_read_b128 v[172:175], v144 offset:2048
	ds_read_b128 v[176:179], v144 offset:3072
	v_lshl_add_u64 v[144:145], s[20:21], 0, v[142:143]
	s_add_i32 m0, s36, 0xc000
	ds_read_b128 v[182:185], v147
	ds_read_b128 v[186:189], v147 offset:1024
	ds_read_b128 v[190:193], v147 offset:2048
	ds_read_b128 v[194:197], v147 offset:3072
	ds_read_b128 v[198:201], v147 offset:4096
	ds_read_b128 v[202:205], v147 offset:5120
	ds_read_b128 v[206:209], v147 offset:6144
	ds_read_b128 v[210:213], v147 offset:7168
	global_load_lds_dwordx4 v[144:145], off
	v_lshl_add_u64 v[144:145], s[20:21], 0, v[140:141]
	s_add_i32 m0, s36, 0xe000
	s_nop 0
	global_load_lds_dwordx4 v[144:145], off
	s_waitcnt vmcnt(8)
	s_waitcnt lgkmcnt(0)
	s_barrier
	s_setprio 2
	s_waitcnt lgkmcnt(0)
	v_mfma_f32_16x16x32_bf16 v[126:129], v[148:151], v[182:185], v[126:129]
	v_mfma_f32_16x16x32_bf16 v[122:125], v[156:159], v[182:185], v[122:125]
	v_mfma_f32_16x16x32_bf16 v[110:113], v[148:151], v[190:193], v[110:113]
	v_mfma_f32_16x16x32_bf16 v[106:109], v[156:159], v[190:193], v[106:109]
	v_mfma_f32_16x16x32_bf16 v[94:97], v[148:151], v[198:201], v[94:97]
	v_mfma_f32_16x16x32_bf16 v[90:93], v[156:159], v[198:201], v[90:93]
	v_mfma_f32_16x16x32_bf16 v[78:81], v[148:151], v[206:209], v[78:81]
	v_mfma_f32_16x16x32_bf16 v[74:77], v[156:159], v[206:209], v[74:77]
	v_mfma_f32_16x16x32_bf16 v[126:129], v[152:155], v[186:189], v[126:129]
	v_mfma_f32_16x16x32_bf16 v[122:125], v[160:163], v[186:189], v[122:125]
	v_mfma_f32_16x16x32_bf16 v[110:113], v[152:155], v[194:197], v[110:113]
	v_mfma_f32_16x16x32_bf16 v[106:109], v[160:163], v[194:197], v[106:109]
	v_mfma_f32_16x16x32_bf16 v[94:97], v[152:155], v[202:205], v[94:97]
	v_mfma_f32_16x16x32_bf16 v[90:93], v[160:163], v[202:205], v[90:93]
	v_mfma_f32_16x16x32_bf16 v[78:81], v[152:155], v[210:213], v[78:81]
	v_mfma_f32_16x16x32_bf16 v[74:77], v[160:163], v[210:213], v[74:77]
	s_setprio 1
	s_setprio 2
	v_mfma_f32_16x16x32_bf16 v[118:121], v[164:167], v[182:185], v[118:121]
	v_mfma_f32_16x16x32_bf16 v[114:117], v[172:175], v[182:185], v[114:117]
	v_mfma_f32_16x16x32_bf16 v[102:105], v[164:167], v[190:193], v[102:105]
	v_mfma_f32_16x16x32_bf16 v[98:101], v[172:175], v[190:193], v[98:101]
	v_mfma_f32_16x16x32_bf16 v[86:89], v[164:167], v[198:201], v[86:89]
	v_mfma_f32_16x16x32_bf16 v[82:85], v[172:175], v[198:201], v[82:85]
	v_mfma_f32_16x16x32_bf16 v[70:73], v[164:167], v[206:209], v[70:73]
	v_mfma_f32_16x16x32_bf16 v[66:69], v[172:175], v[206:209], v[66:69]
	v_mfma_f32_16x16x32_bf16 v[118:121], v[168:171], v[186:189], v[118:121]
	v_mfma_f32_16x16x32_bf16 v[114:117], v[176:179], v[186:189], v[114:117]
	v_mfma_f32_16x16x32_bf16 v[102:105], v[168:171], v[194:197], v[102:105]
	v_mfma_f32_16x16x32_bf16 v[98:101], v[176:179], v[194:197], v[98:101]
	v_mfma_f32_16x16x32_bf16 v[86:89], v[168:171], v[202:205], v[86:89]
	v_mfma_f32_16x16x32_bf16 v[82:85], v[176:179], v[202:205], v[82:85]
	v_mfma_f32_16x16x32_bf16 v[70:73], v[168:171], v[210:213], v[70:73]
	v_mfma_f32_16x16x32_bf16 v[66:69], v[176:179], v[210:213], v[66:69]
	s_setprio 1
	s_barrier
; #define PG8_STAGE(bufoff, gbase, voff) do { _Pragma("unroll") for (int _i = 0; _i < 2; ++_i) \
;         __builtin_amdgcn_global_load_lds((const unsigned*)((const char*)(gbase) + (voff)[_i]), (LAS unsigned*)(lds + (bufoff) + ldsw + _i * 8192), 16, 0, 0); } while (0)
; #define PG8_LDA(dst, b, h) do { _Pragma("unroll") for (int m = 0; m < 4; ++m) _Pragma("unroll") for (int k = 0; k < 2; ++k) dst[m][k] = *(const LAS bf16x8*)(lds + PG8_SA(b, h) + aoff + m * 2048 + k * 1024); } while (0)
; #define PG8_LDB(dst, b, h) do { _Pragma("unroll") for (int n = 0; n < 2; ++n) _Pragma("unroll") for (int k = 0; k < 2; ++k) dst[n][k] = *(const LAS bf16x8*)(lds + PG8_SB(b, h) + boff + n * 2048 + k * 1024); } while (0)
; #define PG8_MMA(ai, bj, At, Bt) do { __builtin_amdgcn_s_setprio(1); _Pragma("unroll") for (int m = 0; m < 4; ++m) _Pragma("unroll") for (int n = 0; n < 2; ++n) _Pragma("unroll") for (int k = 0; k < 2; ++k) \
;         acc[ai][bj][m][n] = __builtin_amdgcn_mfma_f32_16x16x32_bf16(Bt[n][k], At[m][k], acc[ai][bj][m][n], 0, 0, 0); __builtin_amdgcn_s_setprio(0); } while (0)
; #define PG8_WAIT_V(n) asm volatile("s_waitcnt vmcnt(" #n ")" ::: "memory")
; #define PG8_WAIT_L(n) asm volatile("s_waitcnt lgkmcnt(" #n ")" ::: "memory")
; #define PG8_BAR __builtin_amdgcn_s_barrier()
; #define PG8_SCHED __builtin_amdgcn_sched_barrier(0)
; #define PG8_LDA(dst, b, h) do { _Pragma("unroll") for (int m = 0; m < 4; ++m) _Pragma("unroll") for (int k = 0; k < 2; ++k) dst[m][k] = *(const LAS bf16x8*)(lds + PG8_SA(b, h) + aoff + m * 2048 + k * 1024); } while (0)
; template <class Epi, class Sched>
; __device__ __forceinline__ void gemm_phase(LAS unsigned char* lds, const Gemm g, const Sched& S, const Epi& E) {
;     ...
;             PG8_LDA(At, 0, 1); PG8_STAGE(PG8_SB(0, 0), b2, voffB); PG8_STAGE(PG8_SB(0, 1), b2 + hstepB, voffB); PG8_STAGE(PG8_SA(0, 0), a2, voffA);
;             PG8_WAIT_V(8); PG8_WAIT_L(0); PG8_BAR; PG8_MMA(1, 0, At, B0); PG8_MMA(1, 1, At, B1); PG8_BAR; PG8_SCHED;
;             PG8_LDB(B0, 1, 0); PG8_LDB(B1, 1, 1); PG8_SCHED; PG8_LDA(At, 1, 0); PG8_STAGE(PG8_SA(0, 1), a2 + hstepA, voffA);
;             PG8_WAIT_V(8); PG8_WAIT_L(0); PG8_BAR; PG8_MMA(0, 0, At, B0); PG8_MMA(0, 1, At, B1); PG8_BAR; PG8_SCHED;
;             PG8_LDA(At, 1, 1); PG8_STAGE(PG8_SB(1, 0), b3, voffB); PG8_STAGE(PG8_SB(1, 1), b3 + hstepB, voffB); PG8_STAGE(PG8_SA(1, 0), a3, voffA);
	s_add_i32 s52, s52, s30
	v_lshl_add_u64 v[144:145], s[22:23], 0, v[134:135]
	s_mov_b32 m0, s52
	ds_read_b128 v[182:185], v147 offset:16384
	ds_read_b128 v[186:189], v147 offset:17408
	ds_read_b128 v[190:193], v147 offset:18432
	ds_read_b128 v[194:197], v147 offset:19456
	ds_read_b128 v[198:201], v147 offset:20480
	ds_read_b128 v[202:205], v147 offset:21504
	ds_read_b128 v[206:209], v147 offset:22528
	ds_read_b128 v[210:213], v147 offset:23552
	global_load_lds_dwordx4 v[144:145], off
	s_add_i32 m0, s52, 0x2000
	s_add_u32 s52, s22, 0x40000
	v_lshl_add_u64 v[214:215], s[22:23], 0, v[130:131]
	s_addc_u32 s53, s23, 0
	s_add_i32 s54, s54, s30
	global_load_lds_dwordx4 v[214:215], off
	v_lshl_add_u64 v[226:227], s[52:53], 0, v[134:135]
	s_mov_b32 m0, s54
	v_lshl_add_u64 v[228:229], s[24:25], 0, v[132:133]
	global_load_lds_dwordx4 v[226:227], off
	v_lshl_add_u64 v[226:227], s[52:53], 0, v[130:131]
	s_add_i32 m0, s54, 0x2000
	s_nop 0
	global_load_lds_dwordx4 v[226:227], off
	v_lshl_add_u64 v[226:227], s[24:25], 0, v[136:137]
	s_mov_b32 m0, s36
	s_nop 0
	global_load_lds_dwordx4 v[226:227], off
	s_mov_b32 m0, s37
	s_nop 0
	global_load_lds_dwordx4 v[228:229], off
	s_waitcnt vmcnt(8)
	s_waitcnt lgkmcnt(0)
	s_barrier
	s_setprio 2
	s_waitcnt lgkmcnt(0)
	v_mfma_f32_16x16x32_bf16 v[62:65], v[148:151], v[182:185], v[62:65]
	v_mfma_f32_16x16x32_bf16 v[58:61], v[156:159], v[182:185], v[58:61]
	v_mfma_f32_16x16x32_bf16 v[46:49], v[148:151], v[190:193], v[46:49]
	v_mfma_f32_16x16x32_bf16 v[42:45], v[156:159], v[190:193], v[42:45]
	v_mfma_f32_16x16x32_bf16 v[30:33], v[148:151], v[198:201], v[30:33]
	v_mfma_f32_16x16x32_bf16 v[26:29], v[156:159], v[198:201], v[26:29]
	v_mfma_f32_16x16x32_bf16 v[14:17], v[148:151], v[206:209], v[14:17]
	v_mfma_f32_16x16x32_bf16 v[10:13], v[156:159], v[206:209], v[10:13]
	v_mfma_f32_16x16x32_bf16 v[62:65], v[152:155], v[186:189], v[62:65]
	v_mfma_f32_16x16x32_bf16 v[58:61], v[160:163], v[186:189], v[58:61]
	v_mfma_f32_16x16x32_bf16 v[46:49], v[152:155], v[194:197], v[46:49]
	v_mfma_f32_16x16x32_bf16 v[42:45], v[160:163], v[194:197], v[42:45]
	v_mfma_f32_16x16x32_bf16 v[30:33], v[152:155], v[202:205], v[30:33]
	v_mfma_f32_16x16x32_bf16 v[26:29], v[160:163], v[202:205], v[26:29]
	v_mfma_f32_16x16x32_bf16 v[14:17], v[152:155], v[210:213], v[14:17]
	v_mfma_f32_16x16x32_bf16 v[10:13], v[160:163], v[210:213], v[10:13]
	s_setprio 1
	s_setprio 2
	v_mfma_f32_16x16x32_bf16 v[54:57], v[164:167], v[182:185], v[54:57]
	v_mfma_f32_16x16x32_bf16 v[50:53], v[172:175], v[182:185], v[50:53]
	v_mfma_f32_16x16x32_bf16 v[38:41], v[164:167], v[190:193], v[38:41]
	v_mfma_f32_16x16x32_bf16 v[34:37], v[172:175], v[190:193], v[34:37]
	v_mfma_f32_16x16x32_bf16 v[22:25], v[164:167], v[198:201], v[22:25]
	v_mfma_f32_16x16x32_bf16 v[18:21], v[172:175], v[198:201], v[18:21]
	v_mfma_f32_16x16x32_bf16 v[6:9], v[164:167], v[206:209], v[6:9]
	v_mfma_f32_16x16x32_bf16 v[2:5], v[172:175], v[206:209], v[2:5]
	v_mfma_f32_16x16x32_bf16 v[54:57], v[168:171], v[186:189], v[54:57]
	v_mfma_f32_16x16x32_bf16 v[50:53], v[176:179], v[186:189], v[50:53]
	v_mfma_f32_16x16x32_bf16 v[38:41], v[168:171], v[194:197], v[38:41]
	v_mfma_f32_16x16x32_bf16 v[34:37], v[176:179], v[194:197], v[34:37]
	v_mfma_f32_16x16x32_bf16 v[22:25], v[168:171], v[202:205], v[22:25]
	v_mfma_f32_16x16x32_bf16 v[18:21], v[176:179], v[202:205], v[18:21]
	v_mfma_f32_16x16x32_bf16 v[6:9], v[168:171], v[210:213], v[6:9]
	v_mfma_f32_16x16x32_bf16 v[2:5], v[176:179], v[210:213], v[2:5]
	s_setprio 1
	s_barrier
	s_add_i32 s52, 0, 0x18000
	s_add_i32 s53, 0, 0x1c000
	v_add_u32_e32 v160, s52, v1
	v_add_u32_e32 v176, s53, v1
	ds_read_b128 v[148:151], v160
	ds_read_b128 v[152:155], v160 offset:1024
	ds_read_b128 v[156:159], v160 offset:2048
	ds_read_b128 v[160:163], v160 offset:3072
	ds_read_b128 v[164:167], v176
	ds_read_b128 v[168:171], v176 offset:1024
	ds_read_b128 v[172:175], v176 offset:2048
	ds_read_b128 v[176:179], v176 offset:3072
	s_add_u32 s24, s24, 0x40000
	s_addc_u32 s25, s25, 0
	s_mov_b32 m0, s38
	v_lshl_add_u64 v[232:233], s[24:25], 0, v[136:137]
	ds_read_b128 v[182:185], v147 offset:32768
	ds_read_b128 v[186:189], v147 offset:33792
	ds_read_b128 v[190:193], v147 offset:34816
	ds_read_b128 v[194:197], v147 offset:35840
	ds_read_b128 v[198:201], v147 offset:36864
	ds_read_b128 v[202:205], v147 offset:37888
	ds_read_b128 v[206:209], v147 offset:38912
	ds_read_b128 v[210:213], v147 offset:39936
	global_load_lds_dwordx4 v[232:233], off
	v_lshl_add_u64 v[232:233], s[24:25], 0, v[132:133]
	s_mov_b32 m0, s39
	s_nop 0
	global_load_lds_dwordx4 v[232:233], off
	s_waitcnt vmcnt(8)
	s_waitcnt lgkmcnt(0)
	s_barrier
; #define PG8_MMA(ai, bj, At, Bt) do { __builtin_amdgcn_s_setprio(1); _Pragma("unroll") for (int m = 0; m < 4; ++m) _Pragma("unroll") for (int n = 0; n < 2; ++n) _Pragma("unroll") for (int k = 0; k < 2; ++k) \
;         acc[ai][bj][m][n] = __builtin_amdgcn_mfma_f32_16x16x32_bf16(Bt[n][k], At[m][k], acc[ai][bj][m][n], 0, 0, 0); __builtin_amdgcn_s_setprio(0); } while (0)
; #define PG8_WAIT_V(n) asm volatile("s_waitcnt vmcnt(" #n ")" ::: "memory")
; #define PG8_WAIT_L(n) asm volatile("s_waitcnt lgkmcnt(" #n ")" ::: "memory")
; #define PG8_BAR __builtin_amdgcn_s_barrier()
; #define PG8_SCHED __builtin_amdgcn_sched_barrier(0)
; #define PG8_MMA(ai, bj, At, Bt) do { __builtin_amdgcn_s_setprio(1); _Pragma("unroll") for (int m = 0; m < 4; ++m) _Pragma("unroll") for (int n = 0; n < 2; ++n) _Pragma("unroll") for (int k = 0; k < 2; ++k) \
;         acc[ai][bj][m][n] = __builtin_amdgcn_mfma_f32_16x16x32_bf16(Bt[n][k], At[m][k], acc[ai][bj][m][n], 0, 0, 0); __builtin_amdgcn_s_setprio(0); } while (0)
; #define PG8_WAIT_V(n) asm volatile("s_waitcnt vmcnt(" #n ")" ::: "memory")
; #define PG8_WAIT_L(n) asm volatile("s_waitcnt lgkmcnt(" #n ")" ::: "memory")
; #define PG8_BAR __builtin_amdgcn_s_barrier()
; #define PG8_SCHED __builtin_amdgcn_sched_barrier(0)
; template <class Epi, class Sched>
; __device__ __forceinline__ void gemm_phase(LAS unsigned char* lds, const Gemm g, const Sched& S, const Epi& E) {
;     ...
;             PG8_WAIT_V(8); PG8_WAIT_L(0); PG8_BAR; PG8_MMA(1, 0, At, B0); PG8_MMA(1, 1, At, B1); PG8_BAR; PG8_SCHED;
;         }
;         if (wr == 0) PG8_BAR;
	s_setprio 2
	s_waitcnt lgkmcnt(0)
	v_mfma_f32_16x16x32_bf16 v[126:129], v[148:151], v[182:185], v[126:129]
	v_mfma_f32_16x16x32_bf16 v[122:125], v[156:159], v[182:185], v[122:125]
	v_mfma_f32_16x16x32_bf16 v[110:113], v[148:151], v[190:193], v[110:113]
	v_mfma_f32_16x16x32_bf16 v[106:109], v[156:159], v[190:193], v[106:109]
	v_mfma_f32_16x16x32_bf16 v[94:97], v[148:151], v[198:201], v[94:97]
	v_mfma_f32_16x16x32_bf16 v[90:93], v[156:159], v[198:201], v[90:93]
	v_mfma_f32_16x16x32_bf16 v[78:81], v[148:151], v[206:209], v[78:81]
	v_mfma_f32_16x16x32_bf16 v[74:77], v[156:159], v[206:209], v[74:77]
	v_mfma_f32_16x16x32_bf16 v[126:129], v[152:155], v[186:189], v[126:129]
	v_mfma_f32_16x16x32_bf16 v[122:125], v[160:163], v[186:189], v[122:125]
	v_mfma_f32_16x16x32_bf16 v[110:113], v[152:155], v[194:197], v[110:113]
	v_mfma_f32_16x16x32_bf16 v[106:109], v[160:163], v[194:197], v[106:109]
	v_mfma_f32_16x16x32_bf16 v[94:97], v[152:155], v[202:205], v[94:97]
	v_mfma_f32_16x16x32_bf16 v[90:93], v[160:163], v[202:205], v[90:93]
	v_mfma_f32_16x16x32_bf16 v[78:81], v[152:155], v[210:213], v[78:81]
	v_mfma_f32_16x16x32_bf16 v[74:77], v[160:163], v[210:213], v[74:77]
	s_setprio 1
	s_setprio 2
	v_mfma_f32_16x16x32_bf16 v[118:121], v[164:167], v[182:185], v[118:121]
	v_mfma_f32_16x16x32_bf16 v[114:117], v[172:175], v[182:185], v[114:117]
	v_mfma_f32_16x16x32_bf16 v[102:105], v[164:167], v[190:193], v[102:105]
	v_mfma_f32_16x16x32_bf16 v[98:101], v[172:175], v[190:193], v[98:101]
	v_mfma_f32_16x16x32_bf16 v[86:89], v[164:167], v[198:201], v[86:89]
	v_mfma_f32_16x16x32_bf16 v[82:85], v[172:175], v[198:201], v[82:85]
	v_mfma_f32_16x16x32_bf16 v[70:73], v[164:167], v[206:209], v[70:73]
	v_mfma_f32_16x16x32_bf16 v[66:69], v[172:175], v[206:209], v[66:69]
	v_mfma_f32_16x16x32_bf16 v[118:121], v[168:171], v[186:189], v[118:121]
	v_mfma_f32_16x16x32_bf16 v[114:117], v[176:179], v[186:189], v[114:117]
	v_mfma_f32_16x16x32_bf16 v[102:105], v[168:171], v[194:197], v[102:105]
	v_mfma_f32_16x16x32_bf16 v[98:101], v[176:179], v[194:197], v[98:101]
	v_mfma_f32_16x16x32_bf16 v[86:89], v[168:171], v[202:205], v[86:89]
	v_mfma_f32_16x16x32_bf16 v[82:85], v[176:179], v[202:205], v[82:85]
	v_mfma_f32_16x16x32_bf16 v[70:73], v[168:171], v[210:213], v[70:73]
	v_mfma_f32_16x16x32_bf16 v[66:69], v[176:179], v[210:213], v[66:69]
	s_setprio 1
	s_barrier
	s_add_i32 s24, s52, s30
	v_lshl_add_u64 v[144:145], v[144:145], 0, s[86:87]
	s_mov_b32 m0, s24
	ds_read_b128 v[182:185], v147 offset:49152
	ds_read_b128 v[186:189], v147 offset:50176
	ds_read_b128 v[190:193], v147 offset:51200
	ds_read_b128 v[194:197], v147 offset:52224
	ds_read_b128 v[198:201], v147 offset:53248
	ds_read_b128 v[202:205], v147 offset:54272
	ds_read_b128 v[206:209], v147 offset:55296
	ds_read_b128 v[210:213], v147 offset:56320
	global_load_lds_dwordx4 v[144:145], off
	s_add_i32 m0, s24, 0x2000
	s_add_u32 s22, s22, 0x40080
	v_lshl_add_u64 v[144:145], v[214:215], 0, s[86:87]
	s_addc_u32 s23, s23, 0
	s_add_i32 s24, s53, s30
	global_load_lds_dwordx4 v[144:145], off
	v_lshl_add_u64 v[144:145], s[22:23], 0, v[134:135]
	s_mov_b32 m0, s24
	s_nop 0
	global_load_lds_dwordx4 v[144:145], off
	v_lshl_add_u64 v[144:145], s[22:23], 0, v[130:131]
	s_add_i32 m0, s24, 0x2000
	s_nop 0
	global_load_lds_dwordx4 v[144:145], off
	v_lshl_add_u64 v[144:145], v[226:227], 0, s[86:87]
	s_mov_b32 m0, s42
	s_nop 0
	global_load_lds_dwordx4 v[144:145], off
	v_lshl_add_u64 v[144:145], v[228:229], 0, s[86:87]
	s_mov_b32 m0, s43
	s_nop 0
	global_load_lds_dwordx4 v[144:145], off
	s_waitcnt vmcnt(8)
	s_waitcnt lgkmcnt(0)
	s_barrier
	s_setprio 2
	s_waitcnt lgkmcnt(0)
	v_mfma_f32_16x16x32_bf16 v[62:65], v[148:151], v[182:185], v[62:65]
	v_mfma_f32_16x16x32_bf16 v[58:61], v[156:159], v[182:185], v[58:61]
	v_mfma_f32_16x16x32_bf16 v[46:49], v[148:151], v[190:193], v[46:49]
	v_mfma_f32_16x16x32_bf16 v[42:45], v[156:159], v[190:193], v[42:45]
	v_mfma_f32_16x16x32_bf16 v[30:33], v[148:151], v[198:201], v[30:33]
	v_mfma_f32_16x16x32_bf16 v[26:29], v[156:159], v[198:201], v[26:29]
	v_mfma_f32_16x16x32_bf16 v[14:17], v[148:151], v[206:209], v[14:17]
	v_mfma_f32_16x16x32_bf16 v[10:13], v[156:159], v[206:209], v[10:13]
	v_mfma_f32_16x16x32_bf16 v[62:65], v[152:155], v[186:189], v[62:65]
	v_mfma_f32_16x16x32_bf16 v[58:61], v[160:163], v[186:189], v[58:61]
	v_mfma_f32_16x16x32_bf16 v[46:49], v[152:155], v[194:197], v[46:49]
	v_mfma_f32_16x16x32_bf16 v[42:45], v[160:163], v[194:197], v[42:45]
	v_mfma_f32_16x16x32_bf16 v[30:33], v[152:155], v[202:205], v[30:33]
	v_mfma_f32_16x16x32_bf16 v[26:29], v[160:163], v[202:205], v[26:29]
	v_mfma_f32_16x16x32_bf16 v[14:17], v[152:155], v[210:213], v[14:17]
	v_mfma_f32_16x16x32_bf16 v[10:13], v[160:163], v[210:213], v[10:13]
	s_setprio 1
	s_setprio 2
	v_mfma_f32_16x16x32_bf16 v[54:57], v[164:167], v[182:185], v[54:57]
	v_mfma_f32_16x16x32_bf16 v[50:53], v[172:175], v[182:185], v[50:53]
	v_mfma_f32_16x16x32_bf16 v[38:41], v[164:167], v[190:193], v[38:41]
	v_mfma_f32_16x16x32_bf16 v[34:37], v[172:175], v[190:193], v[34:37]
	v_mfma_f32_16x16x32_bf16 v[22:25], v[164:167], v[198:201], v[22:25]
	v_mfma_f32_16x16x32_bf16 v[18:21], v[172:175], v[198:201], v[18:21]
	v_mfma_f32_16x16x32_bf16 v[6:9], v[164:167], v[206:209], v[6:9]
	v_mfma_f32_16x16x32_bf16 v[2:5], v[172:175], v[206:209], v[2:5]
	v_mfma_f32_16x16x32_bf16 v[54:57], v[168:171], v[186:189], v[54:57]
	v_mfma_f32_16x16x32_bf16 v[50:53], v[176:179], v[186:189], v[50:53]
	v_mfma_f32_16x16x32_bf16 v[38:41], v[168:171], v[194:197], v[38:41]
	v_mfma_f32_16x16x32_bf16 v[34:37], v[176:179], v[194:197], v[34:37]
	v_mfma_f32_16x16x32_bf16 v[22:25], v[168:171], v[202:205], v[22:25]
	v_mfma_f32_16x16x32_bf16 v[18:21], v[176:179], v[202:205], v[18:21]
	v_mfma_f32_16x16x32_bf16 v[6:9], v[168:171], v[210:213], v[6:9]
	v_mfma_f32_16x16x32_bf16 v[2:5], v[176:179], v[210:213], v[2:5]
	s_setprio 1
	s_barrier
	s_add_i32 s51, s51, 2
	s_add_u32 s49, s49, 0x100
	s_addc_u32 s50, s50, 0
	s_add_u32 s20, s20, 0x100
	s_addc_u32 s21, s21, 0
	s_cmp_gt_u32 s51, 13
	s_cbranch_scc0 .Lkb_gates
	s_setprio 0
.Lkend_gates:
	s_and_b64 vcc, exec, s[10:11]
	s_cbranch_vccz .LBB0_834
	s_barrier

; #define PG8_STAGE(bufoff, gbase, voff) do { _Pragma("unroll") for (int _i = 0; _i < 2; ++_i) \
;         __builtin_amdgcn_global_load_lds((const unsigned*)((const char*)(gbase) + (voff)[_i]), (LAS unsigned*)(lds + (bufoff) + ldsw + _i * 8192), 16, 0, 0); } while (0)
; #define PG8_LDA(dst, b, h) do { _Pragma("unroll") for (int m = 0; m < 4; ++m) _Pragma("unroll") for (int k = 0; k < 2; ++k) dst[m][k] = *(const LAS bf16x8*)(lds + PG8_SA(b, h) + aoff + m * 2048 + k * 1024); } while (0)
; #define PG8_LDB(dst, b, h) do { _Pragma("unroll") for (int n = 0; n < 2; ++n) _Pragma("unroll") for (int k = 0; k < 2; ++k) dst[n][k] = *(const LAS bf16x8*)(lds + PG8_SB(b, h) + boff + n * 2048 + k * 1024); } while (0)
; #define PG8_SCHED __builtin_amdgcn_sched_barrier(0)
; #define PG8_STAGE(bufoff, gbase, voff) do { _Pragma("unroll") for (int _i = 0; _i < 2; ++_i) \
;         __builtin_amdgcn_global_load_lds((const unsigned*)((const char*)(gbase) + (voff)[_i]), (LAS unsigned*)(lds + (bufoff) + ldsw + _i * 8192), 16, 0, 0); } while (0)
; #define PG8_LDA(dst, b, h) do { _Pragma("unroll") for (int m = 0; m < 4; ++m) _Pragma("unroll") for (int k = 0; k < 2; ++k) dst[m][k] = *(const LAS bf16x8*)(lds + PG8_SA(b, h) + aoff + m * 2048 + k * 1024); } while (0)
; #define PG8_SCHED __builtin_amdgcn_sched_barrier(0)
; template <class Epi, class Sched>
; __device__ __forceinline__ void gemm_phase(LAS unsigned char* lds, const Gemm g, const Sched& S, const Epi& E) {
;     ...
;         const char* nA = has_next ? (const char*)g.A + (size_t)nxt.pm * tstepA : cA; const char* nB = has_next ? (const char*)g.Bt + (size_t)nxt.pn * tstepB : cB;
;         for (int t = 0; t < nt; t += 2) {
;             const bool last = (t == nt - 2);
;             const char* a1 = cA + (size_t)(t + 1) * kstep;
;             const char* a2 = last ? nA : cA + (size_t)(t + 2) * kstep; const char* b2 = last ? nB : cB + (size_t)(t + 2) * kstep;
;             const char* a3 = a2 + kstep; const char* b3 = b2 + kstep;
;             PG8_LDB(B0, 0, 0); PG8_LDB(B1, 0, 1); PG8_SCHED; PG8_LDA(At, 0, 0); PG8_STAGE(PG8_SA(1, 1), a1 + hstepA, voffA);
;     ...
; #pragma unroll
;         for (int a = 0; a < 2; ++a)
; #pragma unroll
;             for (int b = 0; b < 2; ++b)
; #pragma unroll
;                 for (int m = 0; m < 4; ++m)
; #pragma unroll
;                     for (int n = 0; n < 2; ++n) acc[a][b][m][n] = (f32x4){0.f, 0.f, 0.f, 0.f};
.LBB0_1050:
	s_ashr_i32 s23, s22, 31
	s_lshl_b64 s[24:25], s[22:23], 19
	s_add_u32 s24, s45, s24
	s_addc_u32 s25, s46, s25
	s_and_b64 s[26:27], s[8:9], exec
	s_cselect_b32 s23, s25, s37
	s_cselect_b32 s29, s24, s36
	s_ashr_i32 s21, s20, 31
	s_lshl_b64 s[26:27], s[20:21], 19
	s_add_u32 s26, s42, s26
	s_addc_u32 s27, s43, s27
	s_and_b64 s[38:39], s[8:9], exec
	s_cselect_b32 s21, s27, s35
	s_cselect_b32 s56, s26, s34
	s_add_u32 s57, s34, 0x100
	s_addc_u32 s58, s35, 0
	s_add_u32 s34, s36, 0x40080
	v_mov_b32_e32 v2, 0
	s_addc_u32 s35, s37, 0
	s_mov_b32 s62, -2
	v_mov_b32_e32 v3, v2
	v_mov_b32_e32 v4, v2
	v_mov_b32_e32 v5, v2
	v_mov_b32_e32 v6, v2
	v_mov_b32_e32 v7, v2
	v_mov_b32_e32 v8, v2
	v_mov_b32_e32 v9, v2
	v_mov_b32_e32 v18, v2
	v_mov_b32_e32 v19, v2
	v_mov_b32_e32 v20, v2
	v_mov_b32_e32 v21, v2
	v_mov_b32_e32 v22, v2
	v_mov_b32_e32 v23, v2
	v_mov_b32_e32 v24, v2
	v_mov_b32_e32 v25, v2
	v_mov_b32_e32 v34, v2
	v_mov_b32_e32 v35, v2
	v_mov_b32_e32 v36, v2
	v_mov_b32_e32 v37, v2
	v_mov_b32_e32 v38, v2
	v_mov_b32_e32 v39, v2
	v_mov_b32_e32 v40, v2
	v_mov_b32_e32 v41, v2
	v_mov_b32_e32 v50, v2
	v_mov_b32_e32 v51, v2
	v_mov_b32_e32 v52, v2
	v_mov_b32_e32 v53, v2
	v_mov_b32_e32 v54, v2
	v_mov_b32_e32 v55, v2
	v_mov_b32_e32 v56, v2
	v_mov_b32_e32 v57, v2
	v_mov_b32_e32 v10, v2
	v_mov_b32_e32 v11, v2
	v_mov_b32_e32 v12, v2
	v_mov_b32_e32 v13, v2
	v_mov_b32_e32 v14, v2
	v_mov_b32_e32 v15, v2
	v_mov_b32_e32 v16, v2
	v_mov_b32_e32 v17, v2
	v_mov_b32_e32 v26, v2
	v_mov_b32_e32 v27, v2
	v_mov_b32_e32 v28, v2
	v_mov_b32_e32 v29, v2
	v_mov_b32_e32 v30, v2
	v_mov_b32_e32 v31, v2
	v_mov_b32_e32 v32, v2
	v_mov_b32_e32 v33, v2
	v_mov_b32_e32 v42, v2
	v_mov_b32_e32 v43, v2
	v_mov_b32_e32 v44, v2
	v_mov_b32_e32 v45, v2
	v_mov_b32_e32 v46, v2
	v_mov_b32_e32 v47, v2
	v_mov_b32_e32 v48, v2
	v_mov_b32_e32 v49, v2
	v_mov_b32_e32 v58, v2
	v_mov_b32_e32 v59, v2
	v_mov_b32_e32 v60, v2
	v_mov_b32_e32 v61, v2
	v_mov_b32_e32 v62, v2
	v_mov_b32_e32 v63, v2
	v_mov_b32_e32 v64, v2
	v_mov_b32_e32 v65, v2
	v_mov_b32_e32 v66, v2
	v_mov_b32_e32 v67, v2
	v_mov_b32_e32 v68, v2
	v_mov_b32_e32 v69, v2
	v_mov_b32_e32 v70, v2
	v_mov_b32_e32 v71, v2
	v_mov_b32_e32 v72, v2
	v_mov_b32_e32 v73, v2
	v_mov_b32_e32 v82, v2
	v_mov_b32_e32 v83, v2
	v_mov_b32_e32 v84, v2
	v_mov_b32_e32 v85, v2
	v_mov_b32_e32 v86, v2
	v_mov_b32_e32 v87, v2
	v_mov_b32_e32 v88, v2
	v_mov_b32_e32 v89, v2
	v_mov_b32_e32 v98, v2
	v_mov_b32_e32 v99, v2
	v_mov_b32_e32 v100, v2
	v_mov_b32_e32 v101, v2
	v_mov_b32_e32 v102, v2
	v_mov_b32_e32 v103, v2
	v_mov_b32_e32 v104, v2
	v_mov_b32_e32 v105, v2
	s_waitcnt vmcnt(0)
	v_mov_b32_e32 v114, v2
	v_mov_b32_e32 v115, v2
	v_mov_b32_e32 v116, v2
	v_mov_b32_e32 v117, v2
	v_mov_b32_e32 v118, v2
	v_mov_b32_e32 v119, v2
	v_mov_b32_e32 v120, v2
	v_mov_b32_e32 v121, v2
	v_mov_b32_e32 v74, v2
	v_mov_b32_e32 v75, v2
	v_mov_b32_e32 v76, v2
	v_mov_b32_e32 v77, v2
	v_mov_b32_e32 v78, v2
	v_mov_b32_e32 v79, v2
	v_mov_b32_e32 v80, v2
	v_mov_b32_e32 v81, v2
	v_mov_b32_e32 v90, v2
	v_mov_b32_e32 v91, v2
	v_mov_b32_e32 v92, v2
	v_mov_b32_e32 v93, v2
	v_mov_b32_e32 v94, v2
	v_mov_b32_e32 v95, v2
	v_mov_b32_e32 v96, v2
	v_mov_b32_e32 v97, v2
	v_mov_b32_e32 v106, v2
	v_mov_b32_e32 v107, v2
	v_mov_b32_e32 v108, v2
	v_mov_b32_e32 v109, v2
	v_mov_b32_e32 v110, v2
	v_mov_b32_e32 v111, v2
	v_mov_b32_e32 v112, v2
	v_mov_b32_e32 v113, v2
	v_mov_b32_e32 v122, v2
	v_mov_b32_e32 v123, v2
	v_mov_b32_e32 v124, v2
	v_mov_b32_e32 v125, v2
	v_mov_b32_e32 v126, v2
	v_mov_b32_e32 v127, v2
	v_mov_b32_e32 v128, v2
	v_mov_b32_e32 v129, v2
	s_cmp_lg_u64 s[10:11], 0
	s_cbranch_scc1 .Lkb_out
.LBB0_1051:
	s_add_u32 s36, s34, 0xfffc0080
	s_addc_u32 s37, s35, -1
	s_add_i32 s66, 0, 0x10000
	s_cmp_eq_u32 s62, 12
	s_cselect_b32 s39, s23, s37
	s_cselect_b32 s38, s29, s36
	v_add_u32_e32 v146, s66, v148
	s_cselect_b32 s37, s21, s58
	s_cselect_b32 s36, s56, s57
	s_add_i32 s70, 0, 0x14000
	ds_read_b128 v[142:145], v146
	ds_read_b128 v[152:155], v146 offset:1024
	ds_read_b128 v[156:159], v146 offset:2048
	ds_read_b128 v[160:163], v146 offset:3072
	v_add_u32_e32 v146, s70, v148
	ds_read_b128 v[164:167], v146
	ds_read_b128 v[168:171], v146 offset:1024
	ds_read_b128 v[172:175], v146 offset:2048
	ds_read_b128 v[176:179], v146 offset:3072
	v_lshl_add_u64 v[146:147], s[34:35], 0, v[140:141]
	s_add_i32 m0, s31, 0xc000
	ds_read_b128 v[182:185], v150
	ds_read_b128 v[186:189], v150 offset:1024
	ds_read_b128 v[190:193], v150 offset:2048
	ds_read_b128 v[194:197], v150 offset:3072
	ds_read_b128 v[198:201], v150 offset:4096
	ds_read_b128 v[202:205], v150 offset:5120
	ds_read_b128 v[206:209], v150 offset:6144
	ds_read_b128 v[210:213], v150 offset:7168
	global_load_lds_dwordx4 v[146:147], off
	v_lshl_add_u64 v[146:147], s[34:35], 0, v[138:139]
	s_add_i32 m0, s31, 0xe000
	s_nop 0
	global_load_lds_dwordx4 v[146:147], off
	s_waitcnt vmcnt(8)
	s_waitcnt lgkmcnt(0)
	s_barrier
; #define PG8_STAGE(bufoff, gbase, voff) do { _Pragma("unroll") for (int _i = 0; _i < 2; ++_i) \
;         __builtin_amdgcn_global_load_lds((const unsigned*)((const char*)(gbase) + (voff)[_i]), (LAS unsigned*)(lds + (bufoff) + ldsw + _i * 8192), 16, 0, 0); } while (0)
; #define PG8_LDA(dst, b, h) do { _Pragma("unroll") for (int m = 0; m < 4; ++m) _Pragma("unroll") for (int k = 0; k < 2; ++k) dst[m][k] = *(const LAS bf16x8*)(lds + PG8_SA(b, h) + aoff + m * 2048 + k * 1024); } while (0)
; #define PG8_MMA(ai, bj, At, Bt) do { __builtin_amdgcn_s_setprio(1); _Pragma("unroll") for (int m = 0; m < 4; ++m) _Pragma("unroll") for (int n = 0; n < 2; ++n) _Pragma("unroll") for (int k = 0; k < 2; ++k) \
;         acc[ai][bj][m][n] = __builtin_amdgcn_mfma_f32_16x16x32_bf16(Bt[n][k], At[m][k], acc[ai][bj][m][n], 0, 0, 0); __builtin_amdgcn_s_setprio(0); } while (0)
; #define PG8_WAIT_V(n) asm volatile("s_waitcnt vmcnt(" #n ")" ::: "memory")
; #define PG8_WAIT_L(n) asm volatile("s_waitcnt lgkmcnt(" #n ")" ::: "memory")
; #define PG8_BAR __builtin_amdgcn_s_barrier()
; #define PG8_SCHED __builtin_amdgcn_sched_barrier(0)
; #define PG8_STAGE(bufoff, gbase, voff) do { _Pragma("unroll") for (int _i = 0; _i < 2; ++_i) \
;         __builtin_amdgcn_global_load_lds((const unsigned*)((const char*)(gbase) + (voff)[_i]), (LAS unsigned*)(lds + (bufoff) + ldsw + _i * 8192), 16, 0, 0); } while (0)
; #define PG8_LDA(dst, b, h) do { _Pragma("unroll") for (int m = 0; m < 4; ++m) _Pragma("unroll") for (int k = 0; k < 2; ++k) dst[m][k] = *(const LAS bf16x8*)(lds + PG8_SA(b, h) + aoff + m * 2048 + k * 1024); } while (0)
; #define PG8_WAIT_V(n) asm volatile("s_waitcnt vmcnt(" #n ")" ::: "memory")
; #define PG8_WAIT_L(n) asm volatile("s_waitcnt lgkmcnt(" #n ")" ::: "memory")
; #define PG8_BAR __builtin_amdgcn_s_barrier()
; template <class Epi, class Sched>
; __device__ __forceinline__ void gemm_phase(LAS unsigned char* lds, const Gemm g, const Sched& S, const Epi& E) {
;     ...
;             PG8_WAIT_V(8); PG8_WAIT_L(0); PG8_BAR; PG8_MMA(0, 0, At, B0); PG8_MMA(0, 1, At, B1); PG8_BAR; PG8_SCHED;
;             PG8_LDA(At, 0, 1); PG8_STAGE(PG8_SB(0, 0), b2, voffB); PG8_STAGE(PG8_SB(0, 1), b2 + hstepB, voffB); PG8_STAGE(PG8_SA(0, 0), a2, voffA);
;             PG8_WAIT_V(8); PG8_WAIT_L(0); PG8_BAR; PG8_MMA(1, 0, At, B0); PG8_MMA(1, 1, At, B1); PG8_BAR; PG8_SCHED;
	s_setprio 1
	s_waitcnt lgkmcnt(0)
	v_mfma_f32_16x16x32_bf16 v[126:129], v[142:145], v[182:185], v[126:129]
	v_mfma_f32_16x16x32_bf16 v[122:125], v[156:159], v[182:185], v[122:125]
	v_mfma_f32_16x16x32_bf16 v[110:113], v[142:145], v[190:193], v[110:113]
	v_mfma_f32_16x16x32_bf16 v[106:109], v[156:159], v[190:193], v[106:109]
	v_mfma_f32_16x16x32_bf16 v[94:97], v[142:145], v[198:201], v[94:97]
	v_mfma_f32_16x16x32_bf16 v[90:93], v[156:159], v[198:201], v[90:93]
	v_mfma_f32_16x16x32_bf16 v[78:81], v[142:145], v[206:209], v[78:81]
	v_mfma_f32_16x16x32_bf16 v[74:77], v[156:159], v[206:209], v[74:77]
	v_mfma_f32_16x16x32_bf16 v[126:129], v[152:155], v[186:189], v[126:129]
	v_mfma_f32_16x16x32_bf16 v[122:125], v[160:163], v[186:189], v[122:125]
	v_mfma_f32_16x16x32_bf16 v[110:113], v[152:155], v[194:197], v[110:113]
	v_mfma_f32_16x16x32_bf16 v[106:109], v[160:163], v[194:197], v[106:109]
	v_mfma_f32_16x16x32_bf16 v[94:97], v[152:155], v[202:205], v[94:97]
	v_mfma_f32_16x16x32_bf16 v[90:93], v[160:163], v[202:205], v[90:93]
	v_mfma_f32_16x16x32_bf16 v[78:81], v[152:155], v[210:213], v[78:81]
	v_mfma_f32_16x16x32_bf16 v[74:77], v[160:163], v[210:213], v[74:77]
	s_setprio 0
	s_setprio 1
	v_mfma_f32_16x16x32_bf16 v[118:121], v[164:167], v[182:185], v[118:121]
	v_mfma_f32_16x16x32_bf16 v[114:117], v[172:175], v[182:185], v[114:117]
	v_mfma_f32_16x16x32_bf16 v[102:105], v[164:167], v[190:193], v[102:105]
	v_mfma_f32_16x16x32_bf16 v[98:101], v[172:175], v[190:193], v[98:101]
	v_mfma_f32_16x16x32_bf16 v[86:89], v[164:167], v[198:201], v[86:89]
	v_mfma_f32_16x16x32_bf16 v[82:85], v[172:175], v[198:201], v[82:85]
	v_mfma_f32_16x16x32_bf16 v[70:73], v[164:167], v[206:209], v[70:73]
	v_mfma_f32_16x16x32_bf16 v[66:69], v[172:175], v[206:209], v[66:69]
	v_mfma_f32_16x16x32_bf16 v[118:121], v[168:171], v[186:189], v[118:121]
	v_mfma_f32_16x16x32_bf16 v[114:117], v[176:179], v[186:189], v[114:117]
	v_mfma_f32_16x16x32_bf16 v[102:105], v[168:171], v[194:197], v[102:105]
	v_mfma_f32_16x16x32_bf16 v[98:101], v[176:179], v[194:197], v[98:101]
	v_mfma_f32_16x16x32_bf16 v[86:89], v[168:171], v[202:205], v[86:89]
	v_mfma_f32_16x16x32_bf16 v[82:85], v[176:179], v[202:205], v[82:85]
	v_mfma_f32_16x16x32_bf16 v[70:73], v[168:171], v[210:213], v[70:73]
	v_mfma_f32_16x16x32_bf16 v[66:69], v[176:179], v[210:213], v[66:69]
	s_setprio 0
	s_barrier
	s_add_i32 s66, s66, s44
	v_lshl_add_u64 v[146:147], s[36:37], 0, v[132:133]
	s_mov_b32 m0, s66
	ds_read_b128 v[182:185], v150 offset:16384
	ds_read_b128 v[186:189], v150 offset:17408
	ds_read_b128 v[190:193], v150 offset:18432
	ds_read_b128 v[194:197], v150 offset:19456
	ds_read_b128 v[198:201], v150 offset:20480
	ds_read_b128 v[202:205], v150 offset:21504
	ds_read_b128 v[206:209], v150 offset:22528
	ds_read_b128 v[210:213], v150 offset:23552
	global_load_lds_dwordx4 v[146:147], off
	s_add_i32 m0, s66, 0x2000
	s_add_u32 s66, s36, 0x40000
	v_lshl_add_u64 v[214:215], s[36:37], 0, v[136:137]
	s_addc_u32 s67, s37, 0
	s_add_i32 s70, s70, s44
	global_load_lds_dwordx4 v[214:215], off
	v_lshl_add_u64 v[226:227], s[66:67], 0, v[132:133]
	s_mov_b32 m0, s70
	v_lshl_add_u64 v[228:229], s[38:39], 0, v[134:135]
	global_load_lds_dwordx4 v[226:227], off
	v_lshl_add_u64 v[226:227], s[66:67], 0, v[136:137]
	s_add_i32 m0, s70, 0x2000
	s_nop 0
	global_load_lds_dwordx4 v[226:227], off
	v_lshl_add_u64 v[226:227], s[38:39], 0, v[130:131]
	s_mov_b32 m0, s31
	s_nop 0
	global_load_lds_dwordx4 v[226:227], off
	s_mov_b32 m0, s48
	s_nop 0
	global_load_lds_dwordx4 v[228:229], off
	s_waitcnt vmcnt(8)
	s_waitcnt lgkmcnt(0)
	s_barrier
	s_setprio 1
	s_waitcnt lgkmcnt(0)
	v_mfma_f32_16x16x32_bf16 v[62:65], v[142:145], v[182:185], v[62:65]
	v_mfma_f32_16x16x32_bf16 v[58:61], v[156:159], v[182:185], v[58:61]
	v_mfma_f32_16x16x32_bf16 v[46:49], v[142:145], v[190:193], v[46:49]
	v_mfma_f32_16x16x32_bf16 v[42:45], v[156:159], v[190:193], v[42:45]
	v_mfma_f32_16x16x32_bf16 v[30:33], v[142:145], v[198:201], v[30:33]
	v_mfma_f32_16x16x32_bf16 v[26:29], v[156:159], v[198:201], v[26:29]
	v_mfma_f32_16x16x32_bf16 v[14:17], v[142:145], v[206:209], v[14:17]
	v_mfma_f32_16x16x32_bf16 v[10:13], v[156:159], v[206:209], v[10:13]
	v_mfma_f32_16x16x32_bf16 v[62:65], v[152:155], v[186:189], v[62:65]
	v_mfma_f32_16x16x32_bf16 v[58:61], v[160:163], v[186:189], v[58:61]
	v_mfma_f32_16x16x32_bf16 v[46:49], v[152:155], v[194:197], v[46:49]
	v_mfma_f32_16x16x32_bf16 v[42:45], v[160:163], v[194:197], v[42:45]
	v_mfma_f32_16x16x32_bf16 v[30:33], v[152:155], v[202:205], v[30:33]
	v_mfma_f32_16x16x32_bf16 v[26:29], v[160:163], v[202:205], v[26:29]
	v_mfma_f32_16x16x32_bf16 v[14:17], v[152:155], v[210:213], v[14:17]
	v_mfma_f32_16x16x32_bf16 v[10:13], v[160:163], v[210:213], v[10:13]
	s_setprio 0
	s_setprio 1
	v_mfma_f32_16x16x32_bf16 v[54:57], v[164:167], v[182:185], v[54:57]
	v_mfma_f32_16x16x32_bf16 v[50:53], v[172:175], v[182:185], v[50:53]
	v_mfma_f32_16x16x32_bf16 v[38:41], v[164:167], v[190:193], v[38:41]
	v_mfma_f32_16x16x32_bf16 v[34:37], v[172:175], v[190:193], v[34:37]
	v_mfma_f32_16x16x32_bf16 v[22:25], v[164:167], v[198:201], v[22:25]
	v_mfma_f32_16x16x32_bf16 v[18:21], v[172:175], v[198:201], v[18:21]
	v_mfma_f32_16x16x32_bf16 v[6:9], v[164:167], v[206:209], v[6:9]
	v_mfma_f32_16x16x32_bf16 v[2:5], v[172:175], v[206:209], v[2:5]
	v_mfma_f32_16x16x32_bf16 v[54:57], v[168:171], v[186:189], v[54:57]
	v_mfma_f32_16x16x32_bf16 v[50:53], v[176:179], v[186:189], v[50:53]
	v_mfma_f32_16x16x32_bf16 v[38:41], v[168:171], v[194:197], v[38:41]
	v_mfma_f32_16x16x32_bf16 v[34:37], v[176:179], v[194:197], v[34:37]
	v_mfma_f32_16x16x32_bf16 v[22:25], v[168:171], v[202:205], v[22:25]
	v_mfma_f32_16x16x32_bf16 v[18:21], v[176:179], v[202:205], v[18:21]
	v_mfma_f32_16x16x32_bf16 v[6:9], v[168:171], v[210:213], v[6:9]
	v_mfma_f32_16x16x32_bf16 v[2:5], v[176:179], v[210:213], v[2:5]
	s_setprio 0
	s_barrier
; #define PG8_STAGE(bufoff, gbase, voff) do { _Pragma("unroll") for (int _i = 0; _i < 2; ++_i) \
;         __builtin_amdgcn_global_load_lds((const unsigned*)((const char*)(gbase) + (voff)[_i]), (LAS unsigned*)(lds + (bufoff) + ldsw + _i * 8192), 16, 0, 0); } while (0)
; #define PG8_LDA(dst, b, h) do { _Pragma("unroll") for (int m = 0; m < 4; ++m) _Pragma("unroll") for (int k = 0; k < 2; ++k) dst[m][k] = *(const LAS bf16x8*)(lds + PG8_SA(b, h) + aoff + m * 2048 + k * 1024); } while (0)
; #define PG8_LDB(dst, b, h) do { _Pragma("unroll") for (int n = 0; n < 2; ++n) _Pragma("unroll") for (int k = 0; k < 2; ++k) dst[n][k] = *(const LAS bf16x8*)(lds + PG8_SB(b, h) + boff + n * 2048 + k * 1024); } while (0)
; #define PG8_MMA(ai, bj, At, Bt) do { __builtin_amdgcn_s_setprio(1); _Pragma("unroll") for (int m = 0; m < 4; ++m) _Pragma("unroll") for (int n = 0; n < 2; ++n) _Pragma("unroll") for (int k = 0; k < 2; ++k) \
;         acc[ai][bj][m][n] = __builtin_amdgcn_mfma_f32_16x16x32_bf16(Bt[n][k], At[m][k], acc[ai][bj][m][n], 0, 0, 0); __builtin_amdgcn_s_setprio(0); } while (0)
; #define PG8_WAIT_V(n) asm volatile("s_waitcnt vmcnt(" #n ")" ::: "memory")
; #define PG8_WAIT_L(n) asm volatile("s_waitcnt lgkmcnt(" #n ")" ::: "memory")
; #define PG8_BAR __builtin_amdgcn_s_barrier()
; #define PG8_SCHED __builtin_amdgcn_sched_barrier(0)
; #define PG8_STAGE(bufoff, gbase, voff) do { _Pragma("unroll") for (int _i = 0; _i < 2; ++_i) \
;         __builtin_amdgcn_global_load_lds((const unsigned*)((const char*)(gbase) + (voff)[_i]), (LAS unsigned*)(lds + (bufoff) + ldsw + _i * 8192), 16, 0, 0); } while (0)
; #define PG8_LDA(dst, b, h) do { _Pragma("unroll") for (int m = 0; m < 4; ++m) _Pragma("unroll") for (int k = 0; k < 2; ++k) dst[m][k] = *(const LAS bf16x8*)(lds + PG8_SA(b, h) + aoff + m * 2048 + k * 1024); } while (0)
; template <class Epi, class Sched>
; __device__ __forceinline__ void gemm_phase(LAS unsigned char* lds, const Gemm g, const Sched& S, const Epi& E) {
;     ...
;             PG8_LDB(B0, 1, 0); PG8_LDB(B1, 1, 1); PG8_SCHED; PG8_LDA(At, 1, 0); PG8_STAGE(PG8_SA(0, 1), a2 + hstepA, voffA);
;             PG8_WAIT_V(8); PG8_WAIT_L(0); PG8_BAR; PG8_MMA(0, 0, At, B0); PG8_MMA(0, 1, At, B1); PG8_BAR; PG8_SCHED;
;             PG8_LDA(At, 1, 1); PG8_STAGE(PG8_SB(1, 0), b3, voffB); PG8_STAGE(PG8_SB(1, 1), b3 + hstepB, voffB); PG8_STAGE(PG8_SA(1, 0), a3, voffA);
	s_add_i32 s66, 0, 0x18000
	v_add_u32_e32 v151, s66, v148
	s_add_i32 s67, 0, 0x1c000
	ds_read_b128 v[142:145], v151
	ds_read_b128 v[152:155], v151 offset:1024
	ds_read_b128 v[156:159], v151 offset:2048
	ds_read_b128 v[160:163], v151 offset:3072
	v_add_u32_e32 v151, s67, v148
	ds_read_b128 v[164:167], v151
	ds_read_b128 v[168:171], v151 offset:1024
	ds_read_b128 v[172:175], v151 offset:2048
	ds_read_b128 v[176:179], v151 offset:3072
	s_add_u32 s38, s38, 0x40000
	s_addc_u32 s39, s39, 0
	s_mov_b32 m0, s49
	v_lshl_add_u64 v[232:233], s[38:39], 0, v[130:131]
	ds_read_b128 v[182:185], v150 offset:32768
	ds_read_b128 v[186:189], v150 offset:33792
	ds_read_b128 v[190:193], v150 offset:34816
	ds_read_b128 v[194:197], v150 offset:35840
	ds_read_b128 v[198:201], v150 offset:36864
	ds_read_b128 v[202:205], v150 offset:37888
	ds_read_b128 v[206:209], v150 offset:38912
	ds_read_b128 v[210:213], v150 offset:39936
	global_load_lds_dwordx4 v[232:233], off
	v_lshl_add_u64 v[232:233], s[38:39], 0, v[134:135]
	s_mov_b32 m0, s50
	s_nop 0
	global_load_lds_dwordx4 v[232:233], off
	s_waitcnt vmcnt(8)
	s_waitcnt lgkmcnt(0)
	s_barrier
	s_setprio 1
	s_waitcnt lgkmcnt(0)
	v_mfma_f32_16x16x32_bf16 v[126:129], v[142:145], v[182:185], v[126:129]
	v_mfma_f32_16x16x32_bf16 v[122:125], v[156:159], v[182:185], v[122:125]
	v_mfma_f32_16x16x32_bf16 v[110:113], v[142:145], v[190:193], v[110:113]
	v_mfma_f32_16x16x32_bf16 v[106:109], v[156:159], v[190:193], v[106:109]
	v_mfma_f32_16x16x32_bf16 v[94:97], v[142:145], v[198:201], v[94:97]
	v_mfma_f32_16x16x32_bf16 v[90:93], v[156:159], v[198:201], v[90:93]
	v_mfma_f32_16x16x32_bf16 v[78:81], v[142:145], v[206:209], v[78:81]
	v_mfma_f32_16x16x32_bf16 v[74:77], v[156:159], v[206:209], v[74:77]
	v_mfma_f32_16x16x32_bf16 v[126:129], v[152:155], v[186:189], v[126:129]
	v_mfma_f32_16x16x32_bf16 v[122:125], v[160:163], v[186:189], v[122:125]
	v_mfma_f32_16x16x32_bf16 v[110:113], v[152:155], v[194:197], v[110:113]
	v_mfma_f32_16x16x32_bf16 v[106:109], v[160:163], v[194:197], v[106:109]
	v_mfma_f32_16x16x32_bf16 v[94:97], v[152:155], v[202:205], v[94:97]
	v_mfma_f32_16x16x32_bf16 v[90:93], v[160:163], v[202:205], v[90:93]
	v_mfma_f32_16x16x32_bf16 v[78:81], v[152:155], v[210:213], v[78:81]
	v_mfma_f32_16x16x32_bf16 v[74:77], v[160:163], v[210:213], v[74:77]
	s_setprio 0
	s_setprio 1
	v_mfma_f32_16x16x32_bf16 v[118:121], v[164:167], v[182:185], v[118:121]
	v_mfma_f32_16x16x32_bf16 v[114:117], v[172:175], v[182:185], v[114:117]
	v_mfma_f32_16x16x32_bf16 v[102:105], v[164:167], v[190:193], v[102:105]
	v_mfma_f32_16x16x32_bf16 v[98:101], v[172:175], v[190:193], v[98:101]
	v_mfma_f32_16x16x32_bf16 v[86:89], v[164:167], v[198:201], v[86:89]
	v_mfma_f32_16x16x32_bf16 v[82:85], v[172:175], v[198:201], v[82:85]
	v_mfma_f32_16x16x32_bf16 v[70:73], v[164:167], v[206:209], v[70:73]
	v_mfma_f32_16x16x32_bf16 v[66:69], v[172:175], v[206:209], v[66:69]
	v_mfma_f32_16x16x32_bf16 v[118:121], v[168:171], v[186:189], v[118:121]
	v_mfma_f32_16x16x32_bf16 v[114:117], v[176:179], v[186:189], v[114:117]
	v_mfma_f32_16x16x32_bf16 v[102:105], v[168:171], v[194:197], v[102:105]
	v_mfma_f32_16x16x32_bf16 v[98:101], v[176:179], v[194:197], v[98:101]
	v_mfma_f32_16x16x32_bf16 v[86:89], v[168:171], v[202:205], v[86:89]
	v_mfma_f32_16x16x32_bf16 v[82:85], v[176:179], v[202:205], v[82:85]
	v_mfma_f32_16x16x32_bf16 v[70:73], v[168:171], v[210:213], v[70:73]
	v_mfma_f32_16x16x32_bf16 v[66:69], v[176:179], v[210:213], v[66:69]
	s_setprio 0
	s_barrier
	s_add_i32 s38, s66, s44
	v_lshl_add_u64 v[146:147], v[146:147], 0, s[86:87]
	s_mov_b32 m0, s38
	ds_read_b128 v[182:185], v150 offset:49152
	ds_read_b128 v[186:189], v150 offset:50176
	ds_read_b128 v[190:193], v150 offset:51200
	ds_read_b128 v[194:197], v150 offset:52224
	ds_read_b128 v[198:201], v150 offset:53248
	ds_read_b128 v[202:205], v150 offset:54272
	ds_read_b128 v[206:209], v150 offset:55296
	ds_read_b128 v[210:213], v150 offset:56320
	global_load_lds_dwordx4 v[146:147], off
	s_add_i32 m0, s38, 0x2000
	s_add_u32 s36, s36, 0x40080
	v_lshl_add_u64 v[146:147], v[214:215], 0, s[86:87]
	s_addc_u32 s37, s37, 0
	s_add_i32 s38, s67, s44
	global_load_lds_dwordx4 v[146:147], off
	v_lshl_add_u64 v[146:147], s[36:37], 0, v[132:133]
	s_mov_b32 m0, s38
	s_nop 0
	global_load_lds_dwordx4 v[146:147], off
	v_lshl_add_u64 v[146:147], s[36:37], 0, v[136:137]
	s_add_i32 m0, s38, 0x2000
	s_nop 0
	global_load_lds_dwordx4 v[146:147], off
	v_lshl_add_u64 v[146:147], v[226:227], 0, s[86:87]
	s_mov_b32 m0, s51
	s_nop 0
	global_load_lds_dwordx4 v[146:147], off
	v_lshl_add_u64 v[146:147], v[228:229], 0, s[86:87]
	s_mov_b32 m0, s52
	s_nop 0
	global_load_lds_dwordx4 v[146:147], off
	s_waitcnt vmcnt(8)
	s_waitcnt lgkmcnt(0)
	s_barrier
; #define PG8_STAGE(bufoff, gbase, voff) do { _Pragma("unroll") for (int _i = 0; _i < 2; ++_i) \
;         __builtin_amdgcn_global_load_lds((const unsigned*)((const char*)(gbase) + (voff)[_i]), (LAS unsigned*)(lds + (bufoff) + ldsw + _i * 8192), 16, 0, 0); } while (0)
; #define PG8_LDA(dst, b, h) do { _Pragma("unroll") for (int m = 0; m < 4; ++m) _Pragma("unroll") for (int k = 0; k < 2; ++k) dst[m][k] = *(const LAS bf16x8*)(lds + PG8_SA(b, h) + aoff + m * 2048 + k * 1024); } while (0)
; #define PG8_LDB(dst, b, h) do { _Pragma("unroll") for (int n = 0; n < 2; ++n) _Pragma("unroll") for (int k = 0; k < 2; ++k) dst[n][k] = *(const LAS bf16x8*)(lds + PG8_SB(b, h) + boff + n * 2048 + k * 1024); } while (0)
; #define PG8_MMA(ai, bj, At, Bt) do { __builtin_amdgcn_s_setprio(1); _Pragma("unroll") for (int m = 0; m < 4; ++m) _Pragma("unroll") for (int n = 0; n < 2; ++n) _Pragma("unroll") for (int k = 0; k < 2; ++k) \
;         acc[ai][bj][m][n] = __builtin_amdgcn_mfma_f32_16x16x32_bf16(Bt[n][k], At[m][k], acc[ai][bj][m][n], 0, 0, 0); __builtin_amdgcn_s_setprio(0); } while (0)
; #define PG8_WAIT_V(n) asm volatile("s_waitcnt vmcnt(" #n ")" ::: "memory")
; #define PG8_WAIT_L(n) asm volatile("s_waitcnt lgkmcnt(" #n ")" ::: "memory")
; #define PG8_BAR __builtin_amdgcn_s_barrier()
; #define PG8_SCHED __builtin_amdgcn_sched_barrier(0)
; #define PG8_STAGE(bufoff, gbase, voff) do { _Pragma("unroll") for (int _i = 0; _i < 2; ++_i) \
;         __builtin_amdgcn_global_load_lds((const unsigned*)((const char*)(gbase) + (voff)[_i]), (LAS unsigned*)(lds + (bufoff) + ldsw + _i * 8192), 16, 0, 0); } while (0)
; #define PG8_LDA(dst, b, h) do { _Pragma("unroll") for (int m = 0; m < 4; ++m) _Pragma("unroll") for (int k = 0; k < 2; ++k) dst[m][k] = *(const LAS bf16x8*)(lds + PG8_SA(b, h) + aoff + m * 2048 + k * 1024); } while (0)
; #define PG8_BAR __builtin_amdgcn_s_barrier()
; template <class Epi, class Sched>
; __device__ __forceinline__ void gemm_phase(LAS unsigned char* lds, const Gemm g, const Sched& S, const Epi& E) {
;     ...
;             PG8_LDB(B0, 0, 0); PG8_LDB(B1, 0, 1); PG8_SCHED; PG8_LDA(At, 0, 0); PG8_STAGE(PG8_SA(1, 1), a1 + hstepA, voffA);
;             PG8_WAIT_V(8); PG8_WAIT_L(0); PG8_BAR; PG8_MMA(0, 0, At, B0); PG8_MMA(0, 1, At, B1); PG8_BAR; PG8_SCHED;
;     ...
;             PG8_WAIT_V(8); PG8_WAIT_L(0); PG8_BAR; PG8_MMA(1, 0, At, B0); PG8_MMA(1, 1, At, B1); PG8_BAR; PG8_SCHED;
	s_setprio 1
	s_waitcnt lgkmcnt(0)
	v_mfma_f32_16x16x32_bf16 v[62:65], v[142:145], v[182:185], v[62:65]
	v_mfma_f32_16x16x32_bf16 v[58:61], v[156:159], v[182:185], v[58:61]
	v_mfma_f32_16x16x32_bf16 v[46:49], v[142:145], v[190:193], v[46:49]
	v_mfma_f32_16x16x32_bf16 v[42:45], v[156:159], v[190:193], v[42:45]
	v_mfma_f32_16x16x32_bf16 v[30:33], v[142:145], v[198:201], v[30:33]
	v_mfma_f32_16x16x32_bf16 v[26:29], v[156:159], v[198:201], v[26:29]
	v_mfma_f32_16x16x32_bf16 v[14:17], v[142:145], v[206:209], v[14:17]
	v_mfma_f32_16x16x32_bf16 v[10:13], v[156:159], v[206:209], v[10:13]
	v_mfma_f32_16x16x32_bf16 v[62:65], v[152:155], v[186:189], v[62:65]
	v_mfma_f32_16x16x32_bf16 v[58:61], v[160:163], v[186:189], v[58:61]
	v_mfma_f32_16x16x32_bf16 v[46:49], v[152:155], v[194:197], v[46:49]
	v_mfma_f32_16x16x32_bf16 v[42:45], v[160:163], v[194:197], v[42:45]
	v_mfma_f32_16x16x32_bf16 v[30:33], v[152:155], v[202:205], v[30:33]
	v_mfma_f32_16x16x32_bf16 v[26:29], v[160:163], v[202:205], v[26:29]
	v_mfma_f32_16x16x32_bf16 v[14:17], v[152:155], v[210:213], v[14:17]
	v_mfma_f32_16x16x32_bf16 v[10:13], v[160:163], v[210:213], v[10:13]
	s_setprio 0
	s_setprio 1
	v_mfma_f32_16x16x32_bf16 v[54:57], v[164:167], v[182:185], v[54:57]
	v_mfma_f32_16x16x32_bf16 v[50:53], v[172:175], v[182:185], v[50:53]
	v_mfma_f32_16x16x32_bf16 v[38:41], v[164:167], v[190:193], v[38:41]
	v_mfma_f32_16x16x32_bf16 v[34:37], v[172:175], v[190:193], v[34:37]
	v_mfma_f32_16x16x32_bf16 v[22:25], v[164:167], v[198:201], v[22:25]
	v_mfma_f32_16x16x32_bf16 v[18:21], v[172:175], v[198:201], v[18:21]
	v_mfma_f32_16x16x32_bf16 v[6:9], v[164:167], v[206:209], v[6:9]
	v_mfma_f32_16x16x32_bf16 v[2:5], v[172:175], v[206:209], v[2:5]
	v_mfma_f32_16x16x32_bf16 v[54:57], v[168:171], v[186:189], v[54:57]
	v_mfma_f32_16x16x32_bf16 v[50:53], v[176:179], v[186:189], v[50:53]
	v_mfma_f32_16x16x32_bf16 v[38:41], v[168:171], v[194:197], v[38:41]
	v_mfma_f32_16x16x32_bf16 v[34:37], v[176:179], v[194:197], v[34:37]
	v_mfma_f32_16x16x32_bf16 v[22:25], v[168:171], v[202:205], v[22:25]
	v_mfma_f32_16x16x32_bf16 v[18:21], v[176:179], v[202:205], v[18:21]
	v_mfma_f32_16x16x32_bf16 v[6:9], v[168:171], v[210:213], v[6:9]
	v_mfma_f32_16x16x32_bf16 v[2:5], v[176:179], v[210:213], v[2:5]
	s_setprio 0
	s_barrier
	s_add_i32 s62, s62, 2
	s_add_u32 s57, s57, 0x100
	s_addc_u32 s58, s58, 0
	s_add_u32 s34, s34, 0x100
	s_addc_u32 s35, s35, 0
	s_cmp_gt_u32 s62, 13
	s_cbranch_scc0 .LBB0_1051
	s_branch .Lkend_out
.Lkb_out:
	s_add_u32 s36, s34, 0xfffc0080
	s_addc_u32 s37, s35, -1
	s_add_i32 s66, 0, 0x10000
	s_cmp_eq_u32 s62, 12
	s_cselect_b32 s39, s23, s37
	s_cselect_b32 s38, s29, s36
	v_add_u32_e32 v146, s66, v148
	s_cselect_b32 s37, s21, s58
	s_cselect_b32 s36, s56, s57
	s_add_i32 s70, 0, 0x14000
	ds_read_b128 v[142:145], v146
	ds_read_b128 v[152:155], v146 offset:1024
	ds_read_b128 v[156:159], v146 offset:2048
	ds_read_b128 v[160:163], v146 offset:3072
	v_add_u32_e32 v146, s70, v148
	ds_read_b128 v[164:167], v146
	ds_read_b128 v[168:171], v146 offset:1024
	ds_read_b128 v[172:175], v146 offset:2048
	ds_read_b128 v[176:179], v146 offset:3072
	v_lshl_add_u64 v[146:147], s[34:35], 0, v[140:141]
	s_add_i32 m0, s31, 0xc000
	ds_read_b128 v[182:185], v150
	ds_read_b128 v[186:189], v150 offset:1024
	ds_read_b128 v[190:193], v150 offset:2048
	ds_read_b128 v[194:197], v150 offset:3072
	ds_read_b128 v[198:201], v150 offset:4096
	ds_read_b128 v[202:205], v150 offset:5120
	ds_read_b128 v[206:209], v150 offset:6144
	ds_read_b128 v[210:213], v150 offset:7168
	global_load_lds_dwordx4 v[146:147], off
	v_lshl_add_u64 v[146:147], s[34:35], 0, v[138:139]
	s_add_i32 m0, s31, 0xe000
	s_nop 0
	global_load_lds_dwordx4 v[146:147], off
	s_waitcnt vmcnt(8)
	s_waitcnt lgkmcnt(0)
	s_barrier
	s_setprio 2
	s_waitcnt lgkmcnt(0)
	v_mfma_f32_16x16x32_bf16 v[126:129], v[142:145], v[182:185], v[126:129]
	v_mfma_f32_16x16x32_bf16 v[122:125], v[156:159], v[182:185], v[122:125]
	v_mfma_f32_16x16x32_bf16 v[110:113], v[142:145], v[190:193], v[110:113]
	v_mfma_f32_16x16x32_bf16 v[106:109], v[156:159], v[190:193], v[106:109]
	v_mfma_f32_16x16x32_bf16 v[94:97], v[142:145], v[198:201], v[94:97]
	v_mfma_f32_16x16x32_bf16 v[90:93], v[156:159], v[198:201], v[90:93]
	v_mfma_f32_16x16x32_bf16 v[78:81], v[142:145], v[206:209], v[78:81]
	v_mfma_f32_16x16x32_bf16 v[74:77], v[156:159], v[206:209], v[74:77]
	v_mfma_f32_16x16x32_bf16 v[126:129], v[152:155], v[186:189], v[126:129]
	v_mfma_f32_16x16x32_bf16 v[122:125], v[160:163], v[186:189], v[122:125]
	v_mfma_f32_16x16x32_bf16 v[110:113], v[152:155], v[194:197], v[110:113]
	v_mfma_f32_16x16x32_bf16 v[106:109], v[160:163], v[194:197], v[106:109]
	v_mfma_f32_16x16x32_bf16 v[94:97], v[152:155], v[202:205], v[94:97]
	v_mfma_f32_16x16x32_bf16 v[90:93], v[160:163], v[202:205], v[90:93]
	v_mfma_f32_16x16x32_bf16 v[78:81], v[152:155], v[210:213], v[78:81]
	v_mfma_f32_16x16x32_bf16 v[74:77], v[160:163], v[210:213], v[74:77]
	s_setprio 1
	s_setprio 2
	v_mfma_f32_16x16x32_bf16 v[118:121], v[164:167], v[182:185], v[118:121]
	v_mfma_f32_16x16x32_bf16 v[114:117], v[172:175], v[182:185], v[114:117]
	v_mfma_f32_16x16x32_bf16 v[102:105], v[164:167], v[190:193], v[102:105]
	v_mfma_f32_16x16x32_bf16 v[98:101], v[172:175], v[190:193], v[98:101]
	v_mfma_f32_16x16x32_bf16 v[86:89], v[164:167], v[198:201], v[86:89]
	v_mfma_f32_16x16x32_bf16 v[82:85], v[172:175], v[198:201], v[82:85]
	v_mfma_f32_16x16x32_bf16 v[70:73], v[164:167], v[206:209], v[70:73]
	v_mfma_f32_16x16x32_bf16 v[66:69], v[172:175], v[206:209], v[66:69]
	v_mfma_f32_16x16x32_bf16 v[118:121], v[168:171], v[186:189], v[118:121]
	v_mfma_f32_16x16x32_bf16 v[114:117], v[176:179], v[186:189], v[114:117]
	v_mfma_f32_16x16x32_bf16 v[102:105], v[168:171], v[194:197], v[102:105]
	v_mfma_f32_16x16x32_bf16 v[98:101], v[176:179], v[194:197], v[98:101]
	v_mfma_f32_16x16x32_bf16 v[86:89], v[168:171], v[202:205], v[86:89]
	v_mfma_f32_16x16x32_bf16 v[82:85], v[176:179], v[202:205], v[82:85]
	v_mfma_f32_16x16x32_bf16 v[70:73], v[168:171], v[210:213], v[70:73]
	v_mfma_f32_16x16x32_bf16 v[66:69], v[176:179], v[210:213], v[66:69]
	s_setprio 1
	s_barrier
; #define PG8_STAGE(bufoff, gbase, voff) do { _Pragma("unroll") for (int _i = 0; _i < 2; ++_i) \
;         __builtin_amdgcn_global_load_lds((const unsigned*)((const char*)(gbase) + (voff)[_i]), (LAS unsigned*)(lds + (bufoff) + ldsw + _i * 8192), 16, 0, 0); } while (0)
; #define PG8_LDA(dst, b, h) do { _Pragma("unroll") for (int m = 0; m < 4; ++m) _Pragma("unroll") for (int k = 0; k < 2; ++k) dst[m][k] = *(const LAS bf16x8*)(lds + PG8_SA(b, h) + aoff + m * 2048 + k * 1024); } while (0)
; #define PG8_LDB(dst, b, h) do { _Pragma("unroll") for (int n = 0; n < 2; ++n) _Pragma("unroll") for (int k = 0; k < 2; ++k) dst[n][k] = *(const LAS bf16x8*)(lds + PG8_SB(b, h) + boff + n * 2048 + k * 1024); } while (0)
; #define PG8_MMA(ai, bj, At, Bt) do { __builtin_amdgcn_s_setprio(1); _Pragma("unroll") for (int m = 0; m < 4; ++m) _Pragma("unroll") for (int n = 0; n < 2; ++n) _Pragma("unroll") for (int k = 0; k < 2; ++k) \
;         acc[ai][bj][m][n] = __builtin_amdgcn_mfma_f32_16x16x32_bf16(Bt[n][k], At[m][k], acc[ai][bj][m][n], 0, 0, 0); __builtin_amdgcn_s_setprio(0); } while (0)
; #define PG8_WAIT_V(n) asm volatile("s_waitcnt vmcnt(" #n ")" ::: "memory")
; #define PG8_WAIT_L(n) asm volatile("s_waitcnt lgkmcnt(" #n ")" ::: "memory")
; #define PG8_BAR __builtin_amdgcn_s_barrier()
; #define PG8_SCHED __builtin_amdgcn_sched_barrier(0)
; #define PG8_STAGE(bufoff, gbase, voff) do { _Pragma("unroll") for (int _i = 0; _i < 2; ++_i) \
;         __builtin_amdgcn_global_load_lds((const unsigned*)((const char*)(gbase) + (voff)[_i]), (LAS unsigned*)(lds + (bufoff) + ldsw + _i * 8192), 16, 0, 0); } while (0)
; #define PG8_WAIT_V(n) asm volatile("s_waitcnt vmcnt(" #n ")" ::: "memory")
; #define PG8_BAR __builtin_amdgcn_s_barrier()
; template <class Epi, class Sched>
; __device__ __forceinline__ void gemm_phase(LAS unsigned char* lds, const Gemm g, const Sched& S, const Epi& E) {
;     ...
;             PG8_LDA(At, 0, 1); PG8_STAGE(PG8_SB(0, 0), b2, voffB); PG8_STAGE(PG8_SB(0, 1), b2 + hstepB, voffB); PG8_STAGE(PG8_SA(0, 0), a2, voffA);
;             PG8_WAIT_V(8); PG8_WAIT_L(0); PG8_BAR; PG8_MMA(1, 0, At, B0); PG8_MMA(1, 1, At, B1); PG8_BAR; PG8_SCHED;
;             PG8_LDB(B0, 1, 0); PG8_LDB(B1, 1, 1); PG8_SCHED; PG8_LDA(At, 1, 0); PG8_STAGE(PG8_SA(0, 1), a2 + hstepA, voffA);
;             PG8_WAIT_V(8); PG8_WAIT_L(0); PG8_BAR; PG8_MMA(0, 0, At, B0); PG8_MMA(0, 1, At, B1); PG8_BAR; PG8_SCHED;
	s_add_i32 s66, s66, s44
	v_lshl_add_u64 v[146:147], s[36:37], 0, v[132:133]
	s_mov_b32 m0, s66
	ds_read_b128 v[182:185], v150 offset:16384
	ds_read_b128 v[186:189], v150 offset:17408
	ds_read_b128 v[190:193], v150 offset:18432
	ds_read_b128 v[194:197], v150 offset:19456
	ds_read_b128 v[198:201], v150 offset:20480
	ds_read_b128 v[202:205], v150 offset:21504
	ds_read_b128 v[206:209], v150 offset:22528
	ds_read_b128 v[210:213], v150 offset:23552
	global_load_lds_dwordx4 v[146:147], off
	s_add_i32 m0, s66, 0x2000
	s_add_u32 s66, s36, 0x40000
	v_lshl_add_u64 v[214:215], s[36:37], 0, v[136:137]
	s_addc_u32 s67, s37, 0
	s_add_i32 s70, s70, s44
	global_load_lds_dwordx4 v[214:215], off
	v_lshl_add_u64 v[226:227], s[66:67], 0, v[132:133]
	s_mov_b32 m0, s70
	v_lshl_add_u64 v[228:229], s[38:39], 0, v[134:135]
	global_load_lds_dwordx4 v[226:227], off
	v_lshl_add_u64 v[226:227], s[66:67], 0, v[136:137]
	s_add_i32 m0, s70, 0x2000
	s_nop 0
	global_load_lds_dwordx4 v[226:227], off
	v_lshl_add_u64 v[226:227], s[38:39], 0, v[130:131]
	s_mov_b32 m0, s31
	s_nop 0
	global_load_lds_dwordx4 v[226:227], off
	s_mov_b32 m0, s48
	s_nop 0
	global_load_lds_dwordx4 v[228:229], off
	s_waitcnt vmcnt(8)
	s_waitcnt lgkmcnt(0)
	s_barrier
	s_setprio 2
	s_waitcnt lgkmcnt(0)
	v_mfma_f32_16x16x32_bf16 v[62:65], v[142:145], v[182:185], v[62:65]
	v_mfma_f32_16x16x32_bf16 v[58:61], v[156:159], v[182:185], v[58:61]
	v_mfma_f32_16x16x32_bf16 v[46:49], v[142:145], v[190:193], v[46:49]
	v_mfma_f32_16x16x32_bf16 v[42:45], v[156:159], v[190:193], v[42:45]
	v_mfma_f32_16x16x32_bf16 v[30:33], v[142:145], v[198:201], v[30:33]
	v_mfma_f32_16x16x32_bf16 v[26:29], v[156:159], v[198:201], v[26:29]
	v_mfma_f32_16x16x32_bf16 v[14:17], v[142:145], v[206:209], v[14:17]
	v_mfma_f32_16x16x32_bf16 v[10:13], v[156:159], v[206:209], v[10:13]
	v_mfma_f32_16x16x32_bf16 v[62:65], v[152:155], v[186:189], v[62:65]
	v_mfma_f32_16x16x32_bf16 v[58:61], v[160:163], v[186:189], v[58:61]
	v_mfma_f32_16x16x32_bf16 v[46:49], v[152:155], v[194:197], v[46:49]
	v_mfma_f32_16x16x32_bf16 v[42:45], v[160:163], v[194:197], v[42:45]
	v_mfma_f32_16x16x32_bf16 v[30:33], v[152:155], v[202:205], v[30:33]
	v_mfma_f32_16x16x32_bf16 v[26:29], v[160:163], v[202:205], v[26:29]
	v_mfma_f32_16x16x32_bf16 v[14:17], v[152:155], v[210:213], v[14:17]
	v_mfma_f32_16x16x32_bf16 v[10:13], v[160:163], v[210:213], v[10:13]
	s_setprio 1
	s_setprio 2
	v_mfma_f32_16x16x32_bf16 v[54:57], v[164:167], v[182:185], v[54:57]
	v_mfma_f32_16x16x32_bf16 v[50:53], v[172:175], v[182:185], v[50:53]
	v_mfma_f32_16x16x32_bf16 v[38:41], v[164:167], v[190:193], v[38:41]
	v_mfma_f32_16x16x32_bf16 v[34:37], v[172:175], v[190:193], v[34:37]
	v_mfma_f32_16x16x32_bf16 v[22:25], v[164:167], v[198:201], v[22:25]
	v_mfma_f32_16x16x32_bf16 v[18:21], v[172:175], v[198:201], v[18:21]
	v_mfma_f32_16x16x32_bf16 v[6:9], v[164:167], v[206:209], v[6:9]
	v_mfma_f32_16x16x32_bf16 v[2:5], v[172:175], v[206:209], v[2:5]
	v_mfma_f32_16x16x32_bf16 v[54:57], v[168:171], v[186:189], v[54:57]
	v_mfma_f32_16x16x32_bf16 v[50:53], v[176:179], v[186:189], v[50:53]
	v_mfma_f32_16x16x32_bf16 v[38:41], v[168:171], v[194:197], v[38:41]
	v_mfma_f32_16x16x32_bf16 v[34:37], v[176:179], v[194:197], v[34:37]
	v_mfma_f32_16x16x32_bf16 v[22:25], v[168:171], v[202:205], v[22:25]
	v_mfma_f32_16x16x32_bf16 v[18:21], v[176:179], v[202:205], v[18:21]
	v_mfma_f32_16x16x32_bf16 v[6:9], v[168:171], v[210:213], v[6:9]
	v_mfma_f32_16x16x32_bf16 v[2:5], v[176:179], v[210:213], v[2:5]
	s_setprio 1
	s_barrier
	s_add_i32 s66, 0, 0x18000
	v_add_u32_e32 v151, s66, v148
	s_add_i32 s67, 0, 0x1c000
	ds_read_b128 v[142:145], v151
	ds_read_b128 v[152:155], v151 offset:1024
	ds_read_b128 v[156:159], v151 offset:2048
	ds_read_b128 v[160:163], v151 offset:3072
	v_add_u32_e32 v151, s67, v148
	ds_read_b128 v[164:167], v151
	ds_read_b128 v[168:171], v151 offset:1024
	ds_read_b128 v[172:175], v151 offset:2048
	ds_read_b128 v[176:179], v151 offset:3072
	s_add_u32 s38, s38, 0x40000
	s_addc_u32 s39, s39, 0
	s_mov_b32 m0, s49
	v_lshl_add_u64 v[232:233], s[38:39], 0, v[130:131]
	ds_read_b128 v[182:185], v150 offset:32768
	ds_read_b128 v[186:189], v150 offset:33792
	ds_read_b128 v[190:193], v150 offset:34816
	ds_read_b128 v[194:197], v150 offset:35840
	ds_read_b128 v[198:201], v150 offset:36864
	ds_read_b128 v[202:205], v150 offset:37888
	ds_read_b128 v[206:209], v150 offset:38912
	ds_read_b128 v[210:213], v150 offset:39936
	global_load_lds_dwordx4 v[232:233], off
	v_lshl_add_u64 v[232:233], s[38:39], 0, v[134:135]
	s_mov_b32 m0, s50
	s_nop 0
	global_load_lds_dwordx4 v[232:233], off
	s_waitcnt vmcnt(8)
	s_waitcnt lgkmcnt(0)
	s_barrier
; #define PG8_STAGE(bufoff, gbase, voff) do { _Pragma("unroll") for (int _i = 0; _i < 2; ++_i) \
;         __builtin_amdgcn_global_load_lds((const unsigned*)((const char*)(gbase) + (voff)[_i]), (LAS unsigned*)(lds + (bufoff) + ldsw + _i * 8192), 16, 0, 0); } while (0)
; #define PG8_LDA(dst, b, h) do { _Pragma("unroll") for (int m = 0; m < 4; ++m) _Pragma("unroll") for (int k = 0; k < 2; ++k) dst[m][k] = *(const LAS bf16x8*)(lds + PG8_SA(b, h) + aoff + m * 2048 + k * 1024); } while (0)
; #define PG8_MMA(ai, bj, At, Bt) do { __builtin_amdgcn_s_setprio(1); _Pragma("unroll") for (int m = 0; m < 4; ++m) _Pragma("unroll") for (int n = 0; n < 2; ++n) _Pragma("unroll") for (int k = 0; k < 2; ++k) \
;         acc[ai][bj][m][n] = __builtin_amdgcn_mfma_f32_16x16x32_bf16(Bt[n][k], At[m][k], acc[ai][bj][m][n], 0, 0, 0); __builtin_amdgcn_s_setprio(0); } while (0)
; #define PG8_WAIT_V(n) asm volatile("s_waitcnt vmcnt(" #n ")" ::: "memory")
; #define PG8_WAIT_L(n) asm volatile("s_waitcnt lgkmcnt(" #n ")" ::: "memory")
; #define PG8_BAR __builtin_amdgcn_s_barrier()
; #define PG8_SCHED __builtin_amdgcn_sched_barrier(0)
; #define PG8_STAGE(bufoff, gbase, voff) do { _Pragma("unroll") for (int _i = 0; _i < 2; ++_i) \
;         __builtin_amdgcn_global_load_lds((const unsigned*)((const char*)(gbase) + (voff)[_i]), (LAS unsigned*)(lds + (bufoff) + ldsw + _i * 8192), 16, 0, 0); } while (0)
; #define PG8_LDA(dst, b, h) do { _Pragma("unroll") for (int m = 0; m < 4; ++m) _Pragma("unroll") for (int k = 0; k < 2; ++k) dst[m][k] = *(const LAS bf16x8*)(lds + PG8_SA(b, h) + aoff + m * 2048 + k * 1024); } while (0)
; #define PG8_WAIT_V(n) asm volatile("s_waitcnt vmcnt(" #n ")" ::: "memory")
; #define PG8_WAIT_L(n) asm volatile("s_waitcnt lgkmcnt(" #n ")" ::: "memory")
; #define PG8_BAR __builtin_amdgcn_s_barrier()
; template <class Epi, class Sched>
; __device__ __forceinline__ void gemm_phase(LAS unsigned char* lds, const Gemm g, const Sched& S, const Epi& E) {
;     ...
;             PG8_WAIT_V(8); PG8_WAIT_L(0); PG8_BAR; PG8_MMA(0, 0, At, B0); PG8_MMA(0, 1, At, B1); PG8_BAR; PG8_SCHED;
;             PG8_LDA(At, 1, 1); PG8_STAGE(PG8_SB(1, 0), b3, voffB); PG8_STAGE(PG8_SB(1, 1), b3 + hstepB, voffB); PG8_STAGE(PG8_SA(1, 0), a3, voffA);
;             PG8_WAIT_V(8); PG8_WAIT_L(0); PG8_BAR; PG8_MMA(1, 0, At, B0); PG8_MMA(1, 1, At, B1); PG8_BAR; PG8_SCHED;
;         }
;         if (wr == 0) PG8_BAR;
	s_setprio 2
	s_waitcnt lgkmcnt(0)
	v_mfma_f32_16x16x32_bf16 v[126:129], v[142:145], v[182:185], v[126:129]
	v_mfma_f32_16x16x32_bf16 v[122:125], v[156:159], v[182:185], v[122:125]
	v_mfma_f32_16x16x32_bf16 v[110:113], v[142:145], v[190:193], v[110:113]
	v_mfma_f32_16x16x32_bf16 v[106:109], v[156:159], v[190:193], v[106:109]
	v_mfma_f32_16x16x32_bf16 v[94:97], v[142:145], v[198:201], v[94:97]
	v_mfma_f32_16x16x32_bf16 v[90:93], v[156:159], v[198:201], v[90:93]
	v_mfma_f32_16x16x32_bf16 v[78:81], v[142:145], v[206:209], v[78:81]
	v_mfma_f32_16x16x32_bf16 v[74:77], v[156:159], v[206:209], v[74:77]
	v_mfma_f32_16x16x32_bf16 v[126:129], v[152:155], v[186:189], v[126:129]
	v_mfma_f32_16x16x32_bf16 v[122:125], v[160:163], v[186:189], v[122:125]
	v_mfma_f32_16x16x32_bf16 v[110:113], v[152:155], v[194:197], v[110:113]
	v_mfma_f32_16x16x32_bf16 v[106:109], v[160:163], v[194:197], v[106:109]
	v_mfma_f32_16x16x32_bf16 v[94:97], v[152:155], v[202:205], v[94:97]
	v_mfma_f32_16x16x32_bf16 v[90:93], v[160:163], v[202:205], v[90:93]
	v_mfma_f32_16x16x32_bf16 v[78:81], v[152:155], v[210:213], v[78:81]
	v_mfma_f32_16x16x32_bf16 v[74:77], v[160:163], v[210:213], v[74:77]
	s_setprio 1
	s_setprio 2
	v_mfma_f32_16x16x32_bf16 v[118:121], v[164:167], v[182:185], v[118:121]
	v_mfma_f32_16x16x32_bf16 v[114:117], v[172:175], v[182:185], v[114:117]
	v_mfma_f32_16x16x32_bf16 v[102:105], v[164:167], v[190:193], v[102:105]
	v_mfma_f32_16x16x32_bf16 v[98:101], v[172:175], v[190:193], v[98:101]
	v_mfma_f32_16x16x32_bf16 v[86:89], v[164:167], v[198:201], v[86:89]
	v_mfma_f32_16x16x32_bf16 v[82:85], v[172:175], v[198:201], v[82:85]
	v_mfma_f32_16x16x32_bf16 v[70:73], v[164:167], v[206:209], v[70:73]
	v_mfma_f32_16x16x32_bf16 v[66:69], v[172:175], v[206:209], v[66:69]
	v_mfma_f32_16x16x32_bf16 v[118:121], v[168:171], v[186:189], v[118:121]
	v_mfma_f32_16x16x32_bf16 v[114:117], v[176:179], v[186:189], v[114:117]
	v_mfma_f32_16x16x32_bf16 v[102:105], v[168:171], v[194:197], v[102:105]
	v_mfma_f32_16x16x32_bf16 v[98:101], v[176:179], v[194:197], v[98:101]
	v_mfma_f32_16x16x32_bf16 v[86:89], v[168:171], v[202:205], v[86:89]
	v_mfma_f32_16x16x32_bf16 v[82:85], v[176:179], v[202:205], v[82:85]
	v_mfma_f32_16x16x32_bf16 v[70:73], v[168:171], v[210:213], v[70:73]
	v_mfma_f32_16x16x32_bf16 v[66:69], v[176:179], v[210:213], v[66:69]
	s_setprio 1
	s_barrier
	s_add_i32 s38, s66, s44
	v_lshl_add_u64 v[146:147], v[146:147], 0, s[86:87]
	s_mov_b32 m0, s38
	ds_read_b128 v[182:185], v150 offset:49152
	ds_read_b128 v[186:189], v150 offset:50176
	ds_read_b128 v[190:193], v150 offset:51200
	ds_read_b128 v[194:197], v150 offset:52224
	ds_read_b128 v[198:201], v150 offset:53248
	ds_read_b128 v[202:205], v150 offset:54272
	ds_read_b128 v[206:209], v150 offset:55296
	ds_read_b128 v[210:213], v150 offset:56320
	global_load_lds_dwordx4 v[146:147], off
	s_add_i32 m0, s38, 0x2000
	s_add_u32 s36, s36, 0x40080
	v_lshl_add_u64 v[146:147], v[214:215], 0, s[86:87]
	s_addc_u32 s37, s37, 0
	s_add_i32 s38, s67, s44
	global_load_lds_dwordx4 v[146:147], off
	v_lshl_add_u64 v[146:147], s[36:37], 0, v[132:133]
	s_mov_b32 m0, s38
	s_nop 0
	global_load_lds_dwordx4 v[146:147], off
	v_lshl_add_u64 v[146:147], s[36:37], 0, v[136:137]
	s_add_i32 m0, s38, 0x2000
	s_nop 0
	global_load_lds_dwordx4 v[146:147], off
	v_lshl_add_u64 v[146:147], v[226:227], 0, s[86:87]
	s_mov_b32 m0, s51
	s_nop 0
	global_load_lds_dwordx4 v[146:147], off
	v_lshl_add_u64 v[146:147], v[228:229], 0, s[86:87]
	s_mov_b32 m0, s52
	s_nop 0
	global_load_lds_dwordx4 v[146:147], off
	s_waitcnt vmcnt(8)
	s_waitcnt lgkmcnt(0)
	s_barrier
	s_setprio 2
	s_waitcnt lgkmcnt(0)
	v_mfma_f32_16x16x32_bf16 v[62:65], v[142:145], v[182:185], v[62:65]
	v_mfma_f32_16x16x32_bf16 v[58:61], v[156:159], v[182:185], v[58:61]
	v_mfma_f32_16x16x32_bf16 v[46:49], v[142:145], v[190:193], v[46:49]
	v_mfma_f32_16x16x32_bf16 v[42:45], v[156:159], v[190:193], v[42:45]
	v_mfma_f32_16x16x32_bf16 v[30:33], v[142:145], v[198:201], v[30:33]
	v_mfma_f32_16x16x32_bf16 v[26:29], v[156:159], v[198:201], v[26:29]
	v_mfma_f32_16x16x32_bf16 v[14:17], v[142:145], v[206:209], v[14:17]
	v_mfma_f32_16x16x32_bf16 v[10:13], v[156:159], v[206:209], v[10:13]
	v_mfma_f32_16x16x32_bf16 v[62:65], v[152:155], v[186:189], v[62:65]
	v_mfma_f32_16x16x32_bf16 v[58:61], v[160:163], v[186:189], v[58:61]
	v_mfma_f32_16x16x32_bf16 v[46:49], v[152:155], v[194:197], v[46:49]
	v_mfma_f32_16x16x32_bf16 v[42:45], v[160:163], v[194:197], v[42:45]
	v_mfma_f32_16x16x32_bf16 v[30:33], v[152:155], v[202:205], v[30:33]
	v_mfma_f32_16x16x32_bf16 v[26:29], v[160:163], v[202:205], v[26:29]
	v_mfma_f32_16x16x32_bf16 v[14:17], v[152:155], v[210:213], v[14:17]
	v_mfma_f32_16x16x32_bf16 v[10:13], v[160:163], v[210:213], v[10:13]
	s_setprio 1
	s_setprio 2
	v_mfma_f32_16x16x32_bf16 v[54:57], v[164:167], v[182:185], v[54:57]
	v_mfma_f32_16x16x32_bf16 v[50:53], v[172:175], v[182:185], v[50:53]
	v_mfma_f32_16x16x32_bf16 v[38:41], v[164:167], v[190:193], v[38:41]
	v_mfma_f32_16x16x32_bf16 v[34:37], v[172:175], v[190:193], v[34:37]
	v_mfma_f32_16x16x32_bf16 v[22:25], v[164:167], v[198:201], v[22:25]
	v_mfma_f32_16x16x32_bf16 v[18:21], v[172:175], v[198:201], v[18:21]
	v_mfma_f32_16x16x32_bf16 v[6:9], v[164:167], v[206:209], v[6:9]
	v_mfma_f32_16x16x32_bf16 v[2:5], v[172:175], v[206:209], v[2:5]
	v_mfma_f32_16x16x32_bf16 v[54:57], v[168:171], v[186:189], v[54:57]
	v_mfma_f32_16x16x32_bf16 v[50:53], v[176:179], v[186:189], v[50:53]
	v_mfma_f32_16x16x32_bf16 v[38:41], v[168:171], v[194:197], v[38:41]
	v_mfma_f32_16x16x32_bf16 v[34:37], v[176:179], v[194:197], v[34:37]
	v_mfma_f32_16x16x32_bf16 v[22:25], v[168:171], v[202:205], v[22:25]
	v_mfma_f32_16x16x32_bf16 v[18:21], v[176:179], v[202:205], v[18:21]
	v_mfma_f32_16x16x32_bf16 v[6:9], v[168:171], v[210:213], v[6:9]
	v_mfma_f32_16x16x32_bf16 v[2:5], v[176:179], v[210:213], v[2:5]
	s_setprio 1
	s_barrier
	s_add_i32 s62, s62, 2
	s_add_u32 s57, s57, 0x100
	s_addc_u32 s58, s58, 0
	s_add_u32 s34, s34, 0x100
	s_addc_u32 s35, s35, 0
	s_cmp_gt_u32 s62, 13
	s_cbranch_scc0 .Lkb_out
	s_setprio 0
.Lkend_out:
	s_and_b64 vcc, exec, s[18:19]
	s_cbranch_vccz .LBB0_1054
	s_barrier

; #define PG8_STAGE(bufoff, gbase, voff) do { _Pragma("unroll") for (int _i = 0; _i < 2; ++_i) \
;         __builtin_amdgcn_global_load_lds((const unsigned*)((const char*)(gbase) + (voff)[_i]), (LAS unsigned*)(lds + (bufoff) + ldsw + _i * 8192), 16, 0, 0); } while (0)
; #define PG8_LDA(dst, b, h) do { _Pragma("unroll") for (int m = 0; m < 4; ++m) _Pragma("unroll") for (int k = 0; k < 2; ++k) dst[m][k] = *(const LAS bf16x8*)(lds + PG8_SA(b, h) + aoff + m * 2048 + k * 1024); } while (0)
; #define PG8_LDB(dst, b, h) do { _Pragma("unroll") for (int n = 0; n < 2; ++n) _Pragma("unroll") for (int k = 0; k < 2; ++k) dst[n][k] = *(const LAS bf16x8*)(lds + PG8_SB(b, h) + boff + n * 2048 + k * 1024); } while (0)
; #define PG8_SCHED __builtin_amdgcn_sched_barrier(0)
; #define PG8_STAGE(bufoff, gbase, voff) do { _Pragma("unroll") for (int _i = 0; _i < 2; ++_i) \
;         __builtin_amdgcn_global_load_lds((const unsigned*)((const char*)(gbase) + (voff)[_i]), (LAS unsigned*)(lds + (bufoff) + ldsw + _i * 8192), 16, 0, 0); } while (0)
; #define PG8_LDA(dst, b, h) do { _Pragma("unroll") for (int m = 0; m < 4; ++m) _Pragma("unroll") for (int k = 0; k < 2; ++k) dst[m][k] = *(const LAS bf16x8*)(lds + PG8_SA(b, h) + aoff + m * 2048 + k * 1024); } while (0)
; template <class Epi, class Sched>
; __device__ __forceinline__ void gemm_phase(LAS unsigned char* lds, const Gemm g, const Sched& S, const Epi& E) {
;     ...
;         const bool has_next = S.next(ui + 1, nxt);
;         const char* nA = has_next ? (const char*)g.A + (size_t)nxt.pm * tstepA : cA; const char* nB = has_next ? (const char*)g.Bt + (size_t)nxt.pn * tstepB : cB;
;         for (int t = 0; t < nt; t += 2) {
;             const bool last = (t == nt - 2);
;             const char* a1 = cA + (size_t)(t + 1) * kstep;
;             const char* a2 = last ? nA : cA + (size_t)(t + 2) * kstep; const char* b2 = last ? nB : cB + (size_t)(t + 2) * kstep;
;             const char* a3 = a2 + kstep; const char* b3 = b2 + kstep;
;             PG8_LDB(B0, 0, 0); PG8_LDB(B1, 0, 1); PG8_SCHED; PG8_LDA(At, 0, 0); PG8_STAGE(PG8_SA(1, 1), a1 + hstepA, voffA);
;     ...
; #pragma unroll
;         for (int a = 0; a < 2; ++a)
; #pragma unroll
;             for (int b = 0; b < 2; ++b)
; #pragma unroll
;                 for (int m = 0; m < 4; ++m)
; #pragma unroll
;                     for (int n = 0; n < 2; ++n) acc[a][b][m][n] = (f32x4){0.f, 0.f, 0.f, 0.f};
.LBB0_1130:
	s_ashr_i32 s41, s40, 31
	s_lshl_b64 s[42:43], s[40:41], 19
	s_add_u32 s42, s70, s42
	s_addc_u32 s43, s71, s43
	s_and_b64 s[44:45], s[12:13], exec
	s_cselect_b32 s41, s43, s55
	s_cselect_b32 s49, s42, s54
	s_ashr_i32 s37, s36, 31
	s_lshl_b64 s[44:45], s[36:37], 19
	s_add_u32 s44, s72, s44
	s_addc_u32 s45, s73, s45
	s_and_b64 s[56:57], s[12:13], exec
	s_cselect_b32 s37, s45, s53
	s_cselect_b32 s51, s44, s52
	s_add_u32 s67, s52, 0x100
	s_addc_u32 s76, s53, 0
	s_add_u32 s52, s54, 0x40080
	v_mov_b32_e32 v2, 0
	s_addc_u32 s53, s55, 0
	s_mov_b32 s90, -2
	v_mov_b32_e32 v3, v2
	v_mov_b32_e32 v4, v2
	v_mov_b32_e32 v5, v2
	v_mov_b32_e32 v66, v2
	v_mov_b32_e32 v67, v2
	v_mov_b32_e32 v68, v2
	v_mov_b32_e32 v69, v2
	v_mov_b32_e32 v10, v2
	v_mov_b32_e32 v11, v2
	v_mov_b32_e32 v12, v2
	v_mov_b32_e32 v13, v2
	v_mov_b32_e32 v74, v2
	v_mov_b32_e32 v75, v2
	v_mov_b32_e32 v76, v2
	v_mov_b32_e32 v77, v2
	v_mov_b32_e32 v18, v2
	v_mov_b32_e32 v19, v2
	v_mov_b32_e32 v20, v2
	v_mov_b32_e32 v21, v2
	v_mov_b32_e32 v82, v2
	v_mov_b32_e32 v83, v2
	v_mov_b32_e32 v84, v2
	v_mov_b32_e32 v85, v2
	v_mov_b32_e32 v26, v2
	v_mov_b32_e32 v27, v2
	v_mov_b32_e32 v28, v2
	v_mov_b32_e32 v29, v2
	v_mov_b32_e32 v90, v2
	v_mov_b32_e32 v91, v2
	v_mov_b32_e32 v92, v2
	v_mov_b32_e32 v93, v2
	v_mov_b32_e32 v6, v2
	v_mov_b32_e32 v7, v2
	v_mov_b32_e32 v8, v2
	v_mov_b32_e32 v9, v2
	v_mov_b32_e32 v70, v2
	v_mov_b32_e32 v71, v2
	v_mov_b32_e32 v72, v2
	v_mov_b32_e32 v73, v2
	v_mov_b32_e32 v14, v2
	v_mov_b32_e32 v15, v2
	v_mov_b32_e32 v16, v2
	v_mov_b32_e32 v17, v2
	v_mov_b32_e32 v78, v2
	v_mov_b32_e32 v79, v2
	v_mov_b32_e32 v80, v2
	v_mov_b32_e32 v81, v2
	v_mov_b32_e32 v22, v2
	v_mov_b32_e32 v23, v2
	v_mov_b32_e32 v24, v2
	v_mov_b32_e32 v25, v2
	v_mov_b32_e32 v86, v2
	v_mov_b32_e32 v87, v2
	v_mov_b32_e32 v88, v2
	v_mov_b32_e32 v89, v2
	v_mov_b32_e32 v30, v2
	v_mov_b32_e32 v31, v2
	v_mov_b32_e32 v32, v2
	v_mov_b32_e32 v33, v2
	v_mov_b32_e32 v94, v2
	v_mov_b32_e32 v95, v2
	v_mov_b32_e32 v96, v2
	v_mov_b32_e32 v97, v2
	v_mov_b32_e32 v34, v2
	v_mov_b32_e32 v35, v2
	v_mov_b32_e32 v36, v2
	v_mov_b32_e32 v37, v2
	v_mov_b32_e32 v98, v2
	v_mov_b32_e32 v99, v2
	v_mov_b32_e32 v100, v2
	v_mov_b32_e32 v101, v2
	v_mov_b32_e32 v42, v2
	v_mov_b32_e32 v43, v2
	v_mov_b32_e32 v44, v2
	v_mov_b32_e32 v45, v2
	v_mov_b32_e32 v106, v2
	v_mov_b32_e32 v107, v2
	v_mov_b32_e32 v108, v2
	v_mov_b32_e32 v109, v2
	v_mov_b32_e32 v50, v2
	v_mov_b32_e32 v51, v2
	v_mov_b32_e32 v52, v2
	v_mov_b32_e32 v53, v2
	v_mov_b32_e32 v146, v2
	v_mov_b32_e32 v147, v2
	v_mov_b32_e32 v148, v2
	v_mov_b32_e32 v149, v2
	v_mov_b32_e32 v58, v2
	v_mov_b32_e32 v59, v2
	v_mov_b32_e32 v60, v2
	v_mov_b32_e32 v61, v2
	v_mov_b32_e32 v154, v2
	v_mov_b32_e32 v155, v2
	v_mov_b32_e32 v156, v2
	v_mov_b32_e32 v157, v2
	v_mov_b32_e32 v38, v2
	v_mov_b32_e32 v39, v2
	v_mov_b32_e32 v40, v2
	v_mov_b32_e32 v41, v2
	v_mov_b32_e32 v102, v2
	v_mov_b32_e32 v103, v2
	v_mov_b32_e32 v104, v2
	v_mov_b32_e32 v105, v2
	v_mov_b32_e32 v46, v2
	v_mov_b32_e32 v47, v2
	v_mov_b32_e32 v48, v2
	v_mov_b32_e32 v49, v2
	v_mov_b32_e32 v110, v2
	v_mov_b32_e32 v111, v2
	v_mov_b32_e32 v112, v2
	v_mov_b32_e32 v113, v2
	v_mov_b32_e32 v54, v2
	v_mov_b32_e32 v55, v2
	v_mov_b32_e32 v56, v2
	v_mov_b32_e32 v57, v2
	v_mov_b32_e32 v150, v2
	v_mov_b32_e32 v151, v2
	v_mov_b32_e32 v152, v2
	v_mov_b32_e32 v153, v2
	v_mov_b32_e32 v62, v2
	v_mov_b32_e32 v63, v2
	v_mov_b32_e32 v64, v2
	v_mov_b32_e32 v65, v2
	v_mov_b32_e32 v158, v2
	v_mov_b32_e32 v159, v2
	v_mov_b32_e32 v160, v2
	v_mov_b32_e32 v161, v2
	s_cmp_lg_u64 s[4:5], 0
	s_cbranch_scc1 .Lkb_ffnup
.LBB0_1131:
	s_add_u32 s54, s52, 0xfffc0080
	s_addc_u32 s55, s53, -1
	s_add_i32 s91, 0, 0x10000
	s_cmp_eq_u32 s90, 12
	s_cselect_b32 s57, s41, s55
	s_cselect_b32 s56, s49, s54
	s_cselect_b32 s55, s37, s76
	s_cselect_b32 s54, s51, s67
	s_add_i32 s94, 0, 0x14000
	v_add_u32_e32 v126, s91, v231
	v_add_u32_e32 v142, s94, v231
	ds_read_b128 v[114:117], v126
	ds_read_b128 v[118:121], v126 offset:1024
	ds_read_b128 v[122:125], v126 offset:2048
	ds_read_b128 v[126:129], v126 offset:3072
	ds_read_b128 v[130:133], v142
	ds_read_b128 v[134:137], v142 offset:1024
	ds_read_b128 v[138:141], v142 offset:2048
	ds_read_b128 v[142:145], v142 offset:3072
	v_lshl_add_u64 v[210:211], s[52:53], 0, v[174:175]
	s_add_i32 m0, s78, 0xc000
	ds_read_b128 v[176:179], v233
	ds_read_b128 v[182:185], v233 offset:1024
	ds_read_b128 v[186:189], v233 offset:2048
	ds_read_b128 v[190:193], v233 offset:3072
	ds_read_b128 v[194:197], v233 offset:4096
	ds_read_b128 v[198:201], v233 offset:5120
	ds_read_b128 v[202:205], v233 offset:6144
	ds_read_b128 v[206:209], v233 offset:7168
	global_load_lds_dwordx4 v[210:211], off
	v_lshl_add_u64 v[210:211], s[52:53], 0, v[172:173]
	s_add_i32 m0, s78, 0xe000
	s_nop 0
	global_load_lds_dwordx4 v[210:211], off
	s_waitcnt vmcnt(8)
	s_waitcnt lgkmcnt(0)
	s_barrier
; #define PG8_STAGE(bufoff, gbase, voff) do { _Pragma("unroll") for (int _i = 0; _i < 2; ++_i) \
;         __builtin_amdgcn_global_load_lds((const unsigned*)((const char*)(gbase) + (voff)[_i]), (LAS unsigned*)(lds + (bufoff) + ldsw + _i * 8192), 16, 0, 0); } while (0)
; #define PG8_LDA(dst, b, h) do { _Pragma("unroll") for (int m = 0; m < 4; ++m) _Pragma("unroll") for (int k = 0; k < 2; ++k) dst[m][k] = *(const LAS bf16x8*)(lds + PG8_SA(b, h) + aoff + m * 2048 + k * 1024); } while (0)
; #define PG8_MMA(ai, bj, At, Bt) do { __builtin_amdgcn_s_setprio(1); _Pragma("unroll") for (int m = 0; m < 4; ++m) _Pragma("unroll") for (int n = 0; n < 2; ++n) _Pragma("unroll") for (int k = 0; k < 2; ++k) \
;         acc[ai][bj][m][n] = __builtin_amdgcn_mfma_f32_16x16x32_bf16(Bt[n][k], At[m][k], acc[ai][bj][m][n], 0, 0, 0); __builtin_amdgcn_s_setprio(0); } while (0)
; #define PG8_WAIT_V(n) asm volatile("s_waitcnt vmcnt(" #n ")" ::: "memory")
; #define PG8_WAIT_L(n) asm volatile("s_waitcnt lgkmcnt(" #n ")" ::: "memory")
; #define PG8_BAR __builtin_amdgcn_s_barrier()
; #define PG8_SCHED __builtin_amdgcn_sched_barrier(0)
; #define PG8_STAGE(bufoff, gbase, voff) do { _Pragma("unroll") for (int _i = 0; _i < 2; ++_i) \
;         __builtin_amdgcn_global_load_lds((const unsigned*)((const char*)(gbase) + (voff)[_i]), (LAS unsigned*)(lds + (bufoff) + ldsw + _i * 8192), 16, 0, 0); } while (0)
; #define PG8_LDA(dst, b, h) do { _Pragma("unroll") for (int m = 0; m < 4; ++m) _Pragma("unroll") for (int k = 0; k < 2; ++k) dst[m][k] = *(const LAS bf16x8*)(lds + PG8_SA(b, h) + aoff + m * 2048 + k * 1024); } while (0)
; #define PG8_WAIT_V(n) asm volatile("s_waitcnt vmcnt(" #n ")" ::: "memory")
; #define PG8_WAIT_L(n) asm volatile("s_waitcnt lgkmcnt(" #n ")" ::: "memory")
; #define PG8_BAR __builtin_amdgcn_s_barrier()
; template <class Epi, class Sched>
; __device__ __forceinline__ void gemm_phase(LAS unsigned char* lds, const Gemm g, const Sched& S, const Epi& E) {
;     ...
;             PG8_WAIT_V(8); PG8_WAIT_L(0); PG8_BAR; PG8_MMA(0, 0, At, B0); PG8_MMA(0, 1, At, B1); PG8_BAR; PG8_SCHED;
;             PG8_LDA(At, 0, 1); PG8_STAGE(PG8_SB(0, 0), b2, voffB); PG8_STAGE(PG8_SB(0, 1), b2 + hstepB, voffB); PG8_STAGE(PG8_SA(0, 0), a2, voffA);
;             PG8_WAIT_V(8); PG8_WAIT_L(0); PG8_BAR; PG8_MMA(1, 0, At, B0); PG8_MMA(1, 1, At, B1); PG8_BAR; PG8_SCHED;
	s_setprio 1
	s_waitcnt lgkmcnt(0)
	v_mfma_f32_16x16x32_bf16 v[158:161], v[114:117], v[176:179], v[158:161]
	v_mfma_f32_16x16x32_bf16 v[62:65], v[122:125], v[176:179], v[62:65]
	v_mfma_f32_16x16x32_bf16 v[150:153], v[114:117], v[186:189], v[150:153]
	v_mfma_f32_16x16x32_bf16 v[54:57], v[122:125], v[186:189], v[54:57]
	v_mfma_f32_16x16x32_bf16 v[110:113], v[114:117], v[194:197], v[110:113]
	v_mfma_f32_16x16x32_bf16 v[46:49], v[122:125], v[194:197], v[46:49]
	v_mfma_f32_16x16x32_bf16 v[102:105], v[114:117], v[202:205], v[102:105]
	v_mfma_f32_16x16x32_bf16 v[38:41], v[122:125], v[202:205], v[38:41]
	v_mfma_f32_16x16x32_bf16 v[158:161], v[118:121], v[182:185], v[158:161]
	v_mfma_f32_16x16x32_bf16 v[62:65], v[126:129], v[182:185], v[62:65]
	v_mfma_f32_16x16x32_bf16 v[150:153], v[118:121], v[190:193], v[150:153]
	v_mfma_f32_16x16x32_bf16 v[54:57], v[126:129], v[190:193], v[54:57]
	v_mfma_f32_16x16x32_bf16 v[110:113], v[118:121], v[198:201], v[110:113]
	v_mfma_f32_16x16x32_bf16 v[46:49], v[126:129], v[198:201], v[46:49]
	v_mfma_f32_16x16x32_bf16 v[102:105], v[118:121], v[206:209], v[102:105]
	v_mfma_f32_16x16x32_bf16 v[38:41], v[126:129], v[206:209], v[38:41]
	s_setprio 0
	s_setprio 1
	v_mfma_f32_16x16x32_bf16 v[154:157], v[130:133], v[176:179], v[154:157]
	v_mfma_f32_16x16x32_bf16 v[58:61], v[138:141], v[176:179], v[58:61]
	v_mfma_f32_16x16x32_bf16 v[146:149], v[130:133], v[186:189], v[146:149]
	v_mfma_f32_16x16x32_bf16 v[50:53], v[138:141], v[186:189], v[50:53]
	v_mfma_f32_16x16x32_bf16 v[106:109], v[130:133], v[194:197], v[106:109]
	v_mfma_f32_16x16x32_bf16 v[42:45], v[138:141], v[194:197], v[42:45]
	v_mfma_f32_16x16x32_bf16 v[98:101], v[130:133], v[202:205], v[98:101]
	v_mfma_f32_16x16x32_bf16 v[34:37], v[138:141], v[202:205], v[34:37]
	v_mfma_f32_16x16x32_bf16 v[154:157], v[134:137], v[182:185], v[154:157]
	v_mfma_f32_16x16x32_bf16 v[58:61], v[142:145], v[182:185], v[58:61]
	v_mfma_f32_16x16x32_bf16 v[146:149], v[134:137], v[190:193], v[146:149]
	v_mfma_f32_16x16x32_bf16 v[50:53], v[142:145], v[190:193], v[50:53]
	v_mfma_f32_16x16x32_bf16 v[106:109], v[134:137], v[198:201], v[106:109]
	v_mfma_f32_16x16x32_bf16 v[42:45], v[142:145], v[198:201], v[42:45]
	v_mfma_f32_16x16x32_bf16 v[98:101], v[134:137], v[206:209], v[98:101]
	v_mfma_f32_16x16x32_bf16 v[34:37], v[142:145], v[206:209], v[34:37]
	s_setprio 0
	s_barrier
	s_add_i32 s91, s91, s75
	v_lshl_add_u64 v[210:211], s[54:55], 0, v[164:165]
	s_mov_b32 m0, s91
	ds_read_b128 v[176:179], v233 offset:16384
	ds_read_b128 v[182:185], v233 offset:17408
	ds_read_b128 v[186:189], v233 offset:18432
	ds_read_b128 v[190:193], v233 offset:19456
	ds_read_b128 v[194:197], v233 offset:20480
	ds_read_b128 v[198:201], v233 offset:21504
	ds_read_b128 v[202:205], v233 offset:22528
	ds_read_b128 v[206:209], v233 offset:23552
	global_load_lds_dwordx4 v[210:211], off
	s_add_i32 m0, s91, 0x2000
	s_add_u32 s92, s54, 0x40000
	v_lshl_add_u64 v[212:213], s[54:55], 0, v[168:169]
	s_addc_u32 s93, s55, 0
	s_add_i32 s91, s94, s75
	global_load_lds_dwordx4 v[212:213], off
	v_lshl_add_u64 v[214:215], s[92:93], 0, v[164:165]
	s_mov_b32 m0, s91
	v_lshl_add_u64 v[226:227], s[56:57], 0, v[166:167]
	global_load_lds_dwordx4 v[214:215], off
	v_lshl_add_u64 v[214:215], s[92:93], 0, v[168:169]
	s_add_i32 m0, s91, 0x2000
	s_nop 0
	global_load_lds_dwordx4 v[214:215], off
	v_lshl_add_u64 v[214:215], s[56:57], 0, v[162:163]
	s_mov_b32 m0, s78
	s_nop 0
	global_load_lds_dwordx4 v[214:215], off
	s_mov_b32 m0, s80
	s_nop 0
	global_load_lds_dwordx4 v[226:227], off
	s_waitcnt vmcnt(8)
	s_waitcnt lgkmcnt(0)
	s_barrier
	s_setprio 1
	s_waitcnt lgkmcnt(0)
	v_mfma_f32_16x16x32_bf16 v[94:97], v[114:117], v[176:179], v[94:97]
	v_mfma_f32_16x16x32_bf16 v[30:33], v[122:125], v[176:179], v[30:33]
	v_mfma_f32_16x16x32_bf16 v[86:89], v[114:117], v[186:189], v[86:89]
	v_mfma_f32_16x16x32_bf16 v[22:25], v[122:125], v[186:189], v[22:25]
	v_mfma_f32_16x16x32_bf16 v[78:81], v[114:117], v[194:197], v[78:81]
	v_mfma_f32_16x16x32_bf16 v[14:17], v[122:125], v[194:197], v[14:17]
	v_mfma_f32_16x16x32_bf16 v[70:73], v[114:117], v[202:205], v[70:73]
	v_mfma_f32_16x16x32_bf16 v[6:9], v[122:125], v[202:205], v[6:9]
	v_mfma_f32_16x16x32_bf16 v[94:97], v[118:121], v[182:185], v[94:97]
	v_mfma_f32_16x16x32_bf16 v[30:33], v[126:129], v[182:185], v[30:33]
	v_mfma_f32_16x16x32_bf16 v[86:89], v[118:121], v[190:193], v[86:89]
	v_mfma_f32_16x16x32_bf16 v[22:25], v[126:129], v[190:193], v[22:25]
	v_mfma_f32_16x16x32_bf16 v[78:81], v[118:121], v[198:201], v[78:81]
	v_mfma_f32_16x16x32_bf16 v[14:17], v[126:129], v[198:201], v[14:17]
	v_mfma_f32_16x16x32_bf16 v[70:73], v[118:121], v[206:209], v[70:73]
	v_mfma_f32_16x16x32_bf16 v[6:9], v[126:129], v[206:209], v[6:9]
	s_setprio 0
	s_setprio 1
	v_mfma_f32_16x16x32_bf16 v[90:93], v[130:133], v[176:179], v[90:93]
	v_mfma_f32_16x16x32_bf16 v[26:29], v[138:141], v[176:179], v[26:29]
	v_mfma_f32_16x16x32_bf16 v[82:85], v[130:133], v[186:189], v[82:85]
	v_mfma_f32_16x16x32_bf16 v[18:21], v[138:141], v[186:189], v[18:21]
	v_mfma_f32_16x16x32_bf16 v[74:77], v[130:133], v[194:197], v[74:77]
	v_mfma_f32_16x16x32_bf16 v[10:13], v[138:141], v[194:197], v[10:13]
	v_mfma_f32_16x16x32_bf16 v[66:69], v[130:133], v[202:205], v[66:69]
	v_mfma_f32_16x16x32_bf16 v[2:5], v[138:141], v[202:205], v[2:5]
	v_mfma_f32_16x16x32_bf16 v[90:93], v[134:137], v[182:185], v[90:93]
	v_mfma_f32_16x16x32_bf16 v[26:29], v[142:145], v[182:185], v[26:29]
	v_mfma_f32_16x16x32_bf16 v[82:85], v[134:137], v[190:193], v[82:85]
	v_mfma_f32_16x16x32_bf16 v[18:21], v[142:145], v[190:193], v[18:21]
	v_mfma_f32_16x16x32_bf16 v[74:77], v[134:137], v[198:201], v[74:77]
	v_mfma_f32_16x16x32_bf16 v[10:13], v[142:145], v[198:201], v[10:13]
	v_mfma_f32_16x16x32_bf16 v[66:69], v[134:137], v[206:209], v[66:69]
	v_mfma_f32_16x16x32_bf16 v[2:5], v[142:145], v[206:209], v[2:5]
	s_setprio 0
	s_barrier
; #define PG8_STAGE(bufoff, gbase, voff) do { _Pragma("unroll") for (int _i = 0; _i < 2; ++_i) \
;         __builtin_amdgcn_global_load_lds((const unsigned*)((const char*)(gbase) + (voff)[_i]), (LAS unsigned*)(lds + (bufoff) + ldsw + _i * 8192), 16, 0, 0); } while (0)
; #define PG8_LDA(dst, b, h) do { _Pragma("unroll") for (int m = 0; m < 4; ++m) _Pragma("unroll") for (int k = 0; k < 2; ++k) dst[m][k] = *(const LAS bf16x8*)(lds + PG8_SA(b, h) + aoff + m * 2048 + k * 1024); } while (0)
; #define PG8_LDB(dst, b, h) do { _Pragma("unroll") for (int n = 0; n < 2; ++n) _Pragma("unroll") for (int k = 0; k < 2; ++k) dst[n][k] = *(const LAS bf16x8*)(lds + PG8_SB(b, h) + boff + n * 2048 + k * 1024); } while (0)
; #define PG8_MMA(ai, bj, At, Bt) do { __builtin_amdgcn_s_setprio(1); _Pragma("unroll") for (int m = 0; m < 4; ++m) _Pragma("unroll") for (int n = 0; n < 2; ++n) _Pragma("unroll") for (int k = 0; k < 2; ++k) \
;         acc[ai][bj][m][n] = __builtin_amdgcn_mfma_f32_16x16x32_bf16(Bt[n][k], At[m][k], acc[ai][bj][m][n], 0, 0, 0); __builtin_amdgcn_s_setprio(0); } while (0)
; #define PG8_WAIT_V(n) asm volatile("s_waitcnt vmcnt(" #n ")" ::: "memory")
; #define PG8_WAIT_L(n) asm volatile("s_waitcnt lgkmcnt(" #n ")" ::: "memory")
; #define PG8_BAR __builtin_amdgcn_s_barrier()
; #define PG8_SCHED __builtin_amdgcn_sched_barrier(0)
; #define PG8_STAGE(bufoff, gbase, voff) do { _Pragma("unroll") for (int _i = 0; _i < 2; ++_i) \
;         __builtin_amdgcn_global_load_lds((const unsigned*)((const char*)(gbase) + (voff)[_i]), (LAS unsigned*)(lds + (bufoff) + ldsw + _i * 8192), 16, 0, 0); } while (0)
; #define PG8_LDA(dst, b, h) do { _Pragma("unroll") for (int m = 0; m < 4; ++m) _Pragma("unroll") for (int k = 0; k < 2; ++k) dst[m][k] = *(const LAS bf16x8*)(lds + PG8_SA(b, h) + aoff + m * 2048 + k * 1024); } while (0)
; template <class Epi, class Sched>
; __device__ __forceinline__ void gemm_phase(LAS unsigned char* lds, const Gemm g, const Sched& S, const Epi& E) {
;     ...
;             PG8_LDB(B0, 1, 0); PG8_LDB(B1, 1, 1); PG8_SCHED; PG8_LDA(At, 1, 0); PG8_STAGE(PG8_SA(0, 1), a2 + hstepA, voffA);
;             PG8_WAIT_V(8); PG8_WAIT_L(0); PG8_BAR; PG8_MMA(0, 0, At, B0); PG8_MMA(0, 1, At, B1); PG8_BAR; PG8_SCHED;
;             PG8_LDA(At, 1, 1); PG8_STAGE(PG8_SB(1, 0), b3, voffB); PG8_STAGE(PG8_SB(1, 1), b3 + hstepB, voffB); PG8_STAGE(PG8_SA(1, 0), a3, voffA);
	s_add_i32 s91, 0, 0x18000
	s_add_i32 s92, 0, 0x1c000
	v_add_u32_e32 v126, s91, v231
	v_add_u32_e32 v142, s92, v231
	ds_read_b128 v[114:117], v126
	ds_read_b128 v[118:121], v126 offset:1024
	ds_read_b128 v[122:125], v126 offset:2048
	ds_read_b128 v[126:129], v126 offset:3072
	ds_read_b128 v[130:133], v142
	ds_read_b128 v[134:137], v142 offset:1024
	ds_read_b128 v[138:141], v142 offset:2048
	ds_read_b128 v[142:145], v142 offset:3072
	s_add_u32 s56, s56, 0x40000
	s_addc_u32 s57, s57, 0
	s_mov_b32 m0, s81
	v_lshl_add_u64 v[228:229], s[56:57], 0, v[162:163]
	ds_read_b128 v[176:179], v233 offset:32768
	ds_read_b128 v[182:185], v233 offset:33792
	ds_read_b128 v[186:189], v233 offset:34816
	ds_read_b128 v[190:193], v233 offset:35840
	ds_read_b128 v[194:197], v233 offset:36864
	ds_read_b128 v[198:201], v233 offset:37888
	ds_read_b128 v[202:205], v233 offset:38912
	ds_read_b128 v[206:209], v233 offset:39936
	global_load_lds_dwordx4 v[228:229], off
	v_lshl_add_u64 v[228:229], s[56:57], 0, v[166:167]
	s_mov_b32 m0, s82
	s_nop 0
	global_load_lds_dwordx4 v[228:229], off
	s_waitcnt vmcnt(8)
	s_waitcnt lgkmcnt(0)
	s_barrier
	s_setprio 1
	s_waitcnt lgkmcnt(0)
	v_mfma_f32_16x16x32_bf16 v[158:161], v[114:117], v[176:179], v[158:161]
	v_mfma_f32_16x16x32_bf16 v[62:65], v[122:125], v[176:179], v[62:65]
	v_mfma_f32_16x16x32_bf16 v[150:153], v[114:117], v[186:189], v[150:153]
	v_mfma_f32_16x16x32_bf16 v[54:57], v[122:125], v[186:189], v[54:57]
	v_mfma_f32_16x16x32_bf16 v[110:113], v[114:117], v[194:197], v[110:113]
	v_mfma_f32_16x16x32_bf16 v[46:49], v[122:125], v[194:197], v[46:49]
	v_mfma_f32_16x16x32_bf16 v[102:105], v[114:117], v[202:205], v[102:105]
	v_mfma_f32_16x16x32_bf16 v[38:41], v[122:125], v[202:205], v[38:41]
	v_mfma_f32_16x16x32_bf16 v[158:161], v[118:121], v[182:185], v[158:161]
	v_mfma_f32_16x16x32_bf16 v[62:65], v[126:129], v[182:185], v[62:65]
	v_mfma_f32_16x16x32_bf16 v[150:153], v[118:121], v[190:193], v[150:153]
	v_mfma_f32_16x16x32_bf16 v[54:57], v[126:129], v[190:193], v[54:57]
	v_mfma_f32_16x16x32_bf16 v[110:113], v[118:121], v[198:201], v[110:113]
	v_mfma_f32_16x16x32_bf16 v[46:49], v[126:129], v[198:201], v[46:49]
	v_mfma_f32_16x16x32_bf16 v[102:105], v[118:121], v[206:209], v[102:105]
	v_mfma_f32_16x16x32_bf16 v[38:41], v[126:129], v[206:209], v[38:41]
	s_setprio 0
	s_setprio 1
	v_mfma_f32_16x16x32_bf16 v[154:157], v[130:133], v[176:179], v[154:157]
	v_mfma_f32_16x16x32_bf16 v[58:61], v[138:141], v[176:179], v[58:61]
	v_mfma_f32_16x16x32_bf16 v[146:149], v[130:133], v[186:189], v[146:149]
	v_mfma_f32_16x16x32_bf16 v[50:53], v[138:141], v[186:189], v[50:53]
	v_mfma_f32_16x16x32_bf16 v[106:109], v[130:133], v[194:197], v[106:109]
	v_mfma_f32_16x16x32_bf16 v[42:45], v[138:141], v[194:197], v[42:45]
	v_mfma_f32_16x16x32_bf16 v[98:101], v[130:133], v[202:205], v[98:101]
	v_mfma_f32_16x16x32_bf16 v[34:37], v[138:141], v[202:205], v[34:37]
	v_mfma_f32_16x16x32_bf16 v[154:157], v[134:137], v[182:185], v[154:157]
	v_mfma_f32_16x16x32_bf16 v[58:61], v[142:145], v[182:185], v[58:61]
	v_mfma_f32_16x16x32_bf16 v[146:149], v[134:137], v[190:193], v[146:149]
	v_mfma_f32_16x16x32_bf16 v[50:53], v[142:145], v[190:193], v[50:53]
	v_mfma_f32_16x16x32_bf16 v[106:109], v[134:137], v[198:201], v[106:109]
	v_mfma_f32_16x16x32_bf16 v[42:45], v[142:145], v[198:201], v[42:45]
	v_mfma_f32_16x16x32_bf16 v[98:101], v[134:137], v[206:209], v[98:101]
	v_mfma_f32_16x16x32_bf16 v[34:37], v[142:145], v[206:209], v[34:37]
	s_setprio 0
	s_barrier
	s_add_i32 s56, s91, s75
	v_lshl_add_u64 v[210:211], v[210:211], 0, s[86:87]
	s_mov_b32 m0, s56
	ds_read_b128 v[176:179], v233 offset:49152
	ds_read_b128 v[182:185], v233 offset:50176
	ds_read_b128 v[186:189], v233 offset:51200
	ds_read_b128 v[190:193], v233 offset:52224
	ds_read_b128 v[194:197], v233 offset:53248
	ds_read_b128 v[198:201], v233 offset:54272
	ds_read_b128 v[202:205], v233 offset:55296
	ds_read_b128 v[206:209], v233 offset:56320
	global_load_lds_dwordx4 v[210:211], off
	s_add_i32 m0, s56, 0x2000
	s_add_u32 s54, s54, 0x40080
	v_lshl_add_u64 v[210:211], v[212:213], 0, s[86:87]
	s_addc_u32 s55, s55, 0
	s_add_i32 s56, s92, s75
	global_load_lds_dwordx4 v[210:211], off
	v_lshl_add_u64 v[210:211], s[54:55], 0, v[164:165]
	s_mov_b32 m0, s56
	s_nop 0
	global_load_lds_dwordx4 v[210:211], off
	v_lshl_add_u64 v[210:211], s[54:55], 0, v[168:169]
	s_add_i32 m0, s56, 0x2000
	s_nop 0
	global_load_lds_dwordx4 v[210:211], off
	v_lshl_add_u64 v[210:211], v[214:215], 0, s[86:87]
	s_mov_b32 m0, s83
	s_nop 0
	global_load_lds_dwordx4 v[210:211], off
	v_lshl_add_u64 v[210:211], v[226:227], 0, s[86:87]
	s_mov_b32 m0, s84
	s_nop 0
	global_load_lds_dwordx4 v[210:211], off
	s_waitcnt vmcnt(8)
	s_waitcnt lgkmcnt(0)
	s_barrier
; #define PG8_STAGE(bufoff, gbase, voff) do { _Pragma("unroll") for (int _i = 0; _i < 2; ++_i) \
;         __builtin_amdgcn_global_load_lds((const unsigned*)((const char*)(gbase) + (voff)[_i]), (LAS unsigned*)(lds + (bufoff) + ldsw + _i * 8192), 16, 0, 0); } while (0)
; #define PG8_LDA(dst, b, h) do { _Pragma("unroll") for (int m = 0; m < 4; ++m) _Pragma("unroll") for (int k = 0; k < 2; ++k) dst[m][k] = *(const LAS bf16x8*)(lds + PG8_SA(b, h) + aoff + m * 2048 + k * 1024); } while (0)
; #define PG8_LDB(dst, b, h) do { _Pragma("unroll") for (int n = 0; n < 2; ++n) _Pragma("unroll") for (int k = 0; k < 2; ++k) dst[n][k] = *(const LAS bf16x8*)(lds + PG8_SB(b, h) + boff + n * 2048 + k * 1024); } while (0)
; #define PG8_WAIT_V(n) asm volatile("s_waitcnt vmcnt(" #n ")" ::: "memory")
; #define PG8_BAR __builtin_amdgcn_s_barrier()
; template <class Epi, class Sched>
; __device__ __forceinline__ void gemm_phase(LAS unsigned char* lds, const Gemm g, const Sched& S, const Epi& E) {
;     ...
;         for (int t = 0; t < nt; t += 2) {
;             const bool last = (t == nt - 2);
;             const char* a1 = cA + (size_t)(t + 1) * kstep;
;             const char* a2 = last ? nA : cA + (size_t)(t + 2) * kstep; const char* b2 = last ? nB : cB + (size_t)(t + 2) * kstep;
;             const char* a3 = a2 + kstep; const char* b3 = b2 + kstep;
;             PG8_LDB(B0, 0, 0); PG8_LDB(B1, 0, 1); PG8_SCHED; PG8_LDA(At, 0, 0); PG8_STAGE(PG8_SA(1, 1), a1 + hstepA, voffA);
;             PG8_WAIT_V(8); PG8_WAIT_L(0); PG8_BAR; PG8_MMA(0, 0, At, B0); PG8_MMA(0, 1, At, B1); PG8_BAR; PG8_SCHED;
;             PG8_LDA(At, 0, 1); PG8_STAGE(PG8_SB(0, 0), b2, voffB); PG8_STAGE(PG8_SB(0, 1), b2 + hstepB, voffB); PG8_STAGE(PG8_SA(0, 0), a2, voffA);
;             PG8_WAIT_V(8); PG8_WAIT_L(0); PG8_BAR; PG8_MMA(1, 0, At, B0); PG8_MMA(1, 1, At, B1); PG8_BAR; PG8_SCHED;
;             PG8_LDB(B0, 1, 0); PG8_LDB(B1, 1, 1); PG8_SCHED; PG8_LDA(At, 1, 0); PG8_STAGE(PG8_SA(0, 1), a2 + hstepA, voffA);
;             PG8_WAIT_V(8); PG8_WAIT_L(0); PG8_BAR; PG8_MMA(0, 0, At, B0); PG8_MMA(0, 1, At, B1); PG8_BAR; PG8_SCHED;
;             PG8_LDA(At, 1, 1); PG8_STAGE(PG8_SB(1, 0), b3, voffB); PG8_STAGE(PG8_SB(1, 1), b3 + hstepB, voffB); PG8_STAGE(PG8_SA(1, 0), a3, voffA);
;             PG8_WAIT_V(8); PG8_WAIT_L(0); PG8_BAR; PG8_MMA(1, 0, At, B0); PG8_MMA(1, 1, At, B1); PG8_BAR; PG8_SCHED;
	s_setprio 1
	s_waitcnt lgkmcnt(0)
	v_mfma_f32_16x16x32_bf16 v[94:97], v[114:117], v[176:179], v[94:97]
	v_mfma_f32_16x16x32_bf16 v[30:33], v[122:125], v[176:179], v[30:33]
	v_mfma_f32_16x16x32_bf16 v[86:89], v[114:117], v[186:189], v[86:89]
	v_mfma_f32_16x16x32_bf16 v[22:25], v[122:125], v[186:189], v[22:25]
	v_mfma_f32_16x16x32_bf16 v[78:81], v[114:117], v[194:197], v[78:81]
	v_mfma_f32_16x16x32_bf16 v[14:17], v[122:125], v[194:197], v[14:17]
	v_mfma_f32_16x16x32_bf16 v[70:73], v[114:117], v[202:205], v[70:73]
	v_mfma_f32_16x16x32_bf16 v[6:9], v[122:125], v[202:205], v[6:9]
	v_mfma_f32_16x16x32_bf16 v[94:97], v[118:121], v[182:185], v[94:97]
	v_mfma_f32_16x16x32_bf16 v[30:33], v[126:129], v[182:185], v[30:33]
	v_mfma_f32_16x16x32_bf16 v[86:89], v[118:121], v[190:193], v[86:89]
	v_mfma_f32_16x16x32_bf16 v[22:25], v[126:129], v[190:193], v[22:25]
	v_mfma_f32_16x16x32_bf16 v[78:81], v[118:121], v[198:201], v[78:81]
	v_mfma_f32_16x16x32_bf16 v[14:17], v[126:129], v[198:201], v[14:17]
	v_mfma_f32_16x16x32_bf16 v[70:73], v[118:121], v[206:209], v[70:73]
	v_mfma_f32_16x16x32_bf16 v[6:9], v[126:129], v[206:209], v[6:9]
	s_setprio 0
	s_setprio 1
	v_mfma_f32_16x16x32_bf16 v[90:93], v[130:133], v[176:179], v[90:93]
	v_mfma_f32_16x16x32_bf16 v[26:29], v[138:141], v[176:179], v[26:29]
	v_mfma_f32_16x16x32_bf16 v[82:85], v[130:133], v[186:189], v[82:85]
	v_mfma_f32_16x16x32_bf16 v[18:21], v[138:141], v[186:189], v[18:21]
	v_mfma_f32_16x16x32_bf16 v[74:77], v[130:133], v[194:197], v[74:77]
	v_mfma_f32_16x16x32_bf16 v[10:13], v[138:141], v[194:197], v[10:13]
	v_mfma_f32_16x16x32_bf16 v[66:69], v[130:133], v[202:205], v[66:69]
	v_mfma_f32_16x16x32_bf16 v[2:5], v[138:141], v[202:205], v[2:5]
	v_mfma_f32_16x16x32_bf16 v[90:93], v[134:137], v[182:185], v[90:93]
	v_mfma_f32_16x16x32_bf16 v[26:29], v[142:145], v[182:185], v[26:29]
	v_mfma_f32_16x16x32_bf16 v[82:85], v[134:137], v[190:193], v[82:85]
	v_mfma_f32_16x16x32_bf16 v[18:21], v[142:145], v[190:193], v[18:21]
	v_mfma_f32_16x16x32_bf16 v[74:77], v[134:137], v[198:201], v[74:77]
	v_mfma_f32_16x16x32_bf16 v[10:13], v[142:145], v[198:201], v[10:13]
	v_mfma_f32_16x16x32_bf16 v[66:69], v[134:137], v[206:209], v[66:69]
	v_mfma_f32_16x16x32_bf16 v[2:5], v[142:145], v[206:209], v[2:5]
	s_setprio 0
	s_barrier
	s_add_i32 s90, s90, 2
	s_add_u32 s67, s67, 0x100
	s_addc_u32 s76, s76, 0
	s_add_u32 s52, s52, 0x100
	s_addc_u32 s53, s53, 0
	s_cmp_gt_u32 s90, 13
	s_cbranch_scc0 .LBB0_1131
	s_branch .Lkend_ffnup
.Lkb_ffnup:
	s_add_u32 s54, s52, 0xfffc0080
	s_addc_u32 s55, s53, -1
	s_add_i32 s91, 0, 0x10000
	s_cmp_eq_u32 s90, 12
	s_cselect_b32 s57, s41, s55
	s_cselect_b32 s56, s49, s54
	s_cselect_b32 s55, s37, s76
	s_cselect_b32 s54, s51, s67
	s_add_i32 s94, 0, 0x14000
	v_add_u32_e32 v126, s91, v231
	v_add_u32_e32 v142, s94, v231
	ds_read_b128 v[114:117], v126
	ds_read_b128 v[118:121], v126 offset:1024
	ds_read_b128 v[122:125], v126 offset:2048
	ds_read_b128 v[126:129], v126 offset:3072
	ds_read_b128 v[130:133], v142
	ds_read_b128 v[134:137], v142 offset:1024
	ds_read_b128 v[138:141], v142 offset:2048
	ds_read_b128 v[142:145], v142 offset:3072
	v_lshl_add_u64 v[210:211], s[52:53], 0, v[174:175]
	s_add_i32 m0, s78, 0xc000
	ds_read_b128 v[176:179], v233
	ds_read_b128 v[182:185], v233 offset:1024
	ds_read_b128 v[186:189], v233 offset:2048
	ds_read_b128 v[190:193], v233 offset:3072
	ds_read_b128 v[194:197], v233 offset:4096
	ds_read_b128 v[198:201], v233 offset:5120
	ds_read_b128 v[202:205], v233 offset:6144
	ds_read_b128 v[206:209], v233 offset:7168
	global_load_lds_dwordx4 v[210:211], off
	v_lshl_add_u64 v[210:211], s[52:53], 0, v[172:173]
	s_add_i32 m0, s78, 0xe000
	s_nop 0
	global_load_lds_dwordx4 v[210:211], off
	s_waitcnt vmcnt(8)
	s_waitcnt lgkmcnt(0)
	s_barrier
	s_setprio 2
	s_waitcnt lgkmcnt(0)
	v_mfma_f32_16x16x32_bf16 v[158:161], v[114:117], v[176:179], v[158:161]
	v_mfma_f32_16x16x32_bf16 v[62:65], v[122:125], v[176:179], v[62:65]
	v_mfma_f32_16x16x32_bf16 v[150:153], v[114:117], v[186:189], v[150:153]
	v_mfma_f32_16x16x32_bf16 v[54:57], v[122:125], v[186:189], v[54:57]
	v_mfma_f32_16x16x32_bf16 v[110:113], v[114:117], v[194:197], v[110:113]
	v_mfma_f32_16x16x32_bf16 v[46:49], v[122:125], v[194:197], v[46:49]
	v_mfma_f32_16x16x32_bf16 v[102:105], v[114:117], v[202:205], v[102:105]
	v_mfma_f32_16x16x32_bf16 v[38:41], v[122:125], v[202:205], v[38:41]
	v_mfma_f32_16x16x32_bf16 v[158:161], v[118:121], v[182:185], v[158:161]
	v_mfma_f32_16x16x32_bf16 v[62:65], v[126:129], v[182:185], v[62:65]
	v_mfma_f32_16x16x32_bf16 v[150:153], v[118:121], v[190:193], v[150:153]
	v_mfma_f32_16x16x32_bf16 v[54:57], v[126:129], v[190:193], v[54:57]
	v_mfma_f32_16x16x32_bf16 v[110:113], v[118:121], v[198:201], v[110:113]
	v_mfma_f32_16x16x32_bf16 v[46:49], v[126:129], v[198:201], v[46:49]
	v_mfma_f32_16x16x32_bf16 v[102:105], v[118:121], v[206:209], v[102:105]
	v_mfma_f32_16x16x32_bf16 v[38:41], v[126:129], v[206:209], v[38:41]
	s_setprio 1
	s_setprio 2
	v_mfma_f32_16x16x32_bf16 v[154:157], v[130:133], v[176:179], v[154:157]
	v_mfma_f32_16x16x32_bf16 v[58:61], v[138:141], v[176:179], v[58:61]
	v_mfma_f32_16x16x32_bf16 v[146:149], v[130:133], v[186:189], v[146:149]
	v_mfma_f32_16x16x32_bf16 v[50:53], v[138:141], v[186:189], v[50:53]
	v_mfma_f32_16x16x32_bf16 v[106:109], v[130:133], v[194:197], v[106:109]
	v_mfma_f32_16x16x32_bf16 v[42:45], v[138:141], v[194:197], v[42:45]
	v_mfma_f32_16x16x32_bf16 v[98:101], v[130:133], v[202:205], v[98:101]
	v_mfma_f32_16x16x32_bf16 v[34:37], v[138:141], v[202:205], v[34:37]
	v_mfma_f32_16x16x32_bf16 v[154:157], v[134:137], v[182:185], v[154:157]
	v_mfma_f32_16x16x32_bf16 v[58:61], v[142:145], v[182:185], v[58:61]
	v_mfma_f32_16x16x32_bf16 v[146:149], v[134:137], v[190:193], v[146:149]
	v_mfma_f32_16x16x32_bf16 v[50:53], v[142:145], v[190:193], v[50:53]
	v_mfma_f32_16x16x32_bf16 v[106:109], v[134:137], v[198:201], v[106:109]
	v_mfma_f32_16x16x32_bf16 v[42:45], v[142:145], v[198:201], v[42:45]
	v_mfma_f32_16x16x32_bf16 v[98:101], v[134:137], v[206:209], v[98:101]
	v_mfma_f32_16x16x32_bf16 v[34:37], v[142:145], v[206:209], v[34:37]
	s_setprio 1
	s_barrier
; #define PG8_STAGE(bufoff, gbase, voff) do { _Pragma("unroll") for (int _i = 0; _i < 2; ++_i) \
;         __builtin_amdgcn_global_load_lds((const unsigned*)((const char*)(gbase) + (voff)[_i]), (LAS unsigned*)(lds + (bufoff) + ldsw + _i * 8192), 16, 0, 0); } while (0)
; #define PG8_LDA(dst, b, h) do { _Pragma("unroll") for (int m = 0; m < 4; ++m) _Pragma("unroll") for (int k = 0; k < 2; ++k) dst[m][k] = *(const LAS bf16x8*)(lds + PG8_SA(b, h) + aoff + m * 2048 + k * 1024); } while (0)
; #define PG8_LDB(dst, b, h) do { _Pragma("unroll") for (int n = 0; n < 2; ++n) _Pragma("unroll") for (int k = 0; k < 2; ++k) dst[n][k] = *(const LAS bf16x8*)(lds + PG8_SB(b, h) + boff + n * 2048 + k * 1024); } while (0)
; #define PG8_MMA(ai, bj, At, Bt) do { __builtin_amdgcn_s_setprio(1); _Pragma("unroll") for (int m = 0; m < 4; ++m) _Pragma("unroll") for (int n = 0; n < 2; ++n) _Pragma("unroll") for (int k = 0; k < 2; ++k) \
;         acc[ai][bj][m][n] = __builtin_amdgcn_mfma_f32_16x16x32_bf16(Bt[n][k], At[m][k], acc[ai][bj][m][n], 0, 0, 0); __builtin_amdgcn_s_setprio(0); } while (0)
; #define PG8_WAIT_V(n) asm volatile("s_waitcnt vmcnt(" #n ")" ::: "memory")
; #define PG8_WAIT_L(n) asm volatile("s_waitcnt lgkmcnt(" #n ")" ::: "memory")
; #define PG8_BAR __builtin_amdgcn_s_barrier()
; #define PG8_SCHED __builtin_amdgcn_sched_barrier(0)
; #define PG8_LDA(dst, b, h) do { _Pragma("unroll") for (int m = 0; m < 4; ++m) _Pragma("unroll") for (int k = 0; k < 2; ++k) dst[m][k] = *(const LAS bf16x8*)(lds + PG8_SA(b, h) + aoff + m * 2048 + k * 1024); } while (0)
; template <class Epi, class Sched>
; __device__ __forceinline__ void gemm_phase(LAS unsigned char* lds, const Gemm g, const Sched& S, const Epi& E) {
;     ...
;             PG8_LDA(At, 0, 1); PG8_STAGE(PG8_SB(0, 0), b2, voffB); PG8_STAGE(PG8_SB(0, 1), b2 + hstepB, voffB); PG8_STAGE(PG8_SA(0, 0), a2, voffA);
;             PG8_WAIT_V(8); PG8_WAIT_L(0); PG8_BAR; PG8_MMA(1, 0, At, B0); PG8_MMA(1, 1, At, B1); PG8_BAR; PG8_SCHED;
;             PG8_LDB(B0, 1, 0); PG8_LDB(B1, 1, 1); PG8_SCHED; PG8_LDA(At, 1, 0); PG8_STAGE(PG8_SA(0, 1), a2 + hstepA, voffA);
;             PG8_WAIT_V(8); PG8_WAIT_L(0); PG8_BAR; PG8_MMA(0, 0, At, B0); PG8_MMA(0, 1, At, B1); PG8_BAR; PG8_SCHED;
;             PG8_LDA(At, 1, 1); PG8_STAGE(PG8_SB(1, 0), b3, voffB); PG8_STAGE(PG8_SB(1, 1), b3 + hstepB, voffB); PG8_STAGE(PG8_SA(1, 0), a3, voffA);
	s_add_i32 s91, s91, s75
	v_lshl_add_u64 v[210:211], s[54:55], 0, v[164:165]
	s_mov_b32 m0, s91
	ds_read_b128 v[176:179], v233 offset:16384
	ds_read_b128 v[182:185], v233 offset:17408
	ds_read_b128 v[186:189], v233 offset:18432
	ds_read_b128 v[190:193], v233 offset:19456
	ds_read_b128 v[194:197], v233 offset:20480
	ds_read_b128 v[198:201], v233 offset:21504
	ds_read_b128 v[202:205], v233 offset:22528
	ds_read_b128 v[206:209], v233 offset:23552
	global_load_lds_dwordx4 v[210:211], off
	s_add_i32 m0, s91, 0x2000
	s_add_u32 s92, s54, 0x40000
	v_lshl_add_u64 v[212:213], s[54:55], 0, v[168:169]
	s_addc_u32 s93, s55, 0
	s_add_i32 s91, s94, s75
	global_load_lds_dwordx4 v[212:213], off
	v_lshl_add_u64 v[214:215], s[92:93], 0, v[164:165]
	s_mov_b32 m0, s91
	v_lshl_add_u64 v[226:227], s[56:57], 0, v[166:167]
	global_load_lds_dwordx4 v[214:215], off
	v_lshl_add_u64 v[214:215], s[92:93], 0, v[168:169]
	s_add_i32 m0, s91, 0x2000
	s_nop 0
	global_load_lds_dwordx4 v[214:215], off
	v_lshl_add_u64 v[214:215], s[56:57], 0, v[162:163]
	s_mov_b32 m0, s78
	s_nop 0
	global_load_lds_dwordx4 v[214:215], off
	s_mov_b32 m0, s80
	s_nop 0
	global_load_lds_dwordx4 v[226:227], off
	s_waitcnt vmcnt(8)
	s_waitcnt lgkmcnt(0)
	s_barrier
	s_setprio 2
	s_waitcnt lgkmcnt(0)
	v_mfma_f32_16x16x32_bf16 v[94:97], v[114:117], v[176:179], v[94:97]
	v_mfma_f32_16x16x32_bf16 v[30:33], v[122:125], v[176:179], v[30:33]
	v_mfma_f32_16x16x32_bf16 v[86:89], v[114:117], v[186:189], v[86:89]
	v_mfma_f32_16x16x32_bf16 v[22:25], v[122:125], v[186:189], v[22:25]
	v_mfma_f32_16x16x32_bf16 v[78:81], v[114:117], v[194:197], v[78:81]
	v_mfma_f32_16x16x32_bf16 v[14:17], v[122:125], v[194:197], v[14:17]
	v_mfma_f32_16x16x32_bf16 v[70:73], v[114:117], v[202:205], v[70:73]
	v_mfma_f32_16x16x32_bf16 v[6:9], v[122:125], v[202:205], v[6:9]
	v_mfma_f32_16x16x32_bf16 v[94:97], v[118:121], v[182:185], v[94:97]
	v_mfma_f32_16x16x32_bf16 v[30:33], v[126:129], v[182:185], v[30:33]
	v_mfma_f32_16x16x32_bf16 v[86:89], v[118:121], v[190:193], v[86:89]
	v_mfma_f32_16x16x32_bf16 v[22:25], v[126:129], v[190:193], v[22:25]
	v_mfma_f32_16x16x32_bf16 v[78:81], v[118:121], v[198:201], v[78:81]
	v_mfma_f32_16x16x32_bf16 v[14:17], v[126:129], v[198:201], v[14:17]
	v_mfma_f32_16x16x32_bf16 v[70:73], v[118:121], v[206:209], v[70:73]
	v_mfma_f32_16x16x32_bf16 v[6:9], v[126:129], v[206:209], v[6:9]
	s_setprio 1
	s_setprio 2
	v_mfma_f32_16x16x32_bf16 v[90:93], v[130:133], v[176:179], v[90:93]
	v_mfma_f32_16x16x32_bf16 v[26:29], v[138:141], v[176:179], v[26:29]
	v_mfma_f32_16x16x32_bf16 v[82:85], v[130:133], v[186:189], v[82:85]
	v_mfma_f32_16x16x32_bf16 v[18:21], v[138:141], v[186:189], v[18:21]
	v_mfma_f32_16x16x32_bf16 v[74:77], v[130:133], v[194:197], v[74:77]
	v_mfma_f32_16x16x32_bf16 v[10:13], v[138:141], v[194:197], v[10:13]
	v_mfma_f32_16x16x32_bf16 v[66:69], v[130:133], v[202:205], v[66:69]
	v_mfma_f32_16x16x32_bf16 v[2:5], v[138:141], v[202:205], v[2:5]
	v_mfma_f32_16x16x32_bf16 v[90:93], v[134:137], v[182:185], v[90:93]
	v_mfma_f32_16x16x32_bf16 v[26:29], v[142:145], v[182:185], v[26:29]
	v_mfma_f32_16x16x32_bf16 v[82:85], v[134:137], v[190:193], v[82:85]
	v_mfma_f32_16x16x32_bf16 v[18:21], v[142:145], v[190:193], v[18:21]
	v_mfma_f32_16x16x32_bf16 v[74:77], v[134:137], v[198:201], v[74:77]
	v_mfma_f32_16x16x32_bf16 v[10:13], v[142:145], v[198:201], v[10:13]
	v_mfma_f32_16x16x32_bf16 v[66:69], v[134:137], v[206:209], v[66:69]
	v_mfma_f32_16x16x32_bf16 v[2:5], v[142:145], v[206:209], v[2:5]
	s_setprio 1
	s_barrier
	s_add_i32 s91, 0, 0x18000
	s_add_i32 s92, 0, 0x1c000
	v_add_u32_e32 v126, s91, v231
	v_add_u32_e32 v142, s92, v231
	ds_read_b128 v[114:117], v126
	ds_read_b128 v[118:121], v126 offset:1024
	ds_read_b128 v[122:125], v126 offset:2048
	ds_read_b128 v[126:129], v126 offset:3072
	ds_read_b128 v[130:133], v142
	ds_read_b128 v[134:137], v142 offset:1024
	ds_read_b128 v[138:141], v142 offset:2048
	ds_read_b128 v[142:145], v142 offset:3072
	s_add_u32 s56, s56, 0x40000
	s_addc_u32 s57, s57, 0
	s_mov_b32 m0, s81
	v_lshl_add_u64 v[228:229], s[56:57], 0, v[162:163]
	ds_read_b128 v[176:179], v233 offset:32768
	ds_read_b128 v[182:185], v233 offset:33792
	ds_read_b128 v[186:189], v233 offset:34816
	ds_read_b128 v[190:193], v233 offset:35840
	ds_read_b128 v[194:197], v233 offset:36864
	ds_read_b128 v[198:201], v233 offset:37888
	ds_read_b128 v[202:205], v233 offset:38912
	ds_read_b128 v[206:209], v233 offset:39936
	global_load_lds_dwordx4 v[228:229], off
	v_lshl_add_u64 v[228:229], s[56:57], 0, v[166:167]
	s_mov_b32 m0, s82
	s_nop 0
	global_load_lds_dwordx4 v[228:229], off
	s_waitcnt vmcnt(8)
	s_waitcnt lgkmcnt(0)
	s_barrier
; #define PG8_STAGE(bufoff, gbase, voff) do { _Pragma("unroll") for (int _i = 0; _i < 2; ++_i) \
;         __builtin_amdgcn_global_load_lds((const unsigned*)((const char*)(gbase) + (voff)[_i]), (LAS unsigned*)(lds + (bufoff) + ldsw + _i * 8192), 16, 0, 0); } while (0)
; #define PG8_LDA(dst, b, h) do { _Pragma("unroll") for (int m = 0; m < 4; ++m) _Pragma("unroll") for (int k = 0; k < 2; ++k) dst[m][k] = *(const LAS bf16x8*)(lds + PG8_SA(b, h) + aoff + m * 2048 + k * 1024); } while (0)
; #define PG8_MMA(ai, bj, At, Bt) do { __builtin_amdgcn_s_setprio(1); _Pragma("unroll") for (int m = 0; m < 4; ++m) _Pragma("unroll") for (int n = 0; n < 2; ++n) _Pragma("unroll") for (int k = 0; k < 2; ++k) \
;         acc[ai][bj][m][n] = __builtin_amdgcn_mfma_f32_16x16x32_bf16(Bt[n][k], At[m][k], acc[ai][bj][m][n], 0, 0, 0); __builtin_amdgcn_s_setprio(0); } while (0)
; #define PG8_WAIT_V(n) asm volatile("s_waitcnt vmcnt(" #n ")" ::: "memory")
; #define PG8_WAIT_L(n) asm volatile("s_waitcnt lgkmcnt(" #n ")" ::: "memory")
; #define PG8_BAR __builtin_amdgcn_s_barrier()
; #define PG8_SCHED __builtin_amdgcn_sched_barrier(0)
; #define PG8_STAGE(bufoff, gbase, voff) do { _Pragma("unroll") for (int _i = 0; _i < 2; ++_i) \
;         __builtin_amdgcn_global_load_lds((const unsigned*)((const char*)(gbase) + (voff)[_i]), (LAS unsigned*)(lds + (bufoff) + ldsw + _i * 8192), 16, 0, 0); } while (0)
; #define PG8_LDA(dst, b, h) do { _Pragma("unroll") for (int m = 0; m < 4; ++m) _Pragma("unroll") for (int k = 0; k < 2; ++k) dst[m][k] = *(const LAS bf16x8*)(lds + PG8_SA(b, h) + aoff + m * 2048 + k * 1024); } while (0)
; #define PG8_WAIT_V(n) asm volatile("s_waitcnt vmcnt(" #n ")" ::: "memory")
; #define PG8_WAIT_L(n) asm volatile("s_waitcnt lgkmcnt(" #n ")" ::: "memory")
; #define PG8_BAR __builtin_amdgcn_s_barrier()
; template <class Epi, class Sched>
; __device__ __forceinline__ void gemm_phase(LAS unsigned char* lds, const Gemm g, const Sched& S, const Epi& E) {
;     ...
;             PG8_WAIT_V(8); PG8_WAIT_L(0); PG8_BAR; PG8_MMA(0, 0, At, B0); PG8_MMA(0, 1, At, B1); PG8_BAR; PG8_SCHED;
;             PG8_LDA(At, 1, 1); PG8_STAGE(PG8_SB(1, 0), b3, voffB); PG8_STAGE(PG8_SB(1, 1), b3 + hstepB, voffB); PG8_STAGE(PG8_SA(1, 0), a3, voffA);
;             PG8_WAIT_V(8); PG8_WAIT_L(0); PG8_BAR; PG8_MMA(1, 0, At, B0); PG8_MMA(1, 1, At, B1); PG8_BAR; PG8_SCHED;
;         }
;         if (wr == 0) PG8_BAR;
	s_setprio 2
	s_waitcnt lgkmcnt(0)
	v_mfma_f32_16x16x32_bf16 v[158:161], v[114:117], v[176:179], v[158:161]
	v_mfma_f32_16x16x32_bf16 v[62:65], v[122:125], v[176:179], v[62:65]
	v_mfma_f32_16x16x32_bf16 v[150:153], v[114:117], v[186:189], v[150:153]
	v_mfma_f32_16x16x32_bf16 v[54:57], v[122:125], v[186:189], v[54:57]
	v_mfma_f32_16x16x32_bf16 v[110:113], v[114:117], v[194:197], v[110:113]
	v_mfma_f32_16x16x32_bf16 v[46:49], v[122:125], v[194:197], v[46:49]
	v_mfma_f32_16x16x32_bf16 v[102:105], v[114:117], v[202:205], v[102:105]
	v_mfma_f32_16x16x32_bf16 v[38:41], v[122:125], v[202:205], v[38:41]
	v_mfma_f32_16x16x32_bf16 v[158:161], v[118:121], v[182:185], v[158:161]
	v_mfma_f32_16x16x32_bf16 v[62:65], v[126:129], v[182:185], v[62:65]
	v_mfma_f32_16x16x32_bf16 v[150:153], v[118:121], v[190:193], v[150:153]
	v_mfma_f32_16x16x32_bf16 v[54:57], v[126:129], v[190:193], v[54:57]
	v_mfma_f32_16x16x32_bf16 v[110:113], v[118:121], v[198:201], v[110:113]
	v_mfma_f32_16x16x32_bf16 v[46:49], v[126:129], v[198:201], v[46:49]
	v_mfma_f32_16x16x32_bf16 v[102:105], v[118:121], v[206:209], v[102:105]
	v_mfma_f32_16x16x32_bf16 v[38:41], v[126:129], v[206:209], v[38:41]
	s_setprio 1
	s_setprio 2
	v_mfma_f32_16x16x32_bf16 v[154:157], v[130:133], v[176:179], v[154:157]
	v_mfma_f32_16x16x32_bf16 v[58:61], v[138:141], v[176:179], v[58:61]
	v_mfma_f32_16x16x32_bf16 v[146:149], v[130:133], v[186:189], v[146:149]
	v_mfma_f32_16x16x32_bf16 v[50:53], v[138:141], v[186:189], v[50:53]
	v_mfma_f32_16x16x32_bf16 v[106:109], v[130:133], v[194:197], v[106:109]
	v_mfma_f32_16x16x32_bf16 v[42:45], v[138:141], v[194:197], v[42:45]
	v_mfma_f32_16x16x32_bf16 v[98:101], v[130:133], v[202:205], v[98:101]
	v_mfma_f32_16x16x32_bf16 v[34:37], v[138:141], v[202:205], v[34:37]
	v_mfma_f32_16x16x32_bf16 v[154:157], v[134:137], v[182:185], v[154:157]
	v_mfma_f32_16x16x32_bf16 v[58:61], v[142:145], v[182:185], v[58:61]
	v_mfma_f32_16x16x32_bf16 v[146:149], v[134:137], v[190:193], v[146:149]
	v_mfma_f32_16x16x32_bf16 v[50:53], v[142:145], v[190:193], v[50:53]
	v_mfma_f32_16x16x32_bf16 v[106:109], v[134:137], v[198:201], v[106:109]
	v_mfma_f32_16x16x32_bf16 v[42:45], v[142:145], v[198:201], v[42:45]
	v_mfma_f32_16x16x32_bf16 v[98:101], v[134:137], v[206:209], v[98:101]
	v_mfma_f32_16x16x32_bf16 v[34:37], v[142:145], v[206:209], v[34:37]
	s_setprio 1
	s_barrier
	s_add_i32 s56, s91, s75
	v_lshl_add_u64 v[210:211], v[210:211], 0, s[86:87]
	s_mov_b32 m0, s56
	ds_read_b128 v[176:179], v233 offset:49152
	ds_read_b128 v[182:185], v233 offset:50176
	ds_read_b128 v[186:189], v233 offset:51200
	ds_read_b128 v[190:193], v233 offset:52224
	ds_read_b128 v[194:197], v233 offset:53248
	ds_read_b128 v[198:201], v233 offset:54272
	ds_read_b128 v[202:205], v233 offset:55296
	ds_read_b128 v[206:209], v233 offset:56320
	global_load_lds_dwordx4 v[210:211], off
	s_add_i32 m0, s56, 0x2000
	s_add_u32 s54, s54, 0x40080
	v_lshl_add_u64 v[210:211], v[212:213], 0, s[86:87]
	s_addc_u32 s55, s55, 0
	s_add_i32 s56, s92, s75
	global_load_lds_dwordx4 v[210:211], off
	v_lshl_add_u64 v[210:211], s[54:55], 0, v[164:165]
	s_mov_b32 m0, s56
	s_nop 0
	global_load_lds_dwordx4 v[210:211], off
	v_lshl_add_u64 v[210:211], s[54:55], 0, v[168:169]
	s_add_i32 m0, s56, 0x2000
	s_nop 0
	global_load_lds_dwordx4 v[210:211], off
	v_lshl_add_u64 v[210:211], v[214:215], 0, s[86:87]
	s_mov_b32 m0, s83
	s_nop 0
	global_load_lds_dwordx4 v[210:211], off
	v_lshl_add_u64 v[210:211], v[226:227], 0, s[86:87]
	s_mov_b32 m0, s84
	s_nop 0
	global_load_lds_dwordx4 v[210:211], off
	s_waitcnt vmcnt(8)
	s_waitcnt lgkmcnt(0)
	s_barrier
	s_setprio 2
	s_waitcnt lgkmcnt(0)
	v_mfma_f32_16x16x32_bf16 v[94:97], v[114:117], v[176:179], v[94:97]
	v_mfma_f32_16x16x32_bf16 v[30:33], v[122:125], v[176:179], v[30:33]
	v_mfma_f32_16x16x32_bf16 v[86:89], v[114:117], v[186:189], v[86:89]
	v_mfma_f32_16x16x32_bf16 v[22:25], v[122:125], v[186:189], v[22:25]
	v_mfma_f32_16x16x32_bf16 v[78:81], v[114:117], v[194:197], v[78:81]
	v_mfma_f32_16x16x32_bf16 v[14:17], v[122:125], v[194:197], v[14:17]
	v_mfma_f32_16x16x32_bf16 v[70:73], v[114:117], v[202:205], v[70:73]
	v_mfma_f32_16x16x32_bf16 v[6:9], v[122:125], v[202:205], v[6:9]
	v_mfma_f32_16x16x32_bf16 v[94:97], v[118:121], v[182:185], v[94:97]
	v_mfma_f32_16x16x32_bf16 v[30:33], v[126:129], v[182:185], v[30:33]
	v_mfma_f32_16x16x32_bf16 v[86:89], v[118:121], v[190:193], v[86:89]
	v_mfma_f32_16x16x32_bf16 v[22:25], v[126:129], v[190:193], v[22:25]
	v_mfma_f32_16x16x32_bf16 v[78:81], v[118:121], v[198:201], v[78:81]
	v_mfma_f32_16x16x32_bf16 v[14:17], v[126:129], v[198:201], v[14:17]
	v_mfma_f32_16x16x32_bf16 v[70:73], v[118:121], v[206:209], v[70:73]
	v_mfma_f32_16x16x32_bf16 v[6:9], v[126:129], v[206:209], v[6:9]
	s_setprio 1
	s_setprio 2
	v_mfma_f32_16x16x32_bf16 v[90:93], v[130:133], v[176:179], v[90:93]
	v_mfma_f32_16x16x32_bf16 v[26:29], v[138:141], v[176:179], v[26:29]
	v_mfma_f32_16x16x32_bf16 v[82:85], v[130:133], v[186:189], v[82:85]
	v_mfma_f32_16x16x32_bf16 v[18:21], v[138:141], v[186:189], v[18:21]
	v_mfma_f32_16x16x32_bf16 v[74:77], v[130:133], v[194:197], v[74:77]
	v_mfma_f32_16x16x32_bf16 v[10:13], v[138:141], v[194:197], v[10:13]
	v_mfma_f32_16x16x32_bf16 v[66:69], v[130:133], v[202:205], v[66:69]
	v_mfma_f32_16x16x32_bf16 v[2:5], v[138:141], v[202:205], v[2:5]
	v_mfma_f32_16x16x32_bf16 v[90:93], v[134:137], v[182:185], v[90:93]
	v_mfma_f32_16x16x32_bf16 v[26:29], v[142:145], v[182:185], v[26:29]
	v_mfma_f32_16x16x32_bf16 v[82:85], v[134:137], v[190:193], v[82:85]
	v_mfma_f32_16x16x32_bf16 v[18:21], v[142:145], v[190:193], v[18:21]
	v_mfma_f32_16x16x32_bf16 v[74:77], v[134:137], v[198:201], v[74:77]
	v_mfma_f32_16x16x32_bf16 v[10:13], v[142:145], v[198:201], v[10:13]
	v_mfma_f32_16x16x32_bf16 v[66:69], v[134:137], v[206:209], v[66:69]
	v_mfma_f32_16x16x32_bf16 v[2:5], v[142:145], v[206:209], v[2:5]
	s_setprio 1
	s_barrier
	s_add_i32 s90, s90, 2
	s_add_u32 s67, s67, 0x100
	s_addc_u32 s76, s76, 0
	s_add_u32 s52, s52, 0x100
	s_addc_u32 s53, s53, 0
	s_cmp_gt_u32 s90, 13
	s_cbranch_scc0 .Lkb_ffnup
	s_setprio 0
.Lkend_ffnup:
	s_and_b64 vcc, exec, s[20:21]
	s_cbranch_vccz .LBB0_1134
	s_barrier

; #define PG8_STAGE(bufoff, gbase, voff) do { _Pragma("unroll") for (int _i = 0; _i < 2; ++_i) \
;         __builtin_amdgcn_global_load_lds((const unsigned*)((const char*)(gbase) + (voff)[_i]), (LAS unsigned*)(lds + (bufoff) + ldsw + _i * 8192), 16, 0, 0); } while (0)
; #define PG8_LDA(dst, b, h) do { _Pragma("unroll") for (int m = 0; m < 4; ++m) _Pragma("unroll") for (int k = 0; k < 2; ++k) dst[m][k] = *(const LAS bf16x8*)(lds + PG8_SA(b, h) + aoff + m * 2048 + k * 1024); } while (0)
; #define PG8_LDB(dst, b, h) do { _Pragma("unroll") for (int n = 0; n < 2; ++n) _Pragma("unroll") for (int k = 0; k < 2; ++k) dst[n][k] = *(const LAS bf16x8*)(lds + PG8_SB(b, h) + boff + n * 2048 + k * 1024); } while (0)
; #define PG8_MMA(ai, bj, At, Bt) do { __builtin_amdgcn_s_setprio(1); _Pragma("unroll") for (int m = 0; m < 4; ++m) _Pragma("unroll") for (int n = 0; n < 2; ++n) _Pragma("unroll") for (int k = 0; k < 2; ++k) \
;         acc[ai][bj][m][n] = __builtin_amdgcn_mfma_f32_16x16x32_bf16(Bt[n][k], At[m][k], acc[ai][bj][m][n], 0, 0, 0); __builtin_amdgcn_s_setprio(0); } while (0)
; #define PG8_BAR __builtin_amdgcn_s_barrier()
; template <class Epi, class Sched>
; __device__ __forceinline__ void gemm_phase(LAS unsigned char* lds, const Gemm g, const Sched& S, const Epi& E) {
;     ...
;         const bool has_next = S.next(ui + 1, nxt);
;         const char* nA = has_next ? (const char*)g.A + (size_t)nxt.pm * tstepA : cA; const char* nB = has_next ? (const char*)g.Bt + (size_t)nxt.pn * tstepB : cB;
;         for (int t = 0; t < nt; t += 2) {
;             const bool last = (t == nt - 2);
;             const char* a1 = cA + (size_t)(t + 1) * kstep;
;             const char* a2 = last ? nA : cA + (size_t)(t + 2) * kstep; const char* b2 = last ? nB : cB + (size_t)(t + 2) * kstep;
;             const char* a3 = a2 + kstep; const char* b3 = b2 + kstep;
;             PG8_LDB(B0, 0, 0); PG8_LDB(B1, 0, 1); PG8_SCHED; PG8_LDA(At, 0, 0); PG8_STAGE(PG8_SA(1, 1), a1 + hstepA, voffA);
;             PG8_WAIT_V(8); PG8_WAIT_L(0); PG8_BAR; PG8_MMA(0, 0, At, B0); PG8_MMA(0, 1, At, B1); PG8_BAR; PG8_SCHED;
;     ...
; #pragma unroll
;         for (int a = 0; a < 2; ++a)
; #pragma unroll
;             for (int b = 0; b < 2; ++b)
; #pragma unroll
;                 for (int m = 0; m < 4; ++m)
; #pragma unroll
;                     for (int n = 0; n < 2; ++n) acc[a][b][m][n] = (f32x4){0.f, 0.f, 0.f, 0.f};
.LBB0_1237:
	s_add_u32 s44, s16, 0x100
	v_mov_b32_e32 v2, 0
	s_addc_u32 s45, s17, 0
	s_mov_b32 s46, -2
	v_mov_b32_e32 v3, v2
	v_mov_b32_e32 v4, v2
	v_mov_b32_e32 v5, v2
	v_mov_b32_e32 v6, v2
	v_mov_b32_e32 v7, v2
	v_mov_b32_e32 v8, v2
	v_mov_b32_e32 v9, v2
	v_mov_b32_e32 v18, v2
	v_mov_b32_e32 v19, v2
	v_mov_b32_e32 v20, v2
	v_mov_b32_e32 v21, v2
	v_mov_b32_e32 v22, v2
	v_mov_b32_e32 v23, v2
	v_mov_b32_e32 v24, v2
	v_mov_b32_e32 v25, v2
	v_mov_b32_e32 v34, v2
	v_mov_b32_e32 v35, v2
	v_mov_b32_e32 v36, v2
	v_mov_b32_e32 v37, v2
	v_mov_b32_e32 v38, v2
	v_mov_b32_e32 v39, v2
	v_mov_b32_e32 v40, v2
	v_mov_b32_e32 v41, v2
	v_mov_b32_e32 v50, v2
	v_mov_b32_e32 v51, v2
	v_mov_b32_e32 v52, v2
	v_mov_b32_e32 v53, v2
	v_mov_b32_e32 v54, v2
	v_mov_b32_e32 v55, v2
	v_mov_b32_e32 v56, v2
	v_mov_b32_e32 v57, v2
	v_mov_b32_e32 v10, v2
	v_mov_b32_e32 v11, v2
	v_mov_b32_e32 v12, v2
	v_mov_b32_e32 v13, v2
	v_mov_b32_e32 v14, v2
	v_mov_b32_e32 v15, v2
	v_mov_b32_e32 v16, v2
	v_mov_b32_e32 v17, v2
	v_mov_b32_e32 v26, v2
	v_mov_b32_e32 v27, v2
	v_mov_b32_e32 v28, v2
	v_mov_b32_e32 v29, v2
	v_mov_b32_e32 v30, v2
	v_mov_b32_e32 v31, v2
	v_mov_b32_e32 v32, v2
	v_mov_b32_e32 v33, v2
	v_mov_b32_e32 v42, v2
	v_mov_b32_e32 v43, v2
	v_mov_b32_e32 v44, v2
	v_mov_b32_e32 v45, v2
	v_mov_b32_e32 v46, v2
	v_mov_b32_e32 v47, v2
	v_mov_b32_e32 v48, v2
	v_mov_b32_e32 v49, v2
	v_mov_b32_e32 v58, v2
	v_mov_b32_e32 v59, v2
	v_mov_b32_e32 v60, v2
	v_mov_b32_e32 v61, v2
	v_mov_b32_e32 v62, v2
	v_mov_b32_e32 v63, v2
	v_mov_b32_e32 v64, v2
	v_mov_b32_e32 v65, v2
	v_mov_b32_e32 v66, v2
	v_mov_b32_e32 v67, v2
	v_mov_b32_e32 v68, v2
	v_mov_b32_e32 v69, v2
	v_mov_b32_e32 v70, v2
	v_mov_b32_e32 v71, v2
	v_mov_b32_e32 v72, v2
	v_mov_b32_e32 v73, v2
	v_mov_b32_e32 v82, v2
	v_mov_b32_e32 v83, v2
	v_mov_b32_e32 v84, v2
	v_mov_b32_e32 v85, v2
	v_mov_b32_e32 v86, v2
	v_mov_b32_e32 v87, v2
	v_mov_b32_e32 v88, v2
	v_mov_b32_e32 v89, v2
	v_mov_b32_e32 v98, v2
	v_mov_b32_e32 v99, v2
	v_mov_b32_e32 v100, v2
	v_mov_b32_e32 v101, v2
	v_mov_b32_e32 v102, v2
	v_mov_b32_e32 v103, v2
	v_mov_b32_e32 v104, v2
	v_mov_b32_e32 v105, v2
	s_waitcnt vmcnt(0)
	v_mov_b32_e32 v114, v2
	v_mov_b32_e32 v115, v2
	v_mov_b32_e32 v116, v2
	v_mov_b32_e32 v117, v2
	v_mov_b32_e32 v118, v2
	v_mov_b32_e32 v119, v2
	v_mov_b32_e32 v120, v2
	v_mov_b32_e32 v121, v2
	v_mov_b32_e32 v74, v2
	v_mov_b32_e32 v75, v2
	v_mov_b32_e32 v76, v2
	v_mov_b32_e32 v77, v2
	v_mov_b32_e32 v78, v2
	v_mov_b32_e32 v79, v2
	v_mov_b32_e32 v80, v2
	v_mov_b32_e32 v81, v2
	v_mov_b32_e32 v90, v2
	v_mov_b32_e32 v91, v2
	v_mov_b32_e32 v92, v2
	v_mov_b32_e32 v93, v2
	v_mov_b32_e32 v94, v2
	v_mov_b32_e32 v95, v2
	v_mov_b32_e32 v96, v2
	v_mov_b32_e32 v97, v2
	v_mov_b32_e32 v106, v2
	v_mov_b32_e32 v107, v2
	v_mov_b32_e32 v108, v2
	v_mov_b32_e32 v109, v2
	v_mov_b32_e32 v110, v2
	v_mov_b32_e32 v111, v2
	v_mov_b32_e32 v112, v2
	v_mov_b32_e32 v113, v2
	v_mov_b32_e32 v122, v2
	v_mov_b32_e32 v123, v2
	v_mov_b32_e32 v124, v2
	v_mov_b32_e32 v125, v2
	v_mov_b32_e32 v126, v2
	v_mov_b32_e32 v127, v2
	v_mov_b32_e32 v128, v2
	v_mov_b32_e32 v129, v2
	s_cmp_lg_u64 s[2:3], 0
	s_cbranch_scc1 .Lkb_down
.LBB0_1238:
	s_add_u32 s16, s14, 0x100
	s_addc_u32 s17, s15, 0
	s_add_i32 s48, 0, 0x10000
	s_cmp_eq_u32 s46, 40
	s_cselect_b32 s21, s7, s17
	s_cselect_b32 s20, s6, s16
	v_add_u32_e32 v146, s48, v148
	s_cselect_b32 s19, s13, s45
	s_cselect_b32 s18, s12, s44
	s_add_i32 s49, 0, 0x14000
	ds_read_b128 v[142:145], v146
	ds_read_b128 v[152:155], v146 offset:1024
	ds_read_b128 v[156:159], v146 offset:2048
	ds_read_b128 v[160:163], v146 offset:3072
	v_add_u32_e32 v146, s49, v148
	ds_read_b128 v[164:167], v146
	ds_read_b128 v[168:171], v146 offset:1024
	ds_read_b128 v[172:175], v146 offset:2048
	ds_read_b128 v[176:179], v146 offset:3072
	v_lshl_add_u64 v[146:147], s[14:15], 0, v[140:141]
	s_add_i32 m0, s27, 0xc000
	ds_read_b128 v[182:185], v150
	ds_read_b128 v[186:189], v150 offset:1024
	ds_read_b128 v[190:193], v150 offset:2048
	ds_read_b128 v[194:197], v150 offset:3072
	ds_read_b128 v[198:201], v150 offset:4096
	ds_read_b128 v[202:205], v150 offset:5120
	ds_read_b128 v[206:209], v150 offset:6144
	ds_read_b128 v[210:213], v150 offset:7168
	global_load_lds_dwordx4 v[146:147], off
	v_lshl_add_u64 v[146:147], s[14:15], 0, v[138:139]
	s_add_i32 m0, s27, 0xe000
	s_nop 0
	global_load_lds_dwordx4 v[146:147], off
	s_waitcnt vmcnt(8)
	s_waitcnt lgkmcnt(0)
	s_barrier
	s_setprio 1
	s_waitcnt lgkmcnt(0)
	v_mfma_f32_16x16x32_bf16 v[126:129], v[142:145], v[182:185], v[126:129]
	v_mfma_f32_16x16x32_bf16 v[122:125], v[156:159], v[182:185], v[122:125]
	v_mfma_f32_16x16x32_bf16 v[110:113], v[142:145], v[190:193], v[110:113]
	v_mfma_f32_16x16x32_bf16 v[106:109], v[156:159], v[190:193], v[106:109]
	v_mfma_f32_16x16x32_bf16 v[94:97], v[142:145], v[198:201], v[94:97]
	v_mfma_f32_16x16x32_bf16 v[90:93], v[156:159], v[198:201], v[90:93]
	v_mfma_f32_16x16x32_bf16 v[78:81], v[142:145], v[206:209], v[78:81]
	v_mfma_f32_16x16x32_bf16 v[74:77], v[156:159], v[206:209], v[74:77]
	v_mfma_f32_16x16x32_bf16 v[126:129], v[152:155], v[186:189], v[126:129]
	v_mfma_f32_16x16x32_bf16 v[122:125], v[160:163], v[186:189], v[122:125]
	v_mfma_f32_16x16x32_bf16 v[110:113], v[152:155], v[194:197], v[110:113]
	v_mfma_f32_16x16x32_bf16 v[106:109], v[160:163], v[194:197], v[106:109]
	v_mfma_f32_16x16x32_bf16 v[94:97], v[152:155], v[202:205], v[94:97]
	v_mfma_f32_16x16x32_bf16 v[90:93], v[160:163], v[202:205], v[90:93]
	v_mfma_f32_16x16x32_bf16 v[78:81], v[152:155], v[210:213], v[78:81]
	v_mfma_f32_16x16x32_bf16 v[74:77], v[160:163], v[210:213], v[74:77]
	s_setprio 0
	s_setprio 1
	v_mfma_f32_16x16x32_bf16 v[118:121], v[164:167], v[182:185], v[118:121]
	v_mfma_f32_16x16x32_bf16 v[114:117], v[172:175], v[182:185], v[114:117]
	v_mfma_f32_16x16x32_bf16 v[102:105], v[164:167], v[190:193], v[102:105]
	v_mfma_f32_16x16x32_bf16 v[98:101], v[172:175], v[190:193], v[98:101]
	v_mfma_f32_16x16x32_bf16 v[86:89], v[164:167], v[198:201], v[86:89]
	v_mfma_f32_16x16x32_bf16 v[82:85], v[172:175], v[198:201], v[82:85]
	v_mfma_f32_16x16x32_bf16 v[70:73], v[164:167], v[206:209], v[70:73]
	v_mfma_f32_16x16x32_bf16 v[66:69], v[172:175], v[206:209], v[66:69]
	v_mfma_f32_16x16x32_bf16 v[118:121], v[168:171], v[186:189], v[118:121]
	v_mfma_f32_16x16x32_bf16 v[114:117], v[176:179], v[186:189], v[114:117]
	v_mfma_f32_16x16x32_bf16 v[102:105], v[168:171], v[194:197], v[102:105]
	v_mfma_f32_16x16x32_bf16 v[98:101], v[176:179], v[194:197], v[98:101]
	v_mfma_f32_16x16x32_bf16 v[86:89], v[168:171], v[202:205], v[86:89]
	v_mfma_f32_16x16x32_bf16 v[82:85], v[176:179], v[202:205], v[82:85]
	v_mfma_f32_16x16x32_bf16 v[70:73], v[168:171], v[210:213], v[70:73]
	v_mfma_f32_16x16x32_bf16 v[66:69], v[176:179], v[210:213], v[66:69]
	s_setprio 0
	s_barrier
; #define PG8_STAGE(bufoff, gbase, voff) do { _Pragma("unroll") for (int _i = 0; _i < 2; ++_i) \
;         __builtin_amdgcn_global_load_lds((const unsigned*)((const char*)(gbase) + (voff)[_i]), (LAS unsigned*)(lds + (bufoff) + ldsw + _i * 8192), 16, 0, 0); } while (0)
; #define PG8_LDA(dst, b, h) do { _Pragma("unroll") for (int m = 0; m < 4; ++m) _Pragma("unroll") for (int k = 0; k < 2; ++k) dst[m][k] = *(const LAS bf16x8*)(lds + PG8_SA(b, h) + aoff + m * 2048 + k * 1024); } while (0)
; #define PG8_LDB(dst, b, h) do { _Pragma("unroll") for (int n = 0; n < 2; ++n) _Pragma("unroll") for (int k = 0; k < 2; ++k) dst[n][k] = *(const LAS bf16x8*)(lds + PG8_SB(b, h) + boff + n * 2048 + k * 1024); } while (0)
; #define PG8_MMA(ai, bj, At, Bt) do { __builtin_amdgcn_s_setprio(1); _Pragma("unroll") for (int m = 0; m < 4; ++m) _Pragma("unroll") for (int n = 0; n < 2; ++n) _Pragma("unroll") for (int k = 0; k < 2; ++k) \
;         acc[ai][bj][m][n] = __builtin_amdgcn_mfma_f32_16x16x32_bf16(Bt[n][k], At[m][k], acc[ai][bj][m][n], 0, 0, 0); __builtin_amdgcn_s_setprio(0); } while (0)
; #define PG8_WAIT_V(n) asm volatile("s_waitcnt vmcnt(" #n ")" ::: "memory")
; #define PG8_WAIT_L(n) asm volatile("s_waitcnt lgkmcnt(" #n ")" ::: "memory")
; #define PG8_BAR __builtin_amdgcn_s_barrier()
; #define PG8_SCHED __builtin_amdgcn_sched_barrier(0)
; #define PG8_STAGE(bufoff, gbase, voff) do { _Pragma("unroll") for (int _i = 0; _i < 2; ++_i) \
;         __builtin_amdgcn_global_load_lds((const unsigned*)((const char*)(gbase) + (voff)[_i]), (LAS unsigned*)(lds + (bufoff) + ldsw + _i * 8192), 16, 0, 0); } while (0)
; #define PG8_LDA(dst, b, h) do { _Pragma("unroll") for (int m = 0; m < 4; ++m) _Pragma("unroll") for (int k = 0; k < 2; ++k) dst[m][k] = *(const LAS bf16x8*)(lds + PG8_SA(b, h) + aoff + m * 2048 + k * 1024); } while (0)
; template <class Epi, class Sched>
; __device__ __forceinline__ void gemm_phase(LAS unsigned char* lds, const Gemm g, const Sched& S, const Epi& E) {
;     ...
;             PG8_LDA(At, 0, 1); PG8_STAGE(PG8_SB(0, 0), b2, voffB); PG8_STAGE(PG8_SB(0, 1), b2 + hstepB, voffB); PG8_STAGE(PG8_SA(0, 0), a2, voffA);
;             PG8_WAIT_V(8); PG8_WAIT_L(0); PG8_BAR; PG8_MMA(1, 0, At, B0); PG8_MMA(1, 1, At, B1); PG8_BAR; PG8_SCHED;
;             PG8_LDB(B0, 1, 0); PG8_LDB(B1, 1, 1); PG8_SCHED; PG8_LDA(At, 1, 0); PG8_STAGE(PG8_SA(0, 1), a2 + hstepA, voffA);
	s_add_i32 s14, s48, s26
	v_lshl_add_u64 v[146:147], s[18:19], 0, v[132:133]
	s_mov_b32 m0, s14
	ds_read_b128 v[182:185], v150 offset:16384
	ds_read_b128 v[186:189], v150 offset:17408
	ds_read_b128 v[190:193], v150 offset:18432
	ds_read_b128 v[194:197], v150 offset:19456
	ds_read_b128 v[198:201], v150 offset:20480
	ds_read_b128 v[202:205], v150 offset:21504
	ds_read_b128 v[206:209], v150 offset:22528
	ds_read_b128 v[210:213], v150 offset:23552
	global_load_lds_dwordx4 v[146:147], off
	s_add_i32 m0, s14, 0x2000
	s_add_u32 s14, s18, 0xb0000
	v_lshl_add_u64 v[214:215], s[18:19], 0, v[136:137]
	s_addc_u32 s15, s19, 0
	s_add_i32 s48, s49, s26
	global_load_lds_dwordx4 v[214:215], off
	v_lshl_add_u64 v[226:227], s[14:15], 0, v[132:133]
	s_mov_b32 m0, s48
	v_lshl_add_u64 v[228:229], s[20:21], 0, v[134:135]
	global_load_lds_dwordx4 v[226:227], off
	v_lshl_add_u64 v[226:227], s[14:15], 0, v[136:137]
	s_add_i32 m0, s48, 0x2000
	s_nop 0
	global_load_lds_dwordx4 v[226:227], off
	v_lshl_add_u64 v[226:227], s[20:21], 0, v[130:131]
	s_mov_b32 m0, s27
	s_nop 0
	global_load_lds_dwordx4 v[226:227], off
	s_mov_b32 m0, s28
	s_nop 0
	global_load_lds_dwordx4 v[228:229], off
	s_waitcnt vmcnt(8)
	s_waitcnt lgkmcnt(0)
	s_barrier
	s_setprio 1
	s_waitcnt lgkmcnt(0)
	v_mfma_f32_16x16x32_bf16 v[62:65], v[142:145], v[182:185], v[62:65]
	v_mfma_f32_16x16x32_bf16 v[58:61], v[156:159], v[182:185], v[58:61]
	v_mfma_f32_16x16x32_bf16 v[46:49], v[142:145], v[190:193], v[46:49]
	v_mfma_f32_16x16x32_bf16 v[42:45], v[156:159], v[190:193], v[42:45]
	v_mfma_f32_16x16x32_bf16 v[30:33], v[142:145], v[198:201], v[30:33]
	v_mfma_f32_16x16x32_bf16 v[26:29], v[156:159], v[198:201], v[26:29]
	v_mfma_f32_16x16x32_bf16 v[14:17], v[142:145], v[206:209], v[14:17]
	v_mfma_f32_16x16x32_bf16 v[10:13], v[156:159], v[206:209], v[10:13]
	v_mfma_f32_16x16x32_bf16 v[62:65], v[152:155], v[186:189], v[62:65]
	v_mfma_f32_16x16x32_bf16 v[58:61], v[160:163], v[186:189], v[58:61]
	v_mfma_f32_16x16x32_bf16 v[46:49], v[152:155], v[194:197], v[46:49]
	v_mfma_f32_16x16x32_bf16 v[42:45], v[160:163], v[194:197], v[42:45]
	v_mfma_f32_16x16x32_bf16 v[30:33], v[152:155], v[202:205], v[30:33]
	v_mfma_f32_16x16x32_bf16 v[26:29], v[160:163], v[202:205], v[26:29]
	v_mfma_f32_16x16x32_bf16 v[14:17], v[152:155], v[210:213], v[14:17]
	v_mfma_f32_16x16x32_bf16 v[10:13], v[160:163], v[210:213], v[10:13]
	s_setprio 0
	s_setprio 1
	v_mfma_f32_16x16x32_bf16 v[54:57], v[164:167], v[182:185], v[54:57]
	v_mfma_f32_16x16x32_bf16 v[50:53], v[172:175], v[182:185], v[50:53]
	v_mfma_f32_16x16x32_bf16 v[38:41], v[164:167], v[190:193], v[38:41]
	v_mfma_f32_16x16x32_bf16 v[34:37], v[172:175], v[190:193], v[34:37]
	v_mfma_f32_16x16x32_bf16 v[22:25], v[164:167], v[198:201], v[22:25]
	v_mfma_f32_16x16x32_bf16 v[18:21], v[172:175], v[198:201], v[18:21]
	v_mfma_f32_16x16x32_bf16 v[6:9], v[164:167], v[206:209], v[6:9]
	v_mfma_f32_16x16x32_bf16 v[2:5], v[172:175], v[206:209], v[2:5]
	v_mfma_f32_16x16x32_bf16 v[54:57], v[168:171], v[186:189], v[54:57]
	v_mfma_f32_16x16x32_bf16 v[50:53], v[176:179], v[186:189], v[50:53]
	v_mfma_f32_16x16x32_bf16 v[38:41], v[168:171], v[194:197], v[38:41]
	v_mfma_f32_16x16x32_bf16 v[34:37], v[176:179], v[194:197], v[34:37]
	v_mfma_f32_16x16x32_bf16 v[22:25], v[168:171], v[202:205], v[22:25]
	v_mfma_f32_16x16x32_bf16 v[18:21], v[176:179], v[202:205], v[18:21]
	v_mfma_f32_16x16x32_bf16 v[6:9], v[168:171], v[210:213], v[6:9]
	v_mfma_f32_16x16x32_bf16 v[2:5], v[176:179], v[210:213], v[2:5]
	s_setprio 0
	s_barrier
	s_add_i32 s48, 0, 0x18000
	v_add_u32_e32 v151, s48, v148
	s_add_i32 s49, 0, 0x1c000
	ds_read_b128 v[142:145], v151
	ds_read_b128 v[152:155], v151 offset:1024
	ds_read_b128 v[156:159], v151 offset:2048
	ds_read_b128 v[160:163], v151 offset:3072
	v_add_u32_e32 v151, s49, v148
	ds_read_b128 v[164:167], v151
	ds_read_b128 v[168:171], v151 offset:1024
	ds_read_b128 v[172:175], v151 offset:2048
	ds_read_b128 v[176:179], v151 offset:3072
	s_add_u32 s14, s20, 0xb0000
	s_addc_u32 s15, s21, 0
	s_mov_b32 m0, s29
	v_lshl_add_u64 v[232:233], s[14:15], 0, v[130:131]
	ds_read_b128 v[182:185], v150 offset:32768
	ds_read_b128 v[186:189], v150 offset:33792
	ds_read_b128 v[190:193], v150 offset:34816
	ds_read_b128 v[194:197], v150 offset:35840
	ds_read_b128 v[198:201], v150 offset:36864
	ds_read_b128 v[202:205], v150 offset:37888
	ds_read_b128 v[206:209], v150 offset:38912
	ds_read_b128 v[210:213], v150 offset:39936
	global_load_lds_dwordx4 v[232:233], off
	v_lshl_add_u64 v[232:233], s[14:15], 0, v[134:135]
	s_mov_b32 m0, s30
	s_nop 0
	global_load_lds_dwordx4 v[232:233], off
	s_waitcnt vmcnt(8)
	s_waitcnt lgkmcnt(0)
	s_barrier
; #define PG8_STAGE(bufoff, gbase, voff) do { _Pragma("unroll") for (int _i = 0; _i < 2; ++_i) \
;         __builtin_amdgcn_global_load_lds((const unsigned*)((const char*)(gbase) + (voff)[_i]), (LAS unsigned*)(lds + (bufoff) + ldsw + _i * 8192), 16, 0, 0); } while (0)
; #define PG8_LDA(dst, b, h) do { _Pragma("unroll") for (int m = 0; m < 4; ++m) _Pragma("unroll") for (int k = 0; k < 2; ++k) dst[m][k] = *(const LAS bf16x8*)(lds + PG8_SA(b, h) + aoff + m * 2048 + k * 1024); } while (0)
; #define PG8_MMA(ai, bj, At, Bt) do { __builtin_amdgcn_s_setprio(1); _Pragma("unroll") for (int m = 0; m < 4; ++m) _Pragma("unroll") for (int n = 0; n < 2; ++n) _Pragma("unroll") for (int k = 0; k < 2; ++k) \
;         acc[ai][bj][m][n] = __builtin_amdgcn_mfma_f32_16x16x32_bf16(Bt[n][k], At[m][k], acc[ai][bj][m][n], 0, 0, 0); __builtin_amdgcn_s_setprio(0); } while (0)
; #define PG8_WAIT_V(n) asm volatile("s_waitcnt vmcnt(" #n ")" ::: "memory")
; #define PG8_WAIT_L(n) asm volatile("s_waitcnt lgkmcnt(" #n ")" ::: "memory")
; #define PG8_BAR __builtin_amdgcn_s_barrier()
; #define PG8_SCHED __builtin_amdgcn_sched_barrier(0)
; #define PG8_STAGE(bufoff, gbase, voff) do { _Pragma("unroll") for (int _i = 0; _i < 2; ++_i) \
;         __builtin_amdgcn_global_load_lds((const unsigned*)((const char*)(gbase) + (voff)[_i]), (LAS unsigned*)(lds + (bufoff) + ldsw + _i * 8192), 16, 0, 0); } while (0)
; #define PG8_LDA(dst, b, h) do { _Pragma("unroll") for (int m = 0; m < 4; ++m) _Pragma("unroll") for (int k = 0; k < 2; ++k) dst[m][k] = *(const LAS bf16x8*)(lds + PG8_SA(b, h) + aoff + m * 2048 + k * 1024); } while (0)
; #define PG8_WAIT_V(n) asm volatile("s_waitcnt vmcnt(" #n ")" ::: "memory")
; #define PG8_WAIT_L(n) asm volatile("s_waitcnt lgkmcnt(" #n ")" ::: "memory")
; #define PG8_BAR __builtin_amdgcn_s_barrier()
; template <class Epi, class Sched>
; __device__ __forceinline__ void gemm_phase(LAS unsigned char* lds, const Gemm g, const Sched& S, const Epi& E) {
;     ...
;             PG8_WAIT_V(8); PG8_WAIT_L(0); PG8_BAR; PG8_MMA(0, 0, At, B0); PG8_MMA(0, 1, At, B1); PG8_BAR; PG8_SCHED;
;             PG8_LDA(At, 1, 1); PG8_STAGE(PG8_SB(1, 0), b3, voffB); PG8_STAGE(PG8_SB(1, 1), b3 + hstepB, voffB); PG8_STAGE(PG8_SA(1, 0), a3, voffA);
;             PG8_WAIT_V(8); PG8_WAIT_L(0); PG8_BAR; PG8_MMA(1, 0, At, B0); PG8_MMA(1, 1, At, B1); PG8_BAR; PG8_SCHED;
;         }
	s_setprio 1
	s_waitcnt lgkmcnt(0)
	v_mfma_f32_16x16x32_bf16 v[126:129], v[142:145], v[182:185], v[126:129]
	v_mfma_f32_16x16x32_bf16 v[122:125], v[156:159], v[182:185], v[122:125]
	v_mfma_f32_16x16x32_bf16 v[110:113], v[142:145], v[190:193], v[110:113]
	v_mfma_f32_16x16x32_bf16 v[106:109], v[156:159], v[190:193], v[106:109]
	v_mfma_f32_16x16x32_bf16 v[94:97], v[142:145], v[198:201], v[94:97]
	v_mfma_f32_16x16x32_bf16 v[90:93], v[156:159], v[198:201], v[90:93]
	v_mfma_f32_16x16x32_bf16 v[78:81], v[142:145], v[206:209], v[78:81]
	v_mfma_f32_16x16x32_bf16 v[74:77], v[156:159], v[206:209], v[74:77]
	v_mfma_f32_16x16x32_bf16 v[126:129], v[152:155], v[186:189], v[126:129]
	v_mfma_f32_16x16x32_bf16 v[122:125], v[160:163], v[186:189], v[122:125]
	v_mfma_f32_16x16x32_bf16 v[110:113], v[152:155], v[194:197], v[110:113]
	v_mfma_f32_16x16x32_bf16 v[106:109], v[160:163], v[194:197], v[106:109]
	v_mfma_f32_16x16x32_bf16 v[94:97], v[152:155], v[202:205], v[94:97]
	v_mfma_f32_16x16x32_bf16 v[90:93], v[160:163], v[202:205], v[90:93]
	v_mfma_f32_16x16x32_bf16 v[78:81], v[152:155], v[210:213], v[78:81]
	v_mfma_f32_16x16x32_bf16 v[74:77], v[160:163], v[210:213], v[74:77]
	s_setprio 0
	s_setprio 1
	v_mfma_f32_16x16x32_bf16 v[118:121], v[164:167], v[182:185], v[118:121]
	v_mfma_f32_16x16x32_bf16 v[114:117], v[172:175], v[182:185], v[114:117]
	v_mfma_f32_16x16x32_bf16 v[102:105], v[164:167], v[190:193], v[102:105]
	v_mfma_f32_16x16x32_bf16 v[98:101], v[172:175], v[190:193], v[98:101]
	v_mfma_f32_16x16x32_bf16 v[86:89], v[164:167], v[198:201], v[86:89]
	v_mfma_f32_16x16x32_bf16 v[82:85], v[172:175], v[198:201], v[82:85]
	v_mfma_f32_16x16x32_bf16 v[70:73], v[164:167], v[206:209], v[70:73]
	v_mfma_f32_16x16x32_bf16 v[66:69], v[172:175], v[206:209], v[66:69]
	v_mfma_f32_16x16x32_bf16 v[118:121], v[168:171], v[186:189], v[118:121]
	v_mfma_f32_16x16x32_bf16 v[114:117], v[176:179], v[186:189], v[114:117]
	v_mfma_f32_16x16x32_bf16 v[102:105], v[168:171], v[194:197], v[102:105]
	v_mfma_f32_16x16x32_bf16 v[98:101], v[176:179], v[194:197], v[98:101]
	v_mfma_f32_16x16x32_bf16 v[86:89], v[168:171], v[202:205], v[86:89]
	v_mfma_f32_16x16x32_bf16 v[82:85], v[176:179], v[202:205], v[82:85]
	v_mfma_f32_16x16x32_bf16 v[70:73], v[168:171], v[210:213], v[70:73]
	v_mfma_f32_16x16x32_bf16 v[66:69], v[176:179], v[210:213], v[66:69]
	s_setprio 0
	s_barrier
	s_add_i32 s14, s48, s26
	v_lshl_add_u64 v[146:147], v[146:147], 0, s[86:87]
	s_mov_b32 m0, s14
	ds_read_b128 v[182:185], v150 offset:49152
	ds_read_b128 v[186:189], v150 offset:50176
	ds_read_b128 v[190:193], v150 offset:51200
	ds_read_b128 v[194:197], v150 offset:52224
	ds_read_b128 v[198:201], v150 offset:53248
	ds_read_b128 v[202:205], v150 offset:54272
	ds_read_b128 v[206:209], v150 offset:55296
	ds_read_b128 v[210:213], v150 offset:56320
	global_load_lds_dwordx4 v[146:147], off
	s_add_i32 m0, s14, 0x2000
	s_add_u32 s14, s18, 0xb0080
	v_lshl_add_u64 v[146:147], v[214:215], 0, s[86:87]
	s_addc_u32 s15, s19, 0
	s_add_i32 s18, s49, s26
	global_load_lds_dwordx4 v[146:147], off
	v_lshl_add_u64 v[146:147], s[14:15], 0, v[132:133]
	s_mov_b32 m0, s18
	s_nop 0
	global_load_lds_dwordx4 v[146:147], off
	v_lshl_add_u64 v[146:147], s[14:15], 0, v[136:137]
	s_add_i32 m0, s18, 0x2000
	s_nop 0
	global_load_lds_dwordx4 v[146:147], off
	v_lshl_add_u64 v[146:147], v[226:227], 0, s[86:87]
	s_mov_b32 m0, s31
	s_nop 0
	global_load_lds_dwordx4 v[146:147], off
	v_lshl_add_u64 v[146:147], v[228:229], 0, s[86:87]
	s_mov_b32 m0, s38
	s_nop 0
	global_load_lds_dwordx4 v[146:147], off
	s_waitcnt vmcnt(8)
	s_waitcnt lgkmcnt(0)
	s_barrier
	s_setprio 1
	s_waitcnt lgkmcnt(0)
	v_mfma_f32_16x16x32_bf16 v[62:65], v[142:145], v[182:185], v[62:65]
	v_mfma_f32_16x16x32_bf16 v[58:61], v[156:159], v[182:185], v[58:61]
	v_mfma_f32_16x16x32_bf16 v[46:49], v[142:145], v[190:193], v[46:49]
	v_mfma_f32_16x16x32_bf16 v[42:45], v[156:159], v[190:193], v[42:45]
	v_mfma_f32_16x16x32_bf16 v[30:33], v[142:145], v[198:201], v[30:33]
	v_mfma_f32_16x16x32_bf16 v[26:29], v[156:159], v[198:201], v[26:29]
	v_mfma_f32_16x16x32_bf16 v[14:17], v[142:145], v[206:209], v[14:17]
	v_mfma_f32_16x16x32_bf16 v[10:13], v[156:159], v[206:209], v[10:13]
	v_mfma_f32_16x16x32_bf16 v[62:65], v[152:155], v[186:189], v[62:65]
	v_mfma_f32_16x16x32_bf16 v[58:61], v[160:163], v[186:189], v[58:61]
	v_mfma_f32_16x16x32_bf16 v[46:49], v[152:155], v[194:197], v[46:49]
	v_mfma_f32_16x16x32_bf16 v[42:45], v[160:163], v[194:197], v[42:45]
	v_mfma_f32_16x16x32_bf16 v[30:33], v[152:155], v[202:205], v[30:33]
	v_mfma_f32_16x16x32_bf16 v[26:29], v[160:163], v[202:205], v[26:29]
	v_mfma_f32_16x16x32_bf16 v[14:17], v[152:155], v[210:213], v[14:17]
	v_mfma_f32_16x16x32_bf16 v[10:13], v[160:163], v[210:213], v[10:13]
	s_setprio 0
	s_setprio 1
	v_mfma_f32_16x16x32_bf16 v[54:57], v[164:167], v[182:185], v[54:57]
	v_mfma_f32_16x16x32_bf16 v[50:53], v[172:175], v[182:185], v[50:53]
	v_mfma_f32_16x16x32_bf16 v[38:41], v[164:167], v[190:193], v[38:41]
	v_mfma_f32_16x16x32_bf16 v[34:37], v[172:175], v[190:193], v[34:37]
	v_mfma_f32_16x16x32_bf16 v[22:25], v[164:167], v[198:201], v[22:25]
	v_mfma_f32_16x16x32_bf16 v[18:21], v[172:175], v[198:201], v[18:21]
	v_mfma_f32_16x16x32_bf16 v[6:9], v[164:167], v[206:209], v[6:9]
	v_mfma_f32_16x16x32_bf16 v[2:5], v[172:175], v[206:209], v[2:5]
	v_mfma_f32_16x16x32_bf16 v[54:57], v[168:171], v[186:189], v[54:57]
	v_mfma_f32_16x16x32_bf16 v[50:53], v[176:179], v[186:189], v[50:53]
	v_mfma_f32_16x16x32_bf16 v[38:41], v[168:171], v[194:197], v[38:41]
	v_mfma_f32_16x16x32_bf16 v[34:37], v[176:179], v[194:197], v[34:37]
	v_mfma_f32_16x16x32_bf16 v[22:25], v[168:171], v[202:205], v[22:25]
	v_mfma_f32_16x16x32_bf16 v[18:21], v[176:179], v[202:205], v[18:21]
	v_mfma_f32_16x16x32_bf16 v[6:9], v[168:171], v[210:213], v[6:9]
	v_mfma_f32_16x16x32_bf16 v[2:5], v[176:179], v[210:213], v[2:5]
	s_setprio 0
	s_barrier
	s_add_i32 s46, s46, 2
	s_add_u32 s44, s44, 0x100
	s_addc_u32 s45, s45, 0
	s_cmp_gt_u32 s46, 41
	s_mov_b64 s[14:15], s[16:17]
	s_cbranch_scc0 .LBB0_1238
	s_branch .Lkend_down
; #define PG8_STAGE(bufoff, gbase, voff) do { _Pragma("unroll") for (int _i = 0; _i < 2; ++_i) \
;         __builtin_amdgcn_global_load_lds((const unsigned*)((const char*)(gbase) + (voff)[_i]), (LAS unsigned*)(lds + (bufoff) + ldsw + _i * 8192), 16, 0, 0); } while (0)
; #define PG8_LDA(dst, b, h) do { _Pragma("unroll") for (int m = 0; m < 4; ++m) _Pragma("unroll") for (int k = 0; k < 2; ++k) dst[m][k] = *(const LAS bf16x8*)(lds + PG8_SA(b, h) + aoff + m * 2048 + k * 1024); } while (0)
; #define PG8_LDB(dst, b, h) do { _Pragma("unroll") for (int n = 0; n < 2; ++n) _Pragma("unroll") for (int k = 0; k < 2; ++k) dst[n][k] = *(const LAS bf16x8*)(lds + PG8_SB(b, h) + boff + n * 2048 + k * 1024); } while (0)
; #define PG8_MMA(ai, bj, At, Bt) do { __builtin_amdgcn_s_setprio(1); _Pragma("unroll") for (int m = 0; m < 4; ++m) _Pragma("unroll") for (int n = 0; n < 2; ++n) _Pragma("unroll") for (int k = 0; k < 2; ++k) \
;         acc[ai][bj][m][n] = __builtin_amdgcn_mfma_f32_16x16x32_bf16(Bt[n][k], At[m][k], acc[ai][bj][m][n], 0, 0, 0); __builtin_amdgcn_s_setprio(0); } while (0)
; #define PG8_WAIT_V(n) asm volatile("s_waitcnt vmcnt(" #n ")" ::: "memory")
; #define PG8_WAIT_L(n) asm volatile("s_waitcnt lgkmcnt(" #n ")" ::: "memory")
; #define PG8_BAR __builtin_amdgcn_s_barrier()
; #define PG8_SCHED __builtin_amdgcn_sched_barrier(0)
; #define PG8_WAIT_V(n) asm volatile("s_waitcnt vmcnt(" #n ")" ::: "memory")
; #define PG8_WAIT_L(n) asm volatile("s_waitcnt lgkmcnt(" #n ")" ::: "memory")
; template <class Epi, class Sched>
; __device__ __forceinline__ void gemm_phase(LAS unsigned char* lds, const Gemm g, const Sched& S, const Epi& E) {
;     ...
;         for (int t = 0; t < nt; t += 2) {
;             const bool last = (t == nt - 2);
;             const char* a1 = cA + (size_t)(t + 1) * kstep;
;             const char* a2 = last ? nA : cA + (size_t)(t + 2) * kstep; const char* b2 = last ? nB : cB + (size_t)(t + 2) * kstep;
;             const char* a3 = a2 + kstep; const char* b3 = b2 + kstep;
;             PG8_LDB(B0, 0, 0); PG8_LDB(B1, 0, 1); PG8_SCHED; PG8_LDA(At, 0, 0); PG8_STAGE(PG8_SA(1, 1), a1 + hstepA, voffA);
;             PG8_WAIT_V(8); PG8_WAIT_L(0); PG8_BAR; PG8_MMA(0, 0, At, B0); PG8_MMA(0, 1, At, B1); PG8_BAR; PG8_SCHED;
;             PG8_LDA(At, 0, 1); PG8_STAGE(PG8_SB(0, 0), b2, voffB); PG8_STAGE(PG8_SB(0, 1), b2 + hstepB, voffB); PG8_STAGE(PG8_SA(0, 0), a2, voffA);
.Lkb_down:
	s_add_u32 s16, s14, 0x100
	s_addc_u32 s17, s15, 0
	s_add_i32 s48, 0, 0x10000
	s_cmp_eq_u32 s46, 40
	s_cselect_b32 s21, s7, s17
	s_cselect_b32 s20, s6, s16
	v_add_u32_e32 v146, s48, v148
	s_cselect_b32 s19, s13, s45
	s_cselect_b32 s18, s12, s44
	s_add_i32 s49, 0, 0x14000
	ds_read_b128 v[142:145], v146
	ds_read_b128 v[152:155], v146 offset:1024
	ds_read_b128 v[156:159], v146 offset:2048
	ds_read_b128 v[160:163], v146 offset:3072
	v_add_u32_e32 v146, s49, v148
	ds_read_b128 v[164:167], v146
	ds_read_b128 v[168:171], v146 offset:1024
	ds_read_b128 v[172:175], v146 offset:2048
	ds_read_b128 v[176:179], v146 offset:3072
	v_lshl_add_u64 v[146:147], s[14:15], 0, v[140:141]
	s_add_i32 m0, s27, 0xc000
	ds_read_b128 v[182:185], v150
	ds_read_b128 v[186:189], v150 offset:1024
	ds_read_b128 v[190:193], v150 offset:2048
	ds_read_b128 v[194:197], v150 offset:3072
	ds_read_b128 v[198:201], v150 offset:4096
	ds_read_b128 v[202:205], v150 offset:5120
	ds_read_b128 v[206:209], v150 offset:6144
	ds_read_b128 v[210:213], v150 offset:7168
	global_load_lds_dwordx4 v[146:147], off
	v_lshl_add_u64 v[146:147], s[14:15], 0, v[138:139]
	s_add_i32 m0, s27, 0xe000
	s_nop 0
	global_load_lds_dwordx4 v[146:147], off
	s_waitcnt vmcnt(8)
	s_waitcnt lgkmcnt(0)
	s_barrier
	s_setprio 2
	s_waitcnt lgkmcnt(0)
	v_mfma_f32_16x16x32_bf16 v[126:129], v[142:145], v[182:185], v[126:129]
	v_mfma_f32_16x16x32_bf16 v[122:125], v[156:159], v[182:185], v[122:125]
	v_mfma_f32_16x16x32_bf16 v[110:113], v[142:145], v[190:193], v[110:113]
	v_mfma_f32_16x16x32_bf16 v[106:109], v[156:159], v[190:193], v[106:109]
	v_mfma_f32_16x16x32_bf16 v[94:97], v[142:145], v[198:201], v[94:97]
	v_mfma_f32_16x16x32_bf16 v[90:93], v[156:159], v[198:201], v[90:93]
	v_mfma_f32_16x16x32_bf16 v[78:81], v[142:145], v[206:209], v[78:81]
	v_mfma_f32_16x16x32_bf16 v[74:77], v[156:159], v[206:209], v[74:77]
	v_mfma_f32_16x16x32_bf16 v[126:129], v[152:155], v[186:189], v[126:129]
	v_mfma_f32_16x16x32_bf16 v[122:125], v[160:163], v[186:189], v[122:125]
	v_mfma_f32_16x16x32_bf16 v[110:113], v[152:155], v[194:197], v[110:113]
	v_mfma_f32_16x16x32_bf16 v[106:109], v[160:163], v[194:197], v[106:109]
	v_mfma_f32_16x16x32_bf16 v[94:97], v[152:155], v[202:205], v[94:97]
	v_mfma_f32_16x16x32_bf16 v[90:93], v[160:163], v[202:205], v[90:93]
	v_mfma_f32_16x16x32_bf16 v[78:81], v[152:155], v[210:213], v[78:81]
	v_mfma_f32_16x16x32_bf16 v[74:77], v[160:163], v[210:213], v[74:77]
	s_setprio 1
	s_setprio 2
	v_mfma_f32_16x16x32_bf16 v[118:121], v[164:167], v[182:185], v[118:121]
	v_mfma_f32_16x16x32_bf16 v[114:117], v[172:175], v[182:185], v[114:117]
	v_mfma_f32_16x16x32_bf16 v[102:105], v[164:167], v[190:193], v[102:105]
	v_mfma_f32_16x16x32_bf16 v[98:101], v[172:175], v[190:193], v[98:101]
	v_mfma_f32_16x16x32_bf16 v[86:89], v[164:167], v[198:201], v[86:89]
	v_mfma_f32_16x16x32_bf16 v[82:85], v[172:175], v[198:201], v[82:85]
	v_mfma_f32_16x16x32_bf16 v[70:73], v[164:167], v[206:209], v[70:73]
	v_mfma_f32_16x16x32_bf16 v[66:69], v[172:175], v[206:209], v[66:69]
	v_mfma_f32_16x16x32_bf16 v[118:121], v[168:171], v[186:189], v[118:121]
	v_mfma_f32_16x16x32_bf16 v[114:117], v[176:179], v[186:189], v[114:117]
	v_mfma_f32_16x16x32_bf16 v[102:105], v[168:171], v[194:197], v[102:105]
	v_mfma_f32_16x16x32_bf16 v[98:101], v[176:179], v[194:197], v[98:101]
	v_mfma_f32_16x16x32_bf16 v[86:89], v[168:171], v[202:205], v[86:89]
	v_mfma_f32_16x16x32_bf16 v[82:85], v[176:179], v[202:205], v[82:85]
	v_mfma_f32_16x16x32_bf16 v[70:73], v[168:171], v[210:213], v[70:73]
	v_mfma_f32_16x16x32_bf16 v[66:69], v[176:179], v[210:213], v[66:69]
	s_setprio 1
	s_barrier
	s_add_i32 s14, s48, s26
	v_lshl_add_u64 v[146:147], s[18:19], 0, v[132:133]
	s_mov_b32 m0, s14
	ds_read_b128 v[182:185], v150 offset:16384
	ds_read_b128 v[186:189], v150 offset:17408
	ds_read_b128 v[190:193], v150 offset:18432
	ds_read_b128 v[194:197], v150 offset:19456
	ds_read_b128 v[198:201], v150 offset:20480
	ds_read_b128 v[202:205], v150 offset:21504
	ds_read_b128 v[206:209], v150 offset:22528
	ds_read_b128 v[210:213], v150 offset:23552
	global_load_lds_dwordx4 v[146:147], off
	s_add_i32 m0, s14, 0x2000
	s_add_u32 s14, s18, 0xb0000
	v_lshl_add_u64 v[214:215], s[18:19], 0, v[136:137]
	s_addc_u32 s15, s19, 0
	s_add_i32 s48, s49, s26
	global_load_lds_dwordx4 v[214:215], off
	v_lshl_add_u64 v[226:227], s[14:15], 0, v[132:133]
	s_mov_b32 m0, s48
	v_lshl_add_u64 v[228:229], s[20:21], 0, v[134:135]
	global_load_lds_dwordx4 v[226:227], off
	v_lshl_add_u64 v[226:227], s[14:15], 0, v[136:137]
	s_add_i32 m0, s48, 0x2000
	s_nop 0
	global_load_lds_dwordx4 v[226:227], off
	v_lshl_add_u64 v[226:227], s[20:21], 0, v[130:131]
	s_mov_b32 m0, s27
	s_nop 0
	global_load_lds_dwordx4 v[226:227], off
	s_mov_b32 m0, s28
	s_nop 0
	global_load_lds_dwordx4 v[228:229], off
	s_waitcnt vmcnt(8)
	s_waitcnt lgkmcnt(0)
	s_barrier
; #define PG8_STAGE(bufoff, gbase, voff) do { _Pragma("unroll") for (int _i = 0; _i < 2; ++_i) \
;         __builtin_amdgcn_global_load_lds((const unsigned*)((const char*)(gbase) + (voff)[_i]), (LAS unsigned*)(lds + (bufoff) + ldsw + _i * 8192), 16, 0, 0); } while (0)
; #define PG8_LDA(dst, b, h) do { _Pragma("unroll") for (int m = 0; m < 4; ++m) _Pragma("unroll") for (int k = 0; k < 2; ++k) dst[m][k] = *(const LAS bf16x8*)(lds + PG8_SA(b, h) + aoff + m * 2048 + k * 1024); } while (0)
; #define PG8_LDB(dst, b, h) do { _Pragma("unroll") for (int n = 0; n < 2; ++n) _Pragma("unroll") for (int k = 0; k < 2; ++k) dst[n][k] = *(const LAS bf16x8*)(lds + PG8_SB(b, h) + boff + n * 2048 + k * 1024); } while (0)
; #define PG8_MMA(ai, bj, At, Bt) do { __builtin_amdgcn_s_setprio(1); _Pragma("unroll") for (int m = 0; m < 4; ++m) _Pragma("unroll") for (int n = 0; n < 2; ++n) _Pragma("unroll") for (int k = 0; k < 2; ++k) \
;         acc[ai][bj][m][n] = __builtin_amdgcn_mfma_f32_16x16x32_bf16(Bt[n][k], At[m][k], acc[ai][bj][m][n], 0, 0, 0); __builtin_amdgcn_s_setprio(0); } while (0)
; #define PG8_WAIT_V(n) asm volatile("s_waitcnt vmcnt(" #n ")" ::: "memory")
; #define PG8_WAIT_L(n) asm volatile("s_waitcnt lgkmcnt(" #n ")" ::: "memory")
; #define PG8_BAR __builtin_amdgcn_s_barrier()
; #define PG8_SCHED __builtin_amdgcn_sched_barrier(0)
; #define PG8_STAGE(bufoff, gbase, voff) do { _Pragma("unroll") for (int _i = 0; _i < 2; ++_i) \
;         __builtin_amdgcn_global_load_lds((const unsigned*)((const char*)(gbase) + (voff)[_i]), (LAS unsigned*)(lds + (bufoff) + ldsw + _i * 8192), 16, 0, 0); } while (0)
; #define PG8_LDA(dst, b, h) do { _Pragma("unroll") for (int m = 0; m < 4; ++m) _Pragma("unroll") for (int k = 0; k < 2; ++k) dst[m][k] = *(const LAS bf16x8*)(lds + PG8_SA(b, h) + aoff + m * 2048 + k * 1024); } while (0)
; #define PG8_BAR __builtin_amdgcn_s_barrier()
; template <class Epi, class Sched>
; __device__ __forceinline__ void gemm_phase(LAS unsigned char* lds, const Gemm g, const Sched& S, const Epi& E) {
;     ...
;             PG8_WAIT_V(8); PG8_WAIT_L(0); PG8_BAR; PG8_MMA(1, 0, At, B0); PG8_MMA(1, 1, At, B1); PG8_BAR; PG8_SCHED;
;             PG8_LDB(B0, 1, 0); PG8_LDB(B1, 1, 1); PG8_SCHED; PG8_LDA(At, 1, 0); PG8_STAGE(PG8_SA(0, 1), a2 + hstepA, voffA);
;             PG8_WAIT_V(8); PG8_WAIT_L(0); PG8_BAR; PG8_MMA(0, 0, At, B0); PG8_MMA(0, 1, At, B1); PG8_BAR; PG8_SCHED;
	s_setprio 2
	s_waitcnt lgkmcnt(0)
	v_mfma_f32_16x16x32_bf16 v[62:65], v[142:145], v[182:185], v[62:65]
	v_mfma_f32_16x16x32_bf16 v[58:61], v[156:159], v[182:185], v[58:61]
	v_mfma_f32_16x16x32_bf16 v[46:49], v[142:145], v[190:193], v[46:49]
	v_mfma_f32_16x16x32_bf16 v[42:45], v[156:159], v[190:193], v[42:45]
	v_mfma_f32_16x16x32_bf16 v[30:33], v[142:145], v[198:201], v[30:33]
	v_mfma_f32_16x16x32_bf16 v[26:29], v[156:159], v[198:201], v[26:29]
	v_mfma_f32_16x16x32_bf16 v[14:17], v[142:145], v[206:209], v[14:17]
	v_mfma_f32_16x16x32_bf16 v[10:13], v[156:159], v[206:209], v[10:13]
	v_mfma_f32_16x16x32_bf16 v[62:65], v[152:155], v[186:189], v[62:65]
	v_mfma_f32_16x16x32_bf16 v[58:61], v[160:163], v[186:189], v[58:61]
	v_mfma_f32_16x16x32_bf16 v[46:49], v[152:155], v[194:197], v[46:49]
	v_mfma_f32_16x16x32_bf16 v[42:45], v[160:163], v[194:197], v[42:45]
	v_mfma_f32_16x16x32_bf16 v[30:33], v[152:155], v[202:205], v[30:33]
	v_mfma_f32_16x16x32_bf16 v[26:29], v[160:163], v[202:205], v[26:29]
	v_mfma_f32_16x16x32_bf16 v[14:17], v[152:155], v[210:213], v[14:17]
	v_mfma_f32_16x16x32_bf16 v[10:13], v[160:163], v[210:213], v[10:13]
	s_setprio 1
	s_setprio 2
	v_mfma_f32_16x16x32_bf16 v[54:57], v[164:167], v[182:185], v[54:57]
	v_mfma_f32_16x16x32_bf16 v[50:53], v[172:175], v[182:185], v[50:53]
	v_mfma_f32_16x16x32_bf16 v[38:41], v[164:167], v[190:193], v[38:41]
	v_mfma_f32_16x16x32_bf16 v[34:37], v[172:175], v[190:193], v[34:37]
	v_mfma_f32_16x16x32_bf16 v[22:25], v[164:167], v[198:201], v[22:25]
	v_mfma_f32_16x16x32_bf16 v[18:21], v[172:175], v[198:201], v[18:21]
	v_mfma_f32_16x16x32_bf16 v[6:9], v[164:167], v[206:209], v[6:9]
	v_mfma_f32_16x16x32_bf16 v[2:5], v[172:175], v[206:209], v[2:5]
	v_mfma_f32_16x16x32_bf16 v[54:57], v[168:171], v[186:189], v[54:57]
	v_mfma_f32_16x16x32_bf16 v[50:53], v[176:179], v[186:189], v[50:53]
	v_mfma_f32_16x16x32_bf16 v[38:41], v[168:171], v[194:197], v[38:41]
	v_mfma_f32_16x16x32_bf16 v[34:37], v[176:179], v[194:197], v[34:37]
	v_mfma_f32_16x16x32_bf16 v[22:25], v[168:171], v[202:205], v[22:25]
	v_mfma_f32_16x16x32_bf16 v[18:21], v[176:179], v[202:205], v[18:21]
	v_mfma_f32_16x16x32_bf16 v[6:9], v[168:171], v[210:213], v[6:9]
	v_mfma_f32_16x16x32_bf16 v[2:5], v[176:179], v[210:213], v[2:5]
	s_setprio 1
	s_barrier
	s_add_i32 s48, 0, 0x18000
	v_add_u32_e32 v151, s48, v148
	s_add_i32 s49, 0, 0x1c000
	ds_read_b128 v[142:145], v151
	ds_read_b128 v[152:155], v151 offset:1024
	ds_read_b128 v[156:159], v151 offset:2048
	ds_read_b128 v[160:163], v151 offset:3072
	v_add_u32_e32 v151, s49, v148
	ds_read_b128 v[164:167], v151
	ds_read_b128 v[168:171], v151 offset:1024
	ds_read_b128 v[172:175], v151 offset:2048
	ds_read_b128 v[176:179], v151 offset:3072
	s_add_u32 s14, s20, 0xb0000
	s_addc_u32 s15, s21, 0
	s_mov_b32 m0, s29
	v_lshl_add_u64 v[232:233], s[14:15], 0, v[130:131]
	ds_read_b128 v[182:185], v150 offset:32768
	ds_read_b128 v[186:189], v150 offset:33792
	ds_read_b128 v[190:193], v150 offset:34816
	ds_read_b128 v[194:197], v150 offset:35840
	ds_read_b128 v[198:201], v150 offset:36864
	ds_read_b128 v[202:205], v150 offset:37888
	ds_read_b128 v[206:209], v150 offset:38912
	ds_read_b128 v[210:213], v150 offset:39936
	global_load_lds_dwordx4 v[232:233], off
	v_lshl_add_u64 v[232:233], s[14:15], 0, v[134:135]
	s_mov_b32 m0, s30
	s_nop 0
	global_load_lds_dwordx4 v[232:233], off
	s_waitcnt vmcnt(8)
	s_waitcnt lgkmcnt(0)
	s_barrier
	s_setprio 2
	s_waitcnt lgkmcnt(0)
	v_mfma_f32_16x16x32_bf16 v[126:129], v[142:145], v[182:185], v[126:129]
	v_mfma_f32_16x16x32_bf16 v[122:125], v[156:159], v[182:185], v[122:125]
	v_mfma_f32_16x16x32_bf16 v[110:113], v[142:145], v[190:193], v[110:113]
	v_mfma_f32_16x16x32_bf16 v[106:109], v[156:159], v[190:193], v[106:109]
	v_mfma_f32_16x16x32_bf16 v[94:97], v[142:145], v[198:201], v[94:97]
	v_mfma_f32_16x16x32_bf16 v[90:93], v[156:159], v[198:201], v[90:93]
	v_mfma_f32_16x16x32_bf16 v[78:81], v[142:145], v[206:209], v[78:81]
	v_mfma_f32_16x16x32_bf16 v[74:77], v[156:159], v[206:209], v[74:77]
	v_mfma_f32_16x16x32_bf16 v[126:129], v[152:155], v[186:189], v[126:129]
	v_mfma_f32_16x16x32_bf16 v[122:125], v[160:163], v[186:189], v[122:125]
	v_mfma_f32_16x16x32_bf16 v[110:113], v[152:155], v[194:197], v[110:113]
	v_mfma_f32_16x16x32_bf16 v[106:109], v[160:163], v[194:197], v[106:109]
	v_mfma_f32_16x16x32_bf16 v[94:97], v[152:155], v[202:205], v[94:97]
	v_mfma_f32_16x16x32_bf16 v[90:93], v[160:163], v[202:205], v[90:93]
	v_mfma_f32_16x16x32_bf16 v[78:81], v[152:155], v[210:213], v[78:81]
	v_mfma_f32_16x16x32_bf16 v[74:77], v[160:163], v[210:213], v[74:77]
	s_setprio 1
	s_setprio 2
	v_mfma_f32_16x16x32_bf16 v[118:121], v[164:167], v[182:185], v[118:121]
	v_mfma_f32_16x16x32_bf16 v[114:117], v[172:175], v[182:185], v[114:117]
	v_mfma_f32_16x16x32_bf16 v[102:105], v[164:167], v[190:193], v[102:105]
	v_mfma_f32_16x16x32_bf16 v[98:101], v[172:175], v[190:193], v[98:101]
	v_mfma_f32_16x16x32_bf16 v[86:89], v[164:167], v[198:201], v[86:89]
	v_mfma_f32_16x16x32_bf16 v[82:85], v[172:175], v[198:201], v[82:85]
	v_mfma_f32_16x16x32_bf16 v[70:73], v[164:167], v[206:209], v[70:73]
	v_mfma_f32_16x16x32_bf16 v[66:69], v[172:175], v[206:209], v[66:69]
	v_mfma_f32_16x16x32_bf16 v[118:121], v[168:171], v[186:189], v[118:121]
	v_mfma_f32_16x16x32_bf16 v[114:117], v[176:179], v[186:189], v[114:117]
	v_mfma_f32_16x16x32_bf16 v[102:105], v[168:171], v[194:197], v[102:105]
	v_mfma_f32_16x16x32_bf16 v[98:101], v[176:179], v[194:197], v[98:101]
	v_mfma_f32_16x16x32_bf16 v[86:89], v[168:171], v[202:205], v[86:89]
	v_mfma_f32_16x16x32_bf16 v[82:85], v[176:179], v[202:205], v[82:85]
	v_mfma_f32_16x16x32_bf16 v[70:73], v[168:171], v[210:213], v[70:73]
	v_mfma_f32_16x16x32_bf16 v[66:69], v[176:179], v[210:213], v[66:69]
	s_setprio 1
	s_barrier
; #define PG8_STAGE(bufoff, gbase, voff) do { _Pragma("unroll") for (int _i = 0; _i < 2; ++_i) \
;         __builtin_amdgcn_global_load_lds((const unsigned*)((const char*)(gbase) + (voff)[_i]), (LAS unsigned*)(lds + (bufoff) + ldsw + _i * 8192), 16, 0, 0); } while (0)
; #define PG8_LDA(dst, b, h) do { _Pragma("unroll") for (int m = 0; m < 4; ++m) _Pragma("unroll") for (int k = 0; k < 2; ++k) dst[m][k] = *(const LAS bf16x8*)(lds + PG8_SA(b, h) + aoff + m * 2048 + k * 1024); } while (0)
; #define PG8_MMA(ai, bj, At, Bt) do { __builtin_amdgcn_s_setprio(1); _Pragma("unroll") for (int m = 0; m < 4; ++m) _Pragma("unroll") for (int n = 0; n < 2; ++n) _Pragma("unroll") for (int k = 0; k < 2; ++k) \
;         acc[ai][bj][m][n] = __builtin_amdgcn_mfma_f32_16x16x32_bf16(Bt[n][k], At[m][k], acc[ai][bj][m][n], 0, 0, 0); __builtin_amdgcn_s_setprio(0); } while (0)
; #define PG8_WAIT_V(n) asm volatile("s_waitcnt vmcnt(" #n ")" ::: "memory")
; #define PG8_WAIT_L(n) asm volatile("s_waitcnt lgkmcnt(" #n ")" ::: "memory")
; #define PG8_BAR __builtin_amdgcn_s_barrier()
; #define PG8_SCHED __builtin_amdgcn_sched_barrier(0)
; #define PG8_STAGE(bufoff, gbase, voff) do { _Pragma("unroll") for (int _i = 0; _i < 2; ++_i) \
;         __builtin_amdgcn_global_load_lds((const unsigned*)((const char*)(gbase) + (voff)[_i]), (LAS unsigned*)(lds + (bufoff) + ldsw + _i * 8192), 16, 0, 0); } while (0)
; #define PG8_LDA(dst, b, h) do { _Pragma("unroll") for (int m = 0; m < 4; ++m) _Pragma("unroll") for (int k = 0; k < 2; ++k) dst[m][k] = *(const LAS bf16x8*)(lds + PG8_SA(b, h) + aoff + m * 2048 + k * 1024); } while (0)
; #define PG8_WAIT_V(n) asm volatile("s_waitcnt vmcnt(" #n ")" ::: "memory")
; #define PG8_WAIT_L(n) asm volatile("s_waitcnt lgkmcnt(" #n ")" ::: "memory")
; #define PG8_BAR __builtin_amdgcn_s_barrier()
; #define PG8_SCHED __builtin_amdgcn_sched_barrier(0)
; template <class Epi, class Sched>
; __device__ __forceinline__ void gemm_phase(LAS unsigned char* lds, const Gemm g, const Sched& S, const Epi& E) {
;     ...
;             PG8_LDA(At, 1, 1); PG8_STAGE(PG8_SB(1, 0), b3, voffB); PG8_STAGE(PG8_SB(1, 1), b3 + hstepB, voffB); PG8_STAGE(PG8_SA(1, 0), a3, voffA);
;             PG8_WAIT_V(8); PG8_WAIT_L(0); PG8_BAR; PG8_MMA(1, 0, At, B0); PG8_MMA(1, 1, At, B1); PG8_BAR; PG8_SCHED;
;         }
	s_add_i32 s14, s48, s26
	v_lshl_add_u64 v[146:147], v[146:147], 0, s[86:87]
	s_mov_b32 m0, s14
	ds_read_b128 v[182:185], v150 offset:49152
	ds_read_b128 v[186:189], v150 offset:50176
	ds_read_b128 v[190:193], v150 offset:51200
	ds_read_b128 v[194:197], v150 offset:52224
	ds_read_b128 v[198:201], v150 offset:53248
	ds_read_b128 v[202:205], v150 offset:54272
	ds_read_b128 v[206:209], v150 offset:55296
	ds_read_b128 v[210:213], v150 offset:56320
	global_load_lds_dwordx4 v[146:147], off
	s_add_i32 m0, s14, 0x2000
	s_add_u32 s14, s18, 0xb0080
	v_lshl_add_u64 v[146:147], v[214:215], 0, s[86:87]
	s_addc_u32 s15, s19, 0
	s_add_i32 s18, s49, s26
	global_load_lds_dwordx4 v[146:147], off
	v_lshl_add_u64 v[146:147], s[14:15], 0, v[132:133]
	s_mov_b32 m0, s18
	s_nop 0
	global_load_lds_dwordx4 v[146:147], off
	v_lshl_add_u64 v[146:147], s[14:15], 0, v[136:137]
	s_add_i32 m0, s18, 0x2000
	s_nop 0
	global_load_lds_dwordx4 v[146:147], off
	v_lshl_add_u64 v[146:147], v[226:227], 0, s[86:87]
	s_mov_b32 m0, s31
	s_nop 0
	global_load_lds_dwordx4 v[146:147], off
	v_lshl_add_u64 v[146:147], v[228:229], 0, s[86:87]
	s_mov_b32 m0, s38
	s_nop 0
	global_load_lds_dwordx4 v[146:147], off
	s_waitcnt vmcnt(8)
	s_waitcnt lgkmcnt(0)
	s_barrier
	s_setprio 2
	s_waitcnt lgkmcnt(0)
	v_mfma_f32_16x16x32_bf16 v[62:65], v[142:145], v[182:185], v[62:65]
	v_mfma_f32_16x16x32_bf16 v[58:61], v[156:159], v[182:185], v[58:61]
	v_mfma_f32_16x16x32_bf16 v[46:49], v[142:145], v[190:193], v[46:49]
	v_mfma_f32_16x16x32_bf16 v[42:45], v[156:159], v[190:193], v[42:45]
	v_mfma_f32_16x16x32_bf16 v[30:33], v[142:145], v[198:201], v[30:33]
	v_mfma_f32_16x16x32_bf16 v[26:29], v[156:159], v[198:201], v[26:29]
	v_mfma_f32_16x16x32_bf16 v[14:17], v[142:145], v[206:209], v[14:17]
	v_mfma_f32_16x16x32_bf16 v[10:13], v[156:159], v[206:209], v[10:13]
	v_mfma_f32_16x16x32_bf16 v[62:65], v[152:155], v[186:189], v[62:65]
	v_mfma_f32_16x16x32_bf16 v[58:61], v[160:163], v[186:189], v[58:61]
	v_mfma_f32_16x16x32_bf16 v[46:49], v[152:155], v[194:197], v[46:49]
	v_mfma_f32_16x16x32_bf16 v[42:45], v[160:163], v[194:197], v[42:45]
	v_mfma_f32_16x16x32_bf16 v[30:33], v[152:155], v[202:205], v[30:33]
	v_mfma_f32_16x16x32_bf16 v[26:29], v[160:163], v[202:205], v[26:29]
	v_mfma_f32_16x16x32_bf16 v[14:17], v[152:155], v[210:213], v[14:17]
	v_mfma_f32_16x16x32_bf16 v[10:13], v[160:163], v[210:213], v[10:13]
	s_setprio 1
	s_setprio 2
	v_mfma_f32_16x16x32_bf16 v[54:57], v[164:167], v[182:185], v[54:57]
	v_mfma_f32_16x16x32_bf16 v[50:53], v[172:175], v[182:185], v[50:53]
	v_mfma_f32_16x16x32_bf16 v[38:41], v[164:167], v[190:193], v[38:41]
	v_mfma_f32_16x16x32_bf16 v[34:37], v[172:175], v[190:193], v[34:37]
	v_mfma_f32_16x16x32_bf16 v[22:25], v[164:167], v[198:201], v[22:25]
	v_mfma_f32_16x16x32_bf16 v[18:21], v[172:175], v[198:201], v[18:21]
	v_mfma_f32_16x16x32_bf16 v[6:9], v[164:167], v[206:209], v[6:9]
	v_mfma_f32_16x16x32_bf16 v[2:5], v[172:175], v[206:209], v[2:5]
	v_mfma_f32_16x16x32_bf16 v[54:57], v[168:171], v[186:189], v[54:57]
	v_mfma_f32_16x16x32_bf16 v[50:53], v[176:179], v[186:189], v[50:53]
	v_mfma_f32_16x16x32_bf16 v[38:41], v[168:171], v[194:197], v[38:41]
	v_mfma_f32_16x16x32_bf16 v[34:37], v[176:179], v[194:197], v[34:37]
	v_mfma_f32_16x16x32_bf16 v[22:25], v[168:171], v[202:205], v[22:25]
	v_mfma_f32_16x16x32_bf16 v[18:21], v[176:179], v[202:205], v[18:21]
	v_mfma_f32_16x16x32_bf16 v[6:9], v[168:171], v[210:213], v[6:9]
	v_mfma_f32_16x16x32_bf16 v[2:5], v[176:179], v[210:213], v[2:5]
	s_setprio 1
	s_barrier
	s_add_i32 s46, s46, 2
	s_add_u32 s44, s44, 0x100
	s_addc_u32 s45, s45, 0
	s_cmp_gt_u32 s46, 41
	s_mov_b64 s[14:15], s[16:17]
	s_cbranch_scc0 .Lkb_down
	s_setprio 0
